# v3 variant: weight reads sc1 nt instead of nt
# speedup vs baseline: 1.0037x; 1.0037x over previous
.LBB0_5:
	s_or_b64 exec, exec, s[0:1]
	s_ashr_i32 s1, s33, 6
	s_lshl_b32 s0, s18, 3
	s_add_i32 s0, s0, s1
	v_writelane_b32 v249, s1, 0
	s_lshl_b32 s1, s1, 14
	s_add_i32 s20, s1, 0
	v_and_b32_e32 v108, 63, v1
	s_cmpk_gt_i32 s0, 0x5ff
	s_waitcnt lgkmcnt(0)
	s_barrier
	s_cbranch_scc1 .LBB0_12
	s_load_dwordx4 s[4:7], s[16:17], 0x8
	s_mul_hi_i32 s1, s0, 0x2aaaaaab
	s_lshr_b32 s2, s1, 31
	s_ashr_i32 s1, s1, 4
	s_add_i32 s1, s1, s2
	s_lshl_b32 s2, s1, 6
	s_waitcnt lgkmcnt(0)
	s_cmp_eq_u64 s[4:5], 0
	s_cbranch_scc1 .LBB0_8
	v_or_b32_e32 v2, s2, v108
	v_ashrrev_i32_e32 v3, 31, v2
	v_lshl_add_u64 v[2:3], v[2:3], 2, s[4:5]
	global_load_dword v4, v[2:3], off sc1 nt
	s_branch .LBB0_9

.LBB0_9:
	s_mulk_i32 s1, 0x60
	s_sub_i32 s3, s0, s1
	s_lshl_b32 s0, s3, 5
	s_ashr_i32 s1, s0, 31
	s_lshl_b64 s[4:5], s[0:1], 2
	s_add_u32 s4, s6, s4
	v_lshlrev_b32_e32 v2, 2, v1
	v_lshrrev_b32_e32 v5, 5, v108
	s_addc_u32 s5, s7, s5
	v_and_b32_e32 v2, 0x7c, v2
	v_mov_b32_e32 v3, 0
	v_or_b32_e32 v24, s2, v5
	v_lshl_add_u64 v[6:7], s[4:5], 0, v[2:3]
	s_movk_i32 s1, 0x3000
	v_mad_i64_i32 v[8:9], s[4:5], v24, s1, v[6:7]
	v_or_b32_e32 v10, 2, v24
	v_or_b32_e32 v12, 4, v24
	v_or_b32_e32 v14, 6, v24
	v_or_b32_e32 v16, 8, v24
	v_or_b32_e32 v18, 10, v24
	v_or_b32_e32 v20, 12, v24
	v_or_b32_e32 v22, 14, v24
	v_mad_i64_i32 v[10:11], s[4:5], v10, s1, v[6:7]
	v_mad_i64_i32 v[12:13], s[4:5], v12, s1, v[6:7]
	v_mad_i64_i32 v[14:15], s[4:5], v14, s1, v[6:7]
	v_mad_i64_i32 v[16:17], s[4:5], v16, s1, v[6:7]
	v_mad_i64_i32 v[18:19], s[4:5], v18, s1, v[6:7]
	v_mad_i64_i32 v[20:21], s[4:5], v20, s1, v[6:7]
	v_mad_i64_i32 v[22:23], s[4:5], v22, s1, v[6:7]
	global_load_dword v25, v[8:9], off sc1 nt
	global_load_dword v26, v[10:11], off sc1 nt
	global_load_dword v27, v[12:13], off sc1 nt
	global_load_dword v28, v[14:15], off sc1 nt
	global_load_dword v29, v[16:17], off sc1 nt
	global_load_dword v30, v[18:19], off sc1 nt
	global_load_dword v31, v[20:21], off sc1 nt
	global_load_dword v32, v[22:23], off sc1 nt
	v_or_b32_e32 v8, 16, v24
	v_mad_i64_i32 v[8:9], s[4:5], v8, s1, v[6:7]
	v_or_b32_e32 v10, 18, v24
	v_or_b32_e32 v12, 20, v24
	v_or_b32_e32 v14, 22, v24
	v_or_b32_e32 v16, 24, v24
	v_or_b32_e32 v18, 26, v24
	v_or_b32_e32 v20, 28, v24
	v_or_b32_e32 v22, 30, v24
	v_mad_i64_i32 v[10:11], s[4:5], v10, s1, v[6:7]
	v_mad_i64_i32 v[12:13], s[4:5], v12, s1, v[6:7]
	v_mad_i64_i32 v[14:15], s[4:5], v14, s1, v[6:7]
	v_mad_i64_i32 v[16:17], s[4:5], v16, s1, v[6:7]
	v_mad_i64_i32 v[18:19], s[4:5], v18, s1, v[6:7]
	v_mad_i64_i32 v[20:21], s[4:5], v20, s1, v[6:7]
	v_mad_i64_i32 v[22:23], s[4:5], v22, s1, v[6:7]
	global_load_dword v33, v[8:9], off sc1 nt
	global_load_dword v34, v[10:11], off sc1 nt
	global_load_dword v35, v[12:13], off sc1 nt
	global_load_dword v36, v[14:15], off sc1 nt
	global_load_dword v37, v[16:17], off sc1 nt
	global_load_dword v38, v[18:19], off sc1 nt
	global_load_dword v39, v[20:21], off sc1 nt
	global_load_dword v40, v[22:23], off sc1 nt
	v_or_b32_e32 v8, 32, v24
	v_mad_i64_i32 v[8:9], s[4:5], v8, s1, v[6:7]
	v_or_b32_e32 v10, 34, v24
	v_or_b32_e32 v12, 36, v24
	v_or_b32_e32 v14, 38, v24
	v_or_b32_e32 v16, 40, v24
	v_or_b32_e32 v18, 42, v24
	v_or_b32_e32 v20, 44, v24
	v_or_b32_e32 v22, 46, v24
	v_mad_i64_i32 v[10:11], s[4:5], v10, s1, v[6:7]
	v_mad_i64_i32 v[12:13], s[4:5], v12, s1, v[6:7]
	v_mad_i64_i32 v[14:15], s[4:5], v14, s1, v[6:7]
	v_mad_i64_i32 v[16:17], s[4:5], v16, s1, v[6:7]
	v_mad_i64_i32 v[18:19], s[4:5], v18, s1, v[6:7]
	v_mad_i64_i32 v[20:21], s[4:5], v20, s1, v[6:7]
	v_mad_i64_i32 v[22:23], s[4:5], v22, s1, v[6:7]
	global_load_dword v41, v[8:9], off sc1 nt
	global_load_dword v42, v[10:11], off sc1 nt
	global_load_dword v43, v[12:13], off sc1 nt
	global_load_dword v44, v[14:15], off sc1 nt
	global_load_dword v45, v[16:17], off sc1 nt
	global_load_dword v46, v[18:19], off sc1 nt
	global_load_dword v47, v[20:21], off sc1 nt
	global_load_dword v48, v[22:23], off sc1 nt
	v_or_b32_e32 v8, 48, v24
	v_mad_i64_i32 v[8:9], s[4:5], v8, s1, v[6:7]
	v_or_b32_e32 v10, 50, v24
	v_mad_i64_i32 v[10:11], s[4:5], v10, s1, v[6:7]
	global_load_dword v18, v[8:9], off sc1 nt
	global_load_dword v19, v[10:11], off sc1 nt
	v_or_b32_e32 v8, 52, v24
	v_mad_i64_i32 v[8:9], s[4:5], v8, s1, v[6:7]
	v_or_b32_e32 v10, 54, v24
	v_or_b32_e32 v12, 56, v24
	v_or_b32_e32 v14, 58, v24
	v_or_b32_e32 v16, 60, v24
	v_or_b32_e32 v20, 62, v24
	v_mad_i64_i32 v[10:11], s[4:5], v10, s1, v[6:7]
	v_mad_i64_i32 v[12:13], s[4:5], v12, s1, v[6:7]
	v_mad_i64_i32 v[14:15], s[4:5], v14, s1, v[6:7]
	v_mad_i64_i32 v[16:17], s[4:5], v16, s1, v[6:7]
	v_mad_i64_i32 v[6:7], s[4:5], v20, s1, v[6:7]
	global_load_dword v23, v[8:9], off sc1 nt
	global_load_dword v24, v[10:11], off sc1 nt
	global_load_dword v49, v[12:13], off sc1 nt
	global_load_dword v50, v[14:15], off sc1 nt
	global_load_dword v51, v[16:17], off sc1 nt
	global_load_dword v52, v[6:7], off sc1 nt
	v_mbcnt_lo_u32_b32 v20, -1, 0
	v_mbcnt_hi_u32_b32 v20, -1, v20
	v_and_or_b32 v20, v20, 64, v5
	v_lshlrev_b32_e32 v20, 2, v20
	s_waitcnt vmcnt(32)
	ds_bpermute_b32 v21, v20, v4
	ds_bpermute_b32 v22, v20, v4 offset:8
	ds_bpermute_b32 v7, v20, v4 offset:16
	ds_bpermute_b32 v8, v20, v4 offset:24
	v_mul_u32_u24_e32 v5, 0x84, v5
	s_waitcnt vmcnt(31) lgkmcnt(3)
	v_mul_f32_e32 v6, v25, v21
	v_add3_u32 v2, s20, v2, v5
	s_waitcnt vmcnt(30) lgkmcnt(2)
	v_mul_f32_e32 v5, v26, v22
	ds_write2_b32 v2, v6, v5 offset1:66
	ds_bpermute_b32 v5, v20, v4 offset:32
	ds_bpermute_b32 v6, v20, v4 offset:40
	s_waitcnt vmcnt(29) lgkmcnt(4)
	v_mul_f32_e32 v7, v27, v7
	s_waitcnt vmcnt(28) lgkmcnt(3)
	v_mul_f32_e32 v8, v28, v8
	ds_write2_b32 v2, v7, v8 offset0:132 offset1:198
	ds_bpermute_b32 v8, v20, v4 offset:48
	ds_bpermute_b32 v9, v20, v4 offset:56
	s_waitcnt vmcnt(27) lgkmcnt(4)
	v_mul_f32_e32 v5, v29, v5
	s_waitcnt vmcnt(26) lgkmcnt(3)
	v_mul_f32_e32 v6, v30, v6
	v_add_u32_e32 v7, 0x400, v2
	ds_write2_b32 v7, v5, v6 offset0:8 offset1:74
	ds_bpermute_b32 v5, v20, v4 offset:64
	ds_bpermute_b32 v6, v20, v4 offset:72
	s_waitcnt vmcnt(25) lgkmcnt(4)
	v_mul_f32_e32 v8, v31, v8
	s_waitcnt vmcnt(24) lgkmcnt(3)
	v_mul_f32_e32 v9, v32, v9
	ds_write2_b32 v7, v8, v9 offset0:140 offset1:206
	ds_bpermute_b32 v8, v20, v4 offset:80
	ds_bpermute_b32 v9, v20, v4 offset:88
	s_waitcnt vmcnt(23) lgkmcnt(4)
	v_mul_f32_e32 v5, v33, v5
	s_waitcnt vmcnt(22) lgkmcnt(3)
	v_mul_f32_e32 v6, v34, v6
	v_add_u32_e32 v7, 0x800, v2
	ds_write2_b32 v7, v5, v6 offset0:16 offset1:82
	ds_bpermute_b32 v5, v20, v4 offset:96
	ds_bpermute_b32 v6, v20, v4 offset:104
	s_waitcnt vmcnt(21) lgkmcnt(4)
	v_mul_f32_e32 v8, v35, v8
	s_waitcnt vmcnt(20) lgkmcnt(3)
	v_mul_f32_e32 v9, v36, v9
	ds_write2_b32 v7, v8, v9 offset0:148 offset1:214
	ds_bpermute_b32 v8, v20, v4 offset:112
	ds_bpermute_b32 v9, v20, v4 offset:120
	s_waitcnt vmcnt(19) lgkmcnt(4)
	v_mul_f32_e32 v5, v37, v5
	s_waitcnt vmcnt(18) lgkmcnt(3)
	v_mul_f32_e32 v6, v38, v6
	v_add_u32_e32 v7, 0xc00, v2
	ds_write2_b32 v7, v5, v6 offset0:24 offset1:90
	ds_bpermute_b32 v5, v20, v4 offset:128
	ds_bpermute_b32 v6, v20, v4 offset:136
	s_waitcnt vmcnt(17) lgkmcnt(4)
	v_mul_f32_e32 v8, v39, v8
	s_waitcnt vmcnt(16) lgkmcnt(3)
	v_mul_f32_e32 v9, v40, v9
	ds_write2_b32 v7, v8, v9 offset0:156 offset1:222
	ds_bpermute_b32 v8, v20, v4 offset:144
	ds_bpermute_b32 v9, v20, v4 offset:152
	s_waitcnt vmcnt(15) lgkmcnt(4)
	v_mul_f32_e32 v5, v41, v5
	s_waitcnt vmcnt(14) lgkmcnt(3)
	v_mul_f32_e32 v6, v42, v6
	v_add_u32_e32 v7, 0x1000, v2
	ds_write2_b32 v7, v5, v6 offset0:32 offset1:98
	ds_bpermute_b32 v5, v20, v4 offset:160
	ds_bpermute_b32 v6, v20, v4 offset:168
	s_waitcnt vmcnt(13) lgkmcnt(4)
	v_mul_f32_e32 v8, v43, v8
	s_waitcnt vmcnt(12) lgkmcnt(3)
	v_mul_f32_e32 v9, v44, v9
	ds_write2_b32 v7, v8, v9 offset0:164 offset1:230
	ds_bpermute_b32 v8, v20, v4 offset:176
	ds_bpermute_b32 v9, v20, v4 offset:184
	s_waitcnt vmcnt(11) lgkmcnt(4)
	v_mul_f32_e32 v5, v45, v5
	s_waitcnt vmcnt(10) lgkmcnt(3)
	v_mul_f32_e32 v6, v46, v6
	v_add_u32_e32 v7, 0x1400, v2
	ds_write2_b32 v7, v5, v6 offset0:40 offset1:106
	ds_bpermute_b32 v5, v20, v4 offset:192
	ds_bpermute_b32 v6, v20, v4 offset:200
	s_waitcnt vmcnt(9) lgkmcnt(4)
	v_mul_f32_e32 v8, v47, v8
	s_waitcnt vmcnt(8) lgkmcnt(3)
	v_mul_f32_e32 v9, v48, v9
	ds_write2_b32 v7, v8, v9 offset0:172 offset1:238
	ds_bpermute_b32 v7, v20, v4 offset:208
	ds_bpermute_b32 v8, v20, v4 offset:216
	s_waitcnt vmcnt(7) lgkmcnt(4)
	v_mul_f32_e32 v5, v18, v5
	s_waitcnt vmcnt(6) lgkmcnt(3)
	v_mul_f32_e32 v6, v19, v6
	v_add_u32_e32 v9, 0x1800, v2
	ds_write2_b32 v9, v5, v6 offset0:48 offset1:114
	ds_bpermute_b32 v5, v20, v4 offset:224
	s_waitcnt vmcnt(5) lgkmcnt(3)
	v_mul_f32_e32 v6, v23, v7
	s_waitcnt vmcnt(4) lgkmcnt(2)
	v_mul_f32_e32 v7, v24, v8
	ds_bpermute_b32 v8, v20, v4 offset:232
	ds_write2_b32 v9, v6, v7 offset0:180 offset1:246
	ds_bpermute_b32 v6, v20, v4 offset:240
	ds_bpermute_b32 v4, v20, v4 offset:248
	s_waitcnt vmcnt(3) lgkmcnt(4)
	v_mul_f32_e32 v5, v49, v5
	s_waitcnt vmcnt(2) lgkmcnt(3)
	v_mul_f32_e32 v7, v50, v8
	v_add_u32_e32 v2, 0x1c00, v2
	ds_write2_b32 v2, v5, v7 offset0:56 offset1:122
	s_waitcnt vmcnt(1) lgkmcnt(2)
	v_mul_f32_e32 v5, v51, v6
	s_waitcnt vmcnt(0) lgkmcnt(1)
	v_mul_f32_e32 v4, v52, v4
	ds_write2_b32 v2, v5, v4 offset0:188 offset1:254
	s_waitcnt lgkmcnt(0)
	s_cmp_lt_i32 s3, 32
	s_cbranch_scc1 .LBB0_11
	s_cmpk_gt_u32 s0, 0x7ff
	s_cselect_b32 s1, 0xfffffc00, 0
	s_cselect_b32 s3, 0x80, 0
	s_add_i32 s1, s0, s1
	s_lshl_b32 s1, s1, 1
	s_addk_i32 s1, 0xf800
	s_and_b32 s1, s1, 0x7fffff00
	s_or_b32 s1, s1, s3
	s_and_b32 s0, s0, 0x60
	s_or_b32 s0, s1, s0
	s_addk_i32 s0, 0x400

.LBB0_41:
	s_or_b64 exec, exec, s[0:1]
	s_and_b32 s0, s18, 7
	s_ashr_i32 s1, s18, 3
	v_writelane_b32 v249, s1, 3
	s_cmp_lt_u32 s0, 4
	v_writelane_b32 v249, s0, 4
	s_cbranch_scc1 .LBB0_64
	s_load_dwordx4 s[12:15], s[16:17], 0x30
	v_writelane_b32 v249, s20, 5
	v_mov_b32_e32 v8, 1.0
	v_readlane_b32 s0, v249, 0
	s_lshl_b32 s20, s0, 7
	v_or_b32_e32 v2, s20, v108
	s_waitcnt lgkmcnt(0)
	s_cmp_lg_u64 s[12:13], 0
	s_cselect_b64 s[0:1], -1, 0
	s_cmp_eq_u64 s[12:13], 0
	v_ashrrev_i32_e32 v3, 31, v2
	v_mov_b32_e32 v9, 1.0
	s_cbranch_scc1 .LBB0_44
	v_lshl_add_u64 v[4:5], v[2:3], 2, s[12:13]
	global_load_dword v9, v[4:5], off sc1 nt
.LBB0_44:
	v_writelane_b32 v249, s68, 6
	v_lshrrev_b32_e32 v11, 5, v108
	v_mul_u32_u24_e32 v4, 0x1600, v11
	v_writelane_b32 v249, s69, 7
	v_and_b32_e32 v1, 31, v1
	v_readlane_b32 s2, v249, 3
	s_lshl_b32 s2, s2, 2
	v_readlane_b32 s3, v249, 4
	s_add_i32 s2, s3, s2
	s_add_i32 s70, s2, -4
	s_lshl_b32 s22, s70, 5
	s_ashr_i32 s23, s22, 31
	s_lshl_b64 s[2:3], s[22:23], 2
	v_or_b32_e32 v4, v4, v1
	s_add_u32 s2, s14, s2
	s_addc_u32 s3, s15, s3
	v_mov_b32_e32 v5, 0
	v_lshlrev_b32_e32 v4, 2, v4
	v_lshl_add_u64 v[6:7], s[2:3], 0, v[4:5]
	s_or_b32 s2, s20, 2
	s_mul_hi_i32 s79, s2, 0x1600
	s_mul_i32 s78, s2, 0x1600
	s_or_b32 s2, s20, 4
	s_mul_hi_i32 s75, s2, 0x1600
	s_mul_i32 s74, s2, 0x1600
	s_or_b32 s2, s20, 6
	s_mul_hi_i32 s81, s2, 0x1600
	s_mul_i32 s80, s2, 0x1600
	s_or_b32 s2, s20, 8
	s_mul_hi_i32 s83, s2, 0x1600
	s_mul_i32 s82, s2, 0x1600
	s_or_b32 s2, s20, 10
	s_mul_hi_i32 s85, s2, 0x1600
	s_mul_i32 s84, s2, 0x1600
	s_or_b32 s2, s20, 12
	s_mul_hi_i32 s87, s2, 0x1600
	s_mul_i32 s86, s2, 0x1600
	s_or_b32 s2, s20, 14
	s_mul_hi_i32 s89, s2, 0x1600
	s_mul_i32 s88, s2, 0x1600
	s_or_b32 s2, s20, 16
	s_mul_hi_i32 s91, s2, 0x1600
	s_mul_i32 s90, s2, 0x1600
	s_or_b32 s2, s20, 18
	s_mul_hi_i32 s93, s2, 0x1600
	s_mul_i32 s92, s2, 0x1600
	s_or_b32 s2, s20, 20
	s_mul_hi_i32 s95, s2, 0x1600
	s_mul_i32 s94, s2, 0x1600
	s_or_b32 s2, s20, 22
	s_mul_hi_i32 s97, s2, 0x1600
	s_mul_i32 s96, s2, 0x1600
	s_or_b32 s2, s20, 24
	s_mul_hi_i32 s5, s2, 0x1600
	s_mul_i32 s4, s2, 0x1600
	s_or_b32 s2, s20, 26
	s_mul_hi_i32 s9, s2, 0x1600
	s_mul_i32 s8, s2, 0x1600
	s_or_b32 s2, s20, 28
	s_mul_hi_i32 s77, s20, 0x1600
	s_mul_i32 s76, s20, 0x1600
	s_mul_hi_i32 s3, s2, 0x1600
	s_mulk_i32 s2, 0x1600
	v_lshl_add_u64 v[20:21], s[76:77], 2, v[6:7]
	v_lshl_add_u64 v[34:35], s[88:89], 2, v[6:7]
	v_writelane_b32 v249, s2, 8
	v_lshl_add_u64 v[22:23], s[78:79], 2, v[6:7]
	v_lshl_add_u64 v[24:25], s[74:75], 2, v[6:7]
	v_lshl_add_u64 v[26:27], s[80:81], 2, v[6:7]
	v_lshl_add_u64 v[28:29], s[82:83], 2, v[6:7]
	v_lshl_add_u64 v[30:31], s[84:85], 2, v[6:7]
	v_lshl_add_u64 v[32:33], s[86:87], 2, v[6:7]
	global_load_dword v14, v[20:21], off sc1 nt
	global_load_dword v16, v[22:23], off sc1 nt
	global_load_dword v17, v[24:25], off sc1 nt
	global_load_dword v18, v[26:27], off sc1 nt
	global_load_dword v5, v[28:29], off sc1 nt
	global_load_dword v10, v[30:31], off sc1 nt
	global_load_dword v12, v[32:33], off sc1 nt
	global_load_dword v13, v[34:35], off sc1 nt
	v_writelane_b32 v249, s3, 9
	v_lshl_add_u64 v[34:35], s[2:3], 2, v[6:7]
	s_or_b32 s2, s20, 30
	s_mul_hi_i32 s3, s2, 0x1600
	s_mulk_i32 s2, 0x1600
	v_writelane_b32 v249, s2, 10
	v_lshl_add_u64 v[20:21], s[90:91], 2, v[6:7]
	v_lshl_add_u64 v[22:23], s[92:93], 2, v[6:7]
	v_writelane_b32 v249, s3, 11
	v_lshl_add_u64 v[36:37], s[2:3], 2, v[6:7]
	s_or_b32 s2, s20, 32
	s_mul_hi_i32 s3, s2, 0x1600
	s_mulk_i32 s2, 0x1600
	v_lshl_add_u64 v[24:25], s[94:95], 2, v[6:7]
	v_lshl_add_u64 v[28:29], s[96:97], 2, v[6:7]
	v_writelane_b32 v249, s2, 12
	v_lshl_add_u64 v[30:31], s[4:5], 2, v[6:7]
	v_lshl_add_u64 v[32:33], s[8:9], 2, v[6:7]
	global_load_dword v26, v[20:21], off sc1 nt
	s_nop 0
	global_load_dword v21, v[22:23], off sc1 nt
	s_nop 0
	global_load_dword v22, v[24:25], off sc1 nt
	global_load_dword v23, v[28:29], off sc1 nt
	s_nop 0
	global_load_dword v24, v[30:31], off sc1 nt
	global_load_dword v25, v[32:33], off sc1 nt
	global_load_dword v19, v[34:35], off sc1 nt
	global_load_dword v20, v[36:37], off sc1 nt
	v_writelane_b32 v249, s3, 13
	v_lshl_add_u64 v[28:29], s[2:3], 2, v[6:7]
	s_or_b32 s2, s20, 34
	s_mul_hi_i32 s3, s2, 0x1600
	s_mulk_i32 s2, 0x1600
	v_writelane_b32 v249, s2, 14
	v_cndmask_b32_e64 v15, 0, 1, s[0:1]
	s_andn2_b64 vcc, exec, s[0:1]
	v_writelane_b32 v249, s3, 15
	v_lshl_add_u64 v[30:31], s[2:3], 2, v[6:7]
	s_or_b32 s2, s20, 36
	s_mul_hi_i32 s3, s2, 0x1600
	s_mulk_i32 s2, 0x1600
	v_writelane_b32 v249, s2, 16
	s_nop 1
	v_writelane_b32 v249, s3, 17
	v_lshl_add_u64 v[34:35], s[2:3], 2, v[6:7]
	s_or_b32 s2, s20, 38
	s_mul_hi_i32 s3, s2, 0x1600
	s_mulk_i32 s2, 0x1600
	v_writelane_b32 v249, s2, 18
	s_nop 1
	v_writelane_b32 v249, s3, 19
	v_lshl_add_u64 v[36:37], s[2:3], 2, v[6:7]
	s_or_b32 s2, s20, 40
	s_mul_hi_i32 s3, s2, 0x1600
	s_mulk_i32 s2, 0x1600
	v_writelane_b32 v249, s2, 20
	s_nop 1
	v_writelane_b32 v249, s3, 21
	v_lshl_add_u64 v[38:39], s[2:3], 2, v[6:7]
	s_or_b32 s2, s20, 42
	s_mul_hi_i32 s3, s2, 0x1600
	s_mulk_i32 s2, 0x1600
	v_writelane_b32 v249, s2, 22
	s_nop 1
	v_writelane_b32 v249, s3, 23
	v_lshl_add_u64 v[40:41], s[2:3], 2, v[6:7]
	s_or_b32 s2, s20, 44
	s_mul_hi_i32 s3, s2, 0x1600
	s_mulk_i32 s2, 0x1600
	v_writelane_b32 v249, s2, 24
	s_nop 1
	v_writelane_b32 v249, s3, 25
	v_lshl_add_u64 v[42:43], s[2:3], 2, v[6:7]
	s_or_b32 s2, s20, 46
	s_mul_hi_i32 s3, s2, 0x1600
	s_mulk_i32 s2, 0x1600
	v_writelane_b32 v249, s2, 26
	s_nop 1
	v_writelane_b32 v249, s3, 27
	v_lshl_add_u64 v[44:45], s[2:3], 2, v[6:7]
	s_or_b32 s2, s20, 48
	s_mul_hi_i32 s3, s2, 0x1600
	s_mulk_i32 s2, 0x1600
	v_writelane_b32 v249, s2, 28
	global_load_dword v32, v[28:29], off sc1 nt
	global_load_dword v33, v[30:31], off sc1 nt
	s_nop 0
	global_load_dword v34, v[34:35], off sc1 nt
	s_nop 0
	global_load_dword v27, v[36:37], off sc1 nt
	global_load_dword v28, v[38:39], off sc1 nt
	global_load_dword v29, v[40:41], off sc1 nt
	global_load_dword v30, v[42:43], off sc1 nt
	global_load_dword v31, v[44:45], off sc1 nt
	v_writelane_b32 v249, s3, 29
	v_lshl_add_u64 v[36:37], s[2:3], 2, v[6:7]
	s_or_b32 s2, s20, 50
	s_mul_hi_i32 s3, s2, 0x1600
	s_mulk_i32 s2, 0x1600
	v_writelane_b32 v249, s2, 30
	s_nop 1
	v_writelane_b32 v249, s3, 31
	v_lshl_add_u64 v[40:41], s[2:3], 2, v[6:7]
	s_or_b32 s2, s20, 52
	s_mul_hi_i32 s3, s2, 0x1600
	s_mulk_i32 s2, 0x1600
	v_writelane_b32 v249, s2, 32
	s_nop 1
	v_writelane_b32 v249, s3, 33
	v_lshl_add_u64 v[42:43], s[2:3], 2, v[6:7]
	s_or_b32 s2, s20, 54
	s_mul_hi_i32 s3, s2, 0x1600
	s_mulk_i32 s2, 0x1600
	v_writelane_b32 v249, s2, 34
	s_nop 1
	v_writelane_b32 v249, s3, 35
	v_lshl_add_u64 v[44:45], s[2:3], 2, v[6:7]
	s_or_b32 s2, s20, 56
	s_mul_hi_i32 s3, s2, 0x1600
	s_mulk_i32 s2, 0x1600
	v_writelane_b32 v249, s2, 36
	s_nop 1
	v_writelane_b32 v249, s3, 37
	v_lshl_add_u64 v[46:47], s[2:3], 2, v[6:7]
	s_or_b32 s2, s20, 58
	s_mul_hi_i32 s3, s2, 0x1600
	s_mulk_i32 s2, 0x1600
	v_writelane_b32 v249, s2, 38
	s_nop 1
	v_writelane_b32 v249, s3, 39
	v_lshl_add_u64 v[48:49], s[2:3], 2, v[6:7]
	s_or_b32 s2, s20, 60
	s_mul_hi_i32 s3, s2, 0x1600
	s_mulk_i32 s2, 0x1600
	v_writelane_b32 v249, s2, 40
	s_nop 1
	v_writelane_b32 v249, s3, 41
	v_lshl_add_u64 v[50:51], s[2:3], 2, v[6:7]
	s_or_b32 s2, s20, 62
	s_mul_hi_i32 s3, s2, 0x1600
	s_mulk_i32 s2, 0x1600
	v_writelane_b32 v249, s2, 42
	s_nop 1
	v_lshl_add_u64 v[52:53], s[2:3], 2, v[6:7]
	global_load_dword v38, v[36:37], off sc1 nt
	global_load_dword v39, v[40:41], off sc1 nt
	s_nop 0
	global_load_dword v40, v[42:43], off sc1 nt
	global_load_dword v41, v[44:45], off sc1 nt
	s_nop 0
	global_load_dword v42, v[46:47], off sc1 nt
	global_load_dword v35, v[48:49], off sc1 nt
	global_load_dword v36, v[50:51], off sc1 nt
	global_load_dword v37, v[52:53], off sc1 nt
	v_writelane_b32 v249, s3, 43
	v_cmp_ne_u32_e64 s[2:3], 1, v15
	s_nop 1
	v_writelane_b32 v249, s2, 44
	s_nop 1
	v_writelane_b32 v249, s3, 45
	s_cbranch_vccnz .LBB0_46
	v_lshl_add_u64 v[44:45], v[2:3], 2, s[12:13]
	global_load_dword v8, v[44:45], off offset:256 sc1 nt
.LBB0_46:
	s_or_b32 s0, s20, 64
	s_mul_hi_i32 s1, s0, 0x1600
	s_mulk_i32 s0, 0x1600
	v_writelane_b32 v249, s0, 46
	s_or_b32 s2, s20, 0x4e
	s_mul_hi_i32 s13, s2, 0x1600
	v_writelane_b32 v249, s1, 47
	v_lshl_add_u64 v[44:45], s[0:1], 2, v[6:7]
	s_or_b32 s0, s20, 0x42
	s_mul_hi_i32 s1, s0, 0x1600
	s_mulk_i32 s0, 0x1600
	v_writelane_b32 v249, s0, 48
	s_mul_i32 s12, s2, 0x1600
	v_lshl_add_u64 v[58:59], s[12:13], 2, v[6:7]
	v_writelane_b32 v249, s1, 49
	v_lshl_add_u64 v[46:47], s[0:1], 2, v[6:7]
	s_or_b32 s0, s20, 0x44
	s_mul_hi_i32 s1, s0, 0x1600
	s_mulk_i32 s0, 0x1600
	v_writelane_b32 v249, s0, 50
	s_or_b32 s2, s20, 0x50
	s_or_b32 s21, s20, 0x56
	v_writelane_b32 v249, s1, 51
	v_lshl_add_u64 v[48:49], s[0:1], 2, v[6:7]
	s_or_b32 s0, s20, 0x46
	s_mul_hi_i32 s1, s0, 0x1600
	s_mulk_i32 s0, 0x1600
	v_writelane_b32 v249, s0, 52
	s_mul_hi_i32 s15, s2, 0x1600
	s_mul_i32 s14, s2, 0x1600
	v_writelane_b32 v249, s1, 53
	v_lshl_add_u64 v[50:51], s[0:1], 2, v[6:7]
	s_or_b32 s0, s20, 0x48
	s_mul_hi_i32 s1, s0, 0x1600
	s_mulk_i32 s0, 0x1600
	v_writelane_b32 v249, s0, 54
	s_or_b32 s2, s20, 0x52
	s_mul_hi_i32 s25, s21, 0x1600
	v_writelane_b32 v249, s1, 55
	v_lshl_add_u64 v[52:53], s[0:1], 2, v[6:7]
	s_or_b32 s0, s20, 0x4a
	s_mul_hi_i32 s1, s0, 0x1600
	s_mulk_i32 s0, 0x1600
	v_writelane_b32 v249, s0, 56
	s_mul_i32 s24, s21, 0x1600
	s_or_b32 s21, s20, 0x58
	v_writelane_b32 v249, s1, 57
	v_lshl_add_u64 v[54:55], s[0:1], 2, v[6:7]
	s_or_b32 s0, s20, 0x4c
	s_mul_hi_i32 s1, s0, 0x1600
	s_mulk_i32 s0, 0x1600
	v_writelane_b32 v249, s0, 58
	s_mul_hi_i32 s7, s2, 0x1600
	s_mul_i32 s6, s2, 0x1600
	v_lshl_add_u64 v[56:57], s[0:1], 2, v[6:7]
	global_load_dword v43, v[44:45], off sc1 nt
	global_load_dword v74, v[46:47], off sc1 nt
	global_load_dword v75, v[48:49], off sc1 nt
	global_load_dword v76, v[50:51], off sc1 nt
	global_load_dword v77, v[52:53], off sc1 nt
	global_load_dword v78, v[54:55], off sc1 nt
	global_load_dword v79, v[56:57], off sc1 nt
	global_load_dword v80, v[58:59], off sc1 nt
	v_lshl_add_u64 v[44:45], s[14:15], 2, v[6:7]
	s_mul_hi_i32 s27, s21, 0x1600
	s_mul_i32 s26, s21, 0x1600
	s_or_b32 s21, s20, 0x5a
	v_lshl_add_u64 v[46:47], s[6:7], 2, v[6:7]
	global_load_dword v81, v[44:45], off sc1 nt
	global_load_dword v82, v[46:47], off sc1 nt
	s_mul_hi_i32 s29, s21, 0x1600
	s_mul_i32 s28, s21, 0x1600
	s_or_b32 s21, s20, 0x5c
	s_or_b32 s2, s20, 0x54
	s_mul_hi_i32 s31, s21, 0x1600
	s_mul_i32 s30, s21, 0x1600
	s_or_b32 s21, s20, 0x5e
	s_mul_hi_i32 s3, s2, 0x1600
	s_mulk_i32 s2, 0x1600
	s_mul_hi_i32 s35, s21, 0x1600
	s_mul_i32 s34, s21, 0x1600
	s_or_b32 s21, s20, 0x60
	v_lshl_add_u64 v[44:45], s[2:3], 2, v[6:7]
	s_mul_hi_i32 s37, s21, 0x1600
	s_mul_i32 s36, s21, 0x1600
	s_or_b32 s21, s20, 0x62
	v_lshl_add_u64 v[46:47], s[24:25], 2, v[6:7]
	v_lshl_add_u64 v[48:49], s[26:27], 2, v[6:7]
	v_lshl_add_u64 v[50:51], s[28:29], 2, v[6:7]
	v_lshl_add_u64 v[52:53], s[30:31], 2, v[6:7]
	v_lshl_add_u64 v[54:55], s[34:35], 2, v[6:7]
	global_load_dword v83, v[44:45], off sc1 nt
	global_load_dword v84, v[46:47], off sc1 nt
	global_load_dword v85, v[48:49], off sc1 nt
	global_load_dword v86, v[50:51], off sc1 nt
	global_load_dword v87, v[52:53], off sc1 nt
	global_load_dword v88, v[54:55], off sc1 nt
	s_mul_hi_i32 s39, s21, 0x1600
	s_mul_i32 s38, s21, 0x1600
	s_or_b32 s21, s20, 0x64
	v_lshl_add_u64 v[44:45], s[36:37], 2, v[6:7]
	s_mul_hi_i32 s41, s21, 0x1600
	s_mul_i32 s40, s21, 0x1600
	s_or_b32 s21, s20, 0x66
	v_lshl_add_u64 v[46:47], s[38:39], 2, v[6:7]
	global_load_dword v89, v[44:45], off sc1 nt
	global_load_dword v90, v[46:47], off sc1 nt
	s_mul_hi_i32 s43, s21, 0x1600
	s_mul_i32 s42, s21, 0x1600
	s_or_b32 s21, s20, 0x68
	v_lshl_add_u64 v[44:45], s[40:41], 2, v[6:7]
	v_lshl_add_u64 v[46:47], s[42:43], 2, v[6:7]
	s_mul_hi_i32 s45, s21, 0x1600
	s_mul_i32 s44, s21, 0x1600
	s_or_b32 s21, s20, 0x6a
	global_load_dword v91, v[44:45], off sc1 nt
	s_nop 0
	global_load_dword v46, v[46:47], off sc1 nt
	v_lshl_add_u64 v[44:45], s[44:45], 2, v[6:7]
	s_mul_hi_i32 s47, s21, 0x1600
	s_mul_i32 s46, s21, 0x1600
	s_or_b32 s21, s20, 0x6c
	global_load_dword v47, v[44:45], off sc1 nt
	v_lshl_add_u64 v[44:45], s[46:47], 2, v[6:7]
	s_mul_hi_i32 s49, s21, 0x1600
	s_mul_i32 s48, s21, 0x1600
	s_or_b32 s21, s20, 0x6e
	global_load_dword v92, v[44:45], off sc1 nt
	v_lshl_add_u64 v[44:45], s[48:49], 2, v[6:7]
	s_mul_hi_i32 s53, s21, 0x1600
	s_mul_i32 s52, s21, 0x1600
	s_or_b32 s21, s20, 0x70
	global_load_dword v93, v[44:45], off sc1 nt
	v_lshl_add_u64 v[44:45], s[52:53], 2, v[6:7]
	s_mul_hi_i32 s51, s21, 0x1600
	s_mul_i32 s50, s21, 0x1600
	s_or_b32 s21, s20, 0x72
	global_load_dword v94, v[44:45], off sc1 nt
	v_lshl_add_u64 v[44:45], s[50:51], 2, v[6:7]
	s_mul_hi_i32 s55, s21, 0x1600
	s_mul_i32 s54, s21, 0x1600
	s_or_b32 s21, s20, 0x74
	global_load_dword v95, v[44:45], off sc1 nt
	v_lshl_add_u64 v[44:45], s[54:55], 2, v[6:7]
	s_mul_hi_i32 s57, s21, 0x1600
	s_mul_i32 s56, s21, 0x1600
	s_or_b32 s21, s20, 0x76
	global_load_dword v96, v[44:45], off sc1 nt
	v_lshl_add_u64 v[44:45], s[56:57], 2, v[6:7]
	s_mul_hi_i32 s59, s21, 0x1600
	s_mul_i32 s58, s21, 0x1600
	s_or_b32 s21, s20, 0x78
	global_load_dword v97, v[44:45], off sc1 nt
	s_mul_hi_i32 s61, s21, 0x1600
	s_mul_i32 s60, s21, 0x1600
	s_or_b32 s21, s20, 0x7a
	v_lshl_add_u64 v[44:45], s[58:59], 2, v[6:7]
	s_mul_hi_i32 s63, s21, 0x1600
	s_mul_i32 s62, s21, 0x1600
	s_or_b32 s21, s20, 0x7c
	global_load_dword v98, v[44:45], off sc1 nt
	v_lshl_add_u64 v[44:45], s[60:61], 2, v[6:7]
	s_mul_hi_i32 s65, s21, 0x1600
	s_mul_i32 s64, s21, 0x1600
	s_or_b32 s21, s20, 0x7e
	global_load_dword v99, v[44:45], off sc1 nt
	v_lshl_add_u64 v[44:45], s[62:63], 2, v[6:7]
	s_mul_hi_i32 s67, s21, 0x1600
	s_mul_i32 s66, s21, 0x1600
	global_load_dword v100, v[44:45], off sc1 nt
	v_lshl_add_u64 v[44:45], s[64:65], 2, v[6:7]
	v_lshl_add_u64 v[6:7], s[66:67], 2, v[6:7]
	global_load_dword v101, v[44:45], off sc1 nt
	global_load_dword v102, v[6:7], off sc1 nt
	v_lshlrev_b32_e32 v15, 2, v11
	s_waitcnt vmcnt(62)
	ds_bpermute_b32 v45, v15, v9 offset:8
	ds_bpermute_b32 v48, v15, v9 offset:16
	ds_bpermute_b32 v49, v15, v9 offset:24
	ds_bpermute_b32 v50, v15, v9 offset:64
	ds_bpermute_b32 v44, v15, v9
	s_waitcnt lgkmcnt(4)
	v_mul_f32_e32 v16, v16, v45
	s_waitcnt vmcnt(61) lgkmcnt(3)
	v_mul_f32_e32 v7, v17, v48
	s_waitcnt vmcnt(60) lgkmcnt(2)
	v_mul_f32_e32 v6, v18, v49
	ds_bpermute_b32 v17, v15, v9 offset:32
	ds_bpermute_b32 v18, v15, v9 offset:40
	ds_bpermute_b32 v45, v15, v9 offset:56
	s_waitcnt lgkmcnt(3)
	v_mul_f32_e32 v14, v14, v44
	ds_bpermute_b32 v44, v15, v9 offset:48
	s_waitcnt vmcnt(59) lgkmcnt(3)
	v_mul_f32_e32 v55, v5, v17
	s_waitcnt vmcnt(58) lgkmcnt(2)
	v_mul_f32_e32 v53, v10, v18
	s_waitcnt vmcnt(56) lgkmcnt(1)
	v_mul_f32_e32 v48, v13, v45
	ds_bpermute_b32 v5, v15, v9 offset:72
	ds_bpermute_b32 v10, v15, v9 offset:80
	ds_bpermute_b32 v13, v15, v9 offset:96
	ds_bpermute_b32 v18, v15, v9 offset:104
	s_waitcnt vmcnt(55)
	v_mul_f32_e32 v17, v26, v50
	s_waitcnt vmcnt(54) lgkmcnt(3)
	v_mul_f32_e32 v61, v21, v5
	s_waitcnt vmcnt(53) lgkmcnt(2)
	v_mul_f32_e32 v56, v22, v10
	s_waitcnt vmcnt(51) lgkmcnt(1)
	v_mul_f32_e32 v51, v24, v13
	ds_bpermute_b32 v5, v15, v9 offset:112
	ds_bpermute_b32 v10, v15, v9 offset:120
	ds_bpermute_b32 v13, v15, v9 offset:136
	s_waitcnt vmcnt(50) lgkmcnt(3)
	v_mul_f32_e32 v50, v25, v18
	ds_bpermute_b32 v18, v15, v9 offset:144
	s_waitcnt vmcnt(49) lgkmcnt(3)
	v_mul_f32_e32 v64, v19, v5
	s_waitcnt vmcnt(48) lgkmcnt(2)
	v_mul_f32_e32 v62, v20, v10
	s_waitcnt vmcnt(46) lgkmcnt(1)
	v_mul_f32_e32 v57, v33, v13
	ds_bpermute_b32 v5, v15, v9 offset:152
	ds_bpermute_b32 v10, v15, v9 offset:160
	ds_bpermute_b32 v13, v15, v9 offset:176
	s_waitcnt vmcnt(45) lgkmcnt(3)
	v_mul_f32_e32 v52, v34, v18
	ds_bpermute_b32 v18, v15, v9 offset:184
	s_waitcnt vmcnt(44) lgkmcnt(3)
	v_mul_f32_e32 v69, v27, v5
	s_waitcnt vmcnt(43) lgkmcnt(2)
	v_mul_f32_e32 v66, v28, v10
	s_waitcnt vmcnt(41) lgkmcnt(1)
	v_mul_f32_e32 v60, v30, v13
	ds_bpermute_b32 v5, v15, v9 offset:192
	ds_bpermute_b32 v10, v15, v9 offset:200
	ds_bpermute_b32 v13, v15, v9 offset:216
	v_mul_f32_e32 v49, v12, v44
	ds_bpermute_b32 v12, v15, v9 offset:88
	s_waitcnt vmcnt(40) lgkmcnt(4)
	v_mul_f32_e32 v58, v31, v18
	ds_bpermute_b32 v18, v15, v9 offset:224
	s_waitcnt vmcnt(39) lgkmcnt(4)
	v_mul_f32_e32 v71, v38, v5
	s_waitcnt vmcnt(38) lgkmcnt(3)
	v_mul_f32_e32 v70, v39, v10
	s_waitcnt vmcnt(36) lgkmcnt(2)
	v_mul_f32_e32 v67, v41, v13
	ds_bpermute_b32 v5, v15, v9 offset:232
	ds_bpermute_b32 v10, v15, v9 offset:240
	s_waitcnt vmcnt(32)
	ds_bpermute_b32 v13, v15, v8 offset:8
	s_waitcnt lgkmcnt(4)
	v_mul_f32_e32 v54, v23, v12
	ds_bpermute_b32 v12, v15, v9 offset:128
	s_waitcnt lgkmcnt(4)
	v_mul_f32_e32 v63, v42, v18
	s_waitcnt lgkmcnt(3)
	v_mul_f32_e32 v73, v35, v5
	s_waitcnt lgkmcnt(2)
	v_mul_f32_e32 v72, v36, v10
	s_waitcnt vmcnt(30) lgkmcnt(1)
	v_mul_f32_e32 v5, v74, v13
	ds_bpermute_b32 v10, v15, v8 offset:16
	ds_bpermute_b32 v13, v15, v8 offset:24
	ds_bpermute_b32 v18, v15, v8 offset:32
	ds_bpermute_b32 v21, v15, v8 offset:48
	s_waitcnt lgkmcnt(4)
	v_mul_f32_e32 v59, v32, v12
	ds_bpermute_b32 v12, v15, v9 offset:168
	s_waitcnt vmcnt(29) lgkmcnt(4)
	v_mul_f32_e32 v24, v75, v10
	s_waitcnt vmcnt(28) lgkmcnt(3)
	v_mul_f32_e32 v22, v76, v13
	s_waitcnt vmcnt(27) lgkmcnt(2)
	v_mul_f32_e32 v20, v77, v18
	s_waitcnt vmcnt(25) lgkmcnt(1)
	v_mul_f32_e32 v13, v79, v21
	ds_bpermute_b32 v10, v15, v8 offset:56
	ds_bpermute_b32 v18, v15, v8 offset:64
	ds_bpermute_b32 v21, v15, v8 offset:72
	ds_bpermute_b32 v27, v15, v8 offset:88
	s_waitcnt lgkmcnt(4)
	v_mul_f32_e32 v65, v29, v12
	ds_bpermute_b32 v12, v15, v9 offset:208
	ds_bpermute_b32 v9, v15, v9 offset:248
	s_waitcnt vmcnt(24) lgkmcnt(5)
	v_mul_f32_e32 v28, v80, v10
	s_waitcnt vmcnt(23) lgkmcnt(4)
	v_mul_f32_e32 v26, v81, v18
	s_waitcnt vmcnt(22) lgkmcnt(3)
	v_mul_f32_e32 v25, v82, v21
	s_waitcnt vmcnt(20) lgkmcnt(2)
	v_mul_f32_e32 v21, v84, v27
	ds_bpermute_b32 v10, v15, v8 offset:96
	ds_bpermute_b32 v18, v15, v8 offset:104
	ds_bpermute_b32 v27, v15, v8 offset:112
	ds_bpermute_b32 v31, v15, v8 offset:128
	s_waitcnt lgkmcnt(4)
	v_mul_f32_e32 v9, v37, v9
	s_waitcnt vmcnt(19) lgkmcnt(3)
	v_mul_f32_e32 v34, v85, v10
	s_waitcnt vmcnt(18) lgkmcnt(2)
	v_mul_f32_e32 v32, v86, v18
	s_waitcnt vmcnt(17) lgkmcnt(1)
	v_mul_f32_e32 v30, v87, v27
	s_waitcnt vmcnt(15) lgkmcnt(0)
	v_mul_f32_e32 v27, v89, v31
	ds_bpermute_b32 v10, v15, v8 offset:136
	ds_bpermute_b32 v18, v15, v8 offset:144
	ds_bpermute_b32 v31, v15, v8 offset:152
	ds_bpermute_b32 v37, v15, v8 offset:168
	v_mul_f32_e32 v68, v40, v12
	ds_bpermute_b32 v12, v15, v8
	s_waitcnt vmcnt(14) lgkmcnt(4)
	v_mul_f32_e32 v38, v90, v10
	s_waitcnt vmcnt(13) lgkmcnt(3)
	v_mul_f32_e32 v36, v91, v18
	s_waitcnt vmcnt(12) lgkmcnt(2)
	v_mul_f32_e32 v35, v46, v31
	s_waitcnt vmcnt(10) lgkmcnt(1)
	v_mul_f32_e32 v31, v92, v37
	ds_bpermute_b32 v10, v15, v8 offset:176
	ds_bpermute_b32 v18, v15, v8 offset:184
	ds_bpermute_b32 v37, v15, v8 offset:192
	ds_bpermute_b32 v41, v15, v8 offset:208
	s_waitcnt lgkmcnt(4)
	v_mul_f32_e32 v12, v43, v12
	ds_bpermute_b32 v19, v15, v8 offset:40
	ds_bpermute_b32 v23, v15, v8 offset:80
	ds_bpermute_b32 v29, v15, v8 offset:120
	ds_bpermute_b32 v33, v15, v8 offset:160
	ds_bpermute_b32 v39, v15, v8 offset:200
	s_waitcnt vmcnt(9) lgkmcnt(8)
	v_mul_f32_e32 v44, v93, v10
	s_waitcnt vmcnt(8) lgkmcnt(7)
	v_mul_f32_e32 v42, v94, v18
	s_waitcnt vmcnt(7) lgkmcnt(6)
	v_mul_f32_e32 v40, v95, v37
	s_waitcnt vmcnt(5) lgkmcnt(5)
	v_mul_f32_e32 v37, v97, v41
	ds_bpermute_b32 v10, v15, v8 offset:216
	ds_bpermute_b32 v18, v15, v8 offset:224
	ds_bpermute_b32 v41, v15, v8 offset:232
	ds_bpermute_b32 v43, v15, v8 offset:240
	ds_bpermute_b32 v8, v15, v8 offset:248
	s_waitcnt lgkmcnt(9)
	v_mul_f32_e32 v19, v78, v19
	s_waitcnt lgkmcnt(8)
	v_mul_f32_e32 v23, v83, v23
	s_waitcnt vmcnt(2) lgkmcnt(2)
	v_mul_f32_e32 v45, v100, v41
	v_mul_f32_e32 v29, v88, v29
	s_waitcnt vmcnt(0) lgkmcnt(0)
	v_mul_f32_e32 v41, v102, v8
	v_max3_f32 v8, |v14|, 0, |v16|
	v_max3_f32 v8, v8, |v7|, |v6|
	v_max3_f32 v8, v8, |v55|, |v53|
	v_max3_f32 v8, v8, |v49|, |v48|
	v_max3_f32 v8, v8, |v17|, |v61|
	v_max3_f32 v8, v8, |v56|, |v54|
	v_max3_f32 v8, v8, |v51|, |v50|
	v_max3_f32 v8, v8, |v64|, |v62|
	v_max3_f32 v8, v8, |v59|, |v57|
	v_max3_f32 v8, v8, |v52|, |v69|
	v_max3_f32 v8, v8, |v66|, |v65|
	v_max3_f32 v8, v8, |v60|, |v58|
	v_max3_f32 v8, v8, |v71|, |v70|
	v_max3_f32 v8, v8, |v68|, |v67|
	v_max3_f32 v8, v8, |v63|, |v73|
	v_max3_f32 v8, v8, |v72|, |v9|
	v_max3_f32 v8, v8, |v12|, |v5|
	v_max3_f32 v8, v8, |v24|, |v22|
	v_max3_f32 v8, v8, |v20|, |v19|
	v_max3_f32 v8, v8, |v13|, |v28|
	v_max3_f32 v8, v8, |v26|, |v25|
	v_max3_f32 v8, v8, |v23|, |v21|
	v_max3_f32 v8, v8, |v34|, |v32|
	v_max3_f32 v8, v8, |v30|, |v29|
	v_max3_f32 v8, v8, |v27|, |v38|
	v_mul_f32_e32 v33, v47, v33
	v_max3_f32 v8, v8, |v36|, |v35|
	v_max3_f32 v8, v8, |v33|, |v31|
	v_mul_f32_e32 v39, v96, v39
	v_max3_f32 v8, v8, |v44|, |v42|
	v_mul_f32_e32 v47, v98, v10
	v_max3_f32 v8, v8, |v40|, |v39|
	v_mul_f32_e32 v46, v99, v18
	v_max3_f32 v8, v8, |v37|, |v47|
	v_mul_f32_e32 v43, v101, v43
	v_max3_f32 v8, v8, |v46|, |v45|
	v_max3_f32 v8, v8, |v43|, |v41|
	v_writelane_b32 v249, s1, 59
	v_mov_b32_e32 v10, v8
	v_cmp_gt_u32_e64 s[0:1], 32, v108
	s_ashr_i32 s21, s20, 31
	v_permlane32_swap_b32_e32 v8, v10
	v_writelane_b32 v249, s0, 60
	s_nop 1
	v_writelane_b32 v249, s1, 61
	s_and_saveexec_b64 s[68:69], s[0:1]
	s_cbranch_execz .LBB0_48
	v_max_f32_e32 v8, v8, v8
	v_max_f32_e32 v10, v10, v10
	s_add_i32 s23, s20, 0
	v_max_f32_e32 v8, v8, v10
	v_lshl_add_u32 v10, v108, 2, s23
	v_add_u32_e32 v10, 0x20000, v10
	ds_write_b32 v10, v8

.LBB0_50:
	s_or_b64 exec, exec, vcc
	s_mov_b32 s23, 0x42fe0000
	v_div_scale_f32 v10, s[70:71], v8, v8, s23
	v_rcp_f32_e32 v74, v10
	v_div_scale_f32 v75, vcc, s23, v8, s23
	s_mov_b64 s[70:71], 0xa00000
	v_fma_f32 v76, -v10, v74, 1.0
	v_fmac_f32_e32 v74, v76, v74
	v_mul_f32_e32 v76, v75, v74
	v_fma_f32 v77, -v10, v76, v75
	v_fmac_f32_e32 v76, v77, v74
	v_fma_f32 v10, -v10, v76, v75
	v_div_fmas_f32 v10, v10, v74, v76
	v_div_fixup_f32 v10, v10, v8, s23
	v_cmp_lt_f32_e32 vcc, 0, v8
	v_readlane_b32 s23, v249, 5
	s_mov_b32 s33, s19
	v_cndmask_b32_e32 v74, 0, v10, vcc
	v_mul_f32_e32 v14, v14, v74
	v_lshlrev_b32_e32 v10, 2, v1
	v_rndne_f32_e32 v75, v14
	v_mul_u32_u24_e32 v14, 0x84, v11
	v_mul_f32_e32 v7, v7, v74
	v_mul_f32_e32 v6, v6, v74
	v_add3_u32 v14, s23, v10, v14
	v_mul_f32_e32 v16, v16, v74
	v_rndne_f32_e32 v7, v7
	v_rndne_f32_e32 v6, v6
	v_rndne_f32_e32 v16, v16
	ds_write2_b32 v14, v7, v6 offset0:132 offset1:198
	v_mul_f32_e32 v6, v55, v74
	v_mul_f32_e32 v7, v53, v74
	ds_write2_b32 v14, v75, v16 offset1:66
	v_rndne_f32_e32 v6, v6
	v_rndne_f32_e32 v7, v7
	v_add_u32_e32 v75, 0x400, v14
	ds_write2_b32 v75, v6, v7 offset0:8 offset1:74
	v_mul_f32_e32 v6, v49, v74
	v_mul_f32_e32 v7, v48, v74
	v_rndne_f32_e32 v6, v6
	v_rndne_f32_e32 v7, v7
	ds_write2_b32 v75, v6, v7 offset0:140 offset1:206
	v_mul_f32_e32 v6, v17, v74
	v_mul_f32_e32 v7, v61, v74
	v_rndne_f32_e32 v6, v6
	v_rndne_f32_e32 v7, v7
	v_add_u32_e32 v61, 0x800, v14
	ds_write2_b32 v61, v6, v7 offset0:16 offset1:82
	v_mul_f32_e32 v6, v56, v74
	v_mul_f32_e32 v7, v54, v74
	v_rndne_f32_e32 v6, v6
	v_rndne_f32_e32 v7, v7
	ds_write2_b32 v61, v6, v7 offset0:148 offset1:214
	v_mul_f32_e32 v6, v51, v74
	v_mul_f32_e32 v7, v50, v74
	v_rndne_f32_e32 v6, v6
	v_rndne_f32_e32 v7, v7
	v_add_u32_e32 v76, 0xc00, v14
	ds_write2_b32 v76, v6, v7 offset0:24 offset1:90
	v_mul_f32_e32 v6, v64, v74
	v_mul_f32_e32 v7, v62, v74
	v_rndne_f32_e32 v6, v6
	v_rndne_f32_e32 v7, v7
	ds_write2_b32 v76, v6, v7 offset0:156 offset1:222
	v_mul_f32_e32 v6, v59, v74
	v_mul_f32_e32 v7, v57, v74
	v_rndne_f32_e32 v6, v6
	v_rndne_f32_e32 v7, v7
	v_add_u32_e32 v59, 0x1000, v14
	ds_write2_b32 v59, v6, v7 offset0:32 offset1:98
	v_mul_f32_e32 v6, v52, v74
	v_mul_f32_e32 v7, v69, v74
	v_rndne_f32_e32 v6, v6
	v_rndne_f32_e32 v7, v7
	ds_write2_b32 v59, v6, v7 offset0:164 offset1:230
	v_mul_f32_e32 v6, v66, v74
	v_mul_f32_e32 v7, v65, v74
	v_rndne_f32_e32 v6, v6
	v_rndne_f32_e32 v7, v7
	v_add_u32_e32 v62, 0x1400, v14
	ds_write2_b32 v62, v6, v7 offset0:40 offset1:106
	v_mul_f32_e32 v6, v60, v74
	v_mul_f32_e32 v7, v58, v74
	v_rndne_f32_e32 v6, v6
	v_rndne_f32_e32 v7, v7
	ds_write2_b32 v62, v6, v7 offset0:172 offset1:238
	v_mul_f32_e32 v6, v71, v74
	v_mul_f32_e32 v7, v70, v74
	v_rndne_f32_e32 v6, v6
	v_rndne_f32_e32 v7, v7
	v_add_u32_e32 v58, 0x1800, v14
	ds_write2_b32 v58, v6, v7 offset0:48 offset1:114
	v_mul_f32_e32 v6, v68, v74
	v_mul_f32_e32 v7, v67, v74
	v_rndne_f32_e32 v6, v6
	v_rndne_f32_e32 v7, v7
	ds_write2_b32 v58, v6, v7 offset0:180 offset1:246
	v_mul_f32_e32 v6, v63, v74
	v_mul_f32_e32 v7, v73, v74
	v_rndne_f32_e32 v6, v6
	v_rndne_f32_e32 v7, v7
	v_add_u32_e32 v60, 0x1c00, v14
	ds_write2_b32 v60, v6, v7 offset0:56 offset1:122
	v_mul_f32_e32 v6, v72, v74
	v_mul_f32_e32 v7, v9, v74
	v_lshlrev_b32_e32 v1, 4, v108
	v_rndne_f32_e32 v6, v6
	v_rndne_f32_e32 v7, v7
	v_and_b32_e32 v8, 48, v1
	ds_write2_b32 v60, v6, v7 offset0:188 offset1:254
	v_mul_u32_u24_e32 v1, 0x84, v8
	s_waitcnt lgkmcnt(0)
	v_and_b32_e32 v6, 60, v108
	v_add3_u32 v1, s23, v1, v6
	ds_read2_b32 v[48:49], v1 offset1:33
	ds_read2_b32 v[50:51], v1 offset0:66 offset1:99
	v_mov_b32_e32 v9, 0
	v_lshl_add_u64 v[6:7], s[10:11], 0, v[8:9]
	v_lshl_add_u64 v[8:9], v[6:7], 0, s[20:21]
	s_waitcnt lgkmcnt(1)
	v_cvt_i32_f32_e32 v17, v49
	v_cvt_i32_f32_e32 v48, v48
	s_waitcnt lgkmcnt(0)
	v_cvt_i32_f32_sdwa v49, v50 dst_sel:WORD_1 dst_unused:UNUSED_PAD src0_sel:DWORD
	v_cvt_i32_f32_sdwa v52, v51 dst_sel:BYTE_3 dst_unused:UNUSED_PAD src0_sel:DWORD
	ds_read2_b32 v[50:51], v1 offset0:132 offset1:165
	v_lshlrev_b32_e32 v17, 8, v17
	s_mov_b32 s21, 0xc0c0500
	v_perm_b32 v17, v17, v48, s21
	v_and_b32_e32 v48, 0xff0000, v49
	v_or3_b32 v48, v17, v48, v52
	s_waitcnt lgkmcnt(0)
	v_cvt_i32_f32_e32 v17, v50
	v_cvt_i32_f32_e32 v49, v51
	ds_read2_b32 v[50:51], v1 offset0:198 offset1:231
	v_add_u32_e32 v63, 0x400, v1
	ds_read2_b32 v[52:53], v63 offset0:8 offset1:41
	v_lshlrev_b32_e32 v49, 8, v49
	v_perm_b32 v17, v49, v17, s21
	s_waitcnt lgkmcnt(1)
	v_cvt_i32_f32_sdwa v49, v50 dst_sel:WORD_1 dst_unused:UNUSED_PAD src0_sel:DWORD
	v_cvt_i32_f32_sdwa v54, v51 dst_sel:BYTE_3 dst_unused:UNUSED_PAD src0_sel:DWORD
	ds_read2_b32 v[50:51], v63 offset0:74 offset1:107
	s_waitcnt lgkmcnt(1)
	v_cvt_i32_f32_e32 v53, v53
	v_and_b32_e32 v49, 0xff0000, v49
	v_or3_b32 v49, v17, v49, v54
	v_cvt_i32_f32_e32 v17, v52
	v_lshlrev_b32_e32 v54, 8, v53
	s_waitcnt lgkmcnt(0)
	v_cvt_i32_f32_sdwa v50, v50 dst_sel:WORD_1 dst_unused:UNUSED_PAD src0_sel:DWORD
	ds_read2_b32 v[52:53], v63 offset0:140 offset1:173
	v_cvt_i32_f32_sdwa v51, v51 dst_sel:BYTE_3 dst_unused:UNUSED_PAD src0_sel:DWORD
	v_perm_b32 v17, v54, v17, s21
	ds_read2_b32 v[54:55], v63 offset0:206 offset1:239
	v_and_b32_e32 v50, 0xff0000, v50
	v_or3_b32 v50, v17, v50, v51
	s_waitcnt lgkmcnt(1)
	v_cvt_i32_f32_e32 v17, v53
	v_cvt_i32_f32_e32 v51, v52
	s_waitcnt lgkmcnt(0)
	v_cvt_i32_f32_sdwa v52, v54 dst_sel:WORD_1 dst_unused:UNUSED_PAD src0_sel:DWORD
	v_cvt_i32_f32_sdwa v53, v55 dst_sel:BYTE_3 dst_unused:UNUSED_PAD src0_sel:DWORD
	v_lshrrev_b32_e32 v16, 2, v108
	v_lshlrev_b32_e32 v17, 8, v17
	v_perm_b32 v17, v17, v51, s21
	v_and_b32_e32 v51, 0xff0000, v52
	v_or_b32_e32 v52, s68, v16
	v_or3_b32 v51, v17, v51, v53
	v_ashrrev_i32_e32 v53, 31, v52
	v_lshl_add_u64 v[6:7], v[8:9], 0, s[70:71]
	v_lshlrev_b64 v[52:53], 10, v[52:53]
	v_lshl_add_u64 v[54:55], v[6:7], 0, v[52:53]
	global_store_dwordx4 v[54:55], v[48:51], off sc1
	s_nop 1
	ds_read2_b32 v[48:49], v1 offset0:16 offset1:49
	ds_read2_b32 v[50:51], v1 offset0:82 offset1:115
	v_or_b32_e32 v17, 16, v16
	v_mul_f32_e32 v12, v12, v74
	v_mul_f32_e32 v5, v5, v74
	s_waitcnt lgkmcnt(1)
	v_cvt_i32_f32_e32 v54, v49
	v_cvt_i32_f32_e32 v55, v48
	s_waitcnt lgkmcnt(0)
	v_cvt_i32_f32_sdwa v50, v50 dst_sel:WORD_1 dst_unused:UNUSED_PAD src0_sel:DWORD
	ds_read2_b32 v[48:49], v1 offset0:148 offset1:181
	v_lshlrev_b32_e32 v54, 8, v54
	v_perm_b32 v54, v54, v55, s21
	v_and_b32_e32 v55, 0xff0000, v50
	v_cvt_i32_f32_sdwa v56, v51 dst_sel:BYTE_3 dst_unused:UNUSED_PAD src0_sel:DWORD
	ds_read2_b32 v[50:51], v1 offset0:214 offset1:247
	s_waitcnt lgkmcnt(1)
	v_cvt_i32_f32_e32 v49, v49
	v_cvt_i32_f32_e32 v57, v48
	v_or3_b32 v48, v54, v55, v56
	ds_read2_b32 v[54:55], v63 offset0:24 offset1:57
	v_lshlrev_b32_e32 v49, 8, v49
	s_waitcnt lgkmcnt(1)
	v_cvt_i32_f32_sdwa v56, v50 dst_sel:WORD_1 dst_unused:UNUSED_PAD src0_sel:DWORD
	v_perm_b32 v49, v49, v57, s21
	v_cvt_i32_f32_sdwa v57, v51 dst_sel:BYTE_3 dst_unused:UNUSED_PAD src0_sel:DWORD
	ds_read2_b32 v[50:51], v63 offset0:90 offset1:123
	s_waitcnt lgkmcnt(1)
	v_cvt_i32_f32_e32 v55, v55
	v_and_b32_e32 v56, 0xff0000, v56
	v_or3_b32 v49, v49, v56, v57
	v_cvt_i32_f32_e32 v56, v54
	v_lshlrev_b32_e32 v57, 8, v55
	s_waitcnt lgkmcnt(0)
	v_cvt_i32_f32_sdwa v50, v50 dst_sel:WORD_1 dst_unused:UNUSED_PAD src0_sel:DWORD
	ds_read2_b32 v[54:55], v63 offset0:156 offset1:189
	v_cvt_i32_f32_sdwa v51, v51 dst_sel:BYTE_3 dst_unused:UNUSED_PAD src0_sel:DWORD
	v_perm_b32 v64, v57, v56, s21
	ds_read2_b32 v[56:57], v63 offset0:222 offset1:255
	v_and_b32_e32 v50, 0xff0000, v50
	v_or3_b32 v50, v64, v50, v51
	s_waitcnt lgkmcnt(1)
	v_cvt_i32_f32_e32 v51, v55
	v_cvt_i32_f32_e32 v54, v54
	s_waitcnt lgkmcnt(0)
	v_cvt_i32_f32_sdwa v55, v56 dst_sel:WORD_1 dst_unused:UNUSED_PAD src0_sel:DWORD
	v_cvt_i32_f32_sdwa v56, v57 dst_sel:BYTE_3 dst_unused:UNUSED_PAD src0_sel:DWORD
	v_lshlrev_b32_e32 v51, 8, v51
	v_perm_b32 v51, v51, v54, s21
	v_and_b32_e32 v54, 0xff0000, v55
	v_or3_b32 v51, v51, v54, v56
	v_or_b32_e32 v54, s68, v17
	v_ashrrev_i32_e32 v55, 31, v54
	v_lshlrev_b64 v[54:55], 10, v[54:55]
	v_lshl_add_u64 v[56:57], v[6:7], 0, v[54:55]
	global_store_dwordx4 v[56:57], v[48:51], off sc1
	s_nop 1
	s_waitcnt lgkmcnt(0)
	v_rndne_f32_e32 v12, v12
	v_rndne_f32_e32 v5, v5
	ds_write2_b32 v14, v12, v5 offset1:66
	v_mul_f32_e32 v5, v24, v74
	v_mul_f32_e32 v12, v22, v74
	v_rndne_f32_e32 v5, v5
	v_rndne_f32_e32 v12, v12
	ds_write2_b32 v14, v5, v12 offset0:132 offset1:198
	v_mul_f32_e32 v5, v20, v74
	v_mul_f32_e32 v12, v19, v74
	v_rndne_f32_e32 v5, v5
	v_rndne_f32_e32 v12, v12
	ds_write2_b32 v75, v5, v12 offset0:8 offset1:74
	v_mul_f32_e32 v5, v13, v74
	v_mul_f32_e32 v12, v28, v74
	v_rndne_f32_e32 v5, v5
	v_rndne_f32_e32 v12, v12
	ds_write2_b32 v75, v5, v12 offset0:140 offset1:206
	v_mul_f32_e32 v5, v26, v74
	v_mul_f32_e32 v12, v25, v74
	v_rndne_f32_e32 v5, v5
	v_rndne_f32_e32 v12, v12
	ds_write2_b32 v61, v5, v12 offset0:16 offset1:82
	v_mul_f32_e32 v5, v23, v74
	v_mul_f32_e32 v12, v21, v74
	v_rndne_f32_e32 v5, v5
	v_rndne_f32_e32 v12, v12
	ds_write2_b32 v61, v5, v12 offset0:148 offset1:214
	v_mul_f32_e32 v5, v34, v74
	v_mul_f32_e32 v12, v32, v74
	v_rndne_f32_e32 v5, v5
	v_rndne_f32_e32 v12, v12
	ds_write2_b32 v76, v5, v12 offset0:24 offset1:90
	v_mul_f32_e32 v5, v30, v74
	v_mul_f32_e32 v12, v29, v74
	v_rndne_f32_e32 v5, v5
	v_rndne_f32_e32 v12, v12
	ds_write2_b32 v76, v5, v12 offset0:156 offset1:222
	v_mul_f32_e32 v5, v27, v74
	v_mul_f32_e32 v12, v38, v74
	v_rndne_f32_e32 v5, v5
	v_rndne_f32_e32 v12, v12
	ds_write2_b32 v59, v5, v12 offset0:32 offset1:98
	v_mul_f32_e32 v5, v36, v74
	v_mul_f32_e32 v12, v35, v74
	v_rndne_f32_e32 v5, v5
	v_rndne_f32_e32 v12, v12
	ds_write2_b32 v59, v5, v12 offset0:164 offset1:230
	v_mul_f32_e32 v5, v33, v74
	v_mul_f32_e32 v12, v31, v74
	v_rndne_f32_e32 v5, v5
	v_rndne_f32_e32 v12, v12
	ds_write2_b32 v62, v5, v12 offset0:40 offset1:106
	v_mul_f32_e32 v5, v44, v74
	v_mul_f32_e32 v12, v42, v74
	v_rndne_f32_e32 v5, v5
	v_rndne_f32_e32 v12, v12
	ds_write2_b32 v62, v5, v12 offset0:172 offset1:238
	v_mul_f32_e32 v5, v40, v74
	v_mul_f32_e32 v12, v39, v74
	v_rndne_f32_e32 v5, v5
	v_rndne_f32_e32 v12, v12
	ds_write2_b32 v58, v5, v12 offset0:48 offset1:114
	v_mul_f32_e32 v5, v37, v74
	v_mul_f32_e32 v12, v47, v74
	v_rndne_f32_e32 v5, v5
	v_rndne_f32_e32 v12, v12
	ds_write2_b32 v58, v5, v12 offset0:180 offset1:246
	v_mul_f32_e32 v5, v46, v74
	v_mul_f32_e32 v12, v45, v74
	v_rndne_f32_e32 v5, v5
	v_rndne_f32_e32 v12, v12
	ds_write2_b32 v60, v5, v12 offset0:56 offset1:122
	v_mul_f32_e32 v5, v43, v74
	v_mul_f32_e32 v12, v41, v74
	v_rndne_f32_e32 v5, v5
	v_rndne_f32_e32 v12, v12
	ds_write2_b32 v60, v5, v12 offset0:188 offset1:254
	s_waitcnt lgkmcnt(0)
	ds_read2_b32 v[12:13], v1 offset1:33
	ds_read2_b32 v[20:21], v1 offset0:66 offset1:99
	ds_read2_b32 v[22:23], v63 offset0:8 offset1:41
	s_mov_b64 s[68:69], 0xa00040
	v_lshl_add_u64 v[8:9], v[8:9], 0, s[68:69]
	s_waitcnt lgkmcnt(2)
	v_cvt_i32_f32_e32 v5, v13
	v_cvt_i32_f32_e32 v19, v12
	ds_read2_b32 v[12:13], v1 offset0:132 offset1:165
	s_waitcnt lgkmcnt(2)
	v_cvt_i32_f32_sdwa v20, v20 dst_sel:WORD_1 dst_unused:UNUSED_PAD src0_sel:DWORD
	v_lshlrev_b32_e32 v5, 8, v5
	v_perm_b32 v5, v5, v19, s21
	s_waitcnt lgkmcnt(1)
	v_cvt_i32_f32_e32 v23, v23
	v_and_b32_e32 v19, 0xff0000, v20
	v_cvt_i32_f32_sdwa v20, v21 dst_sel:BYTE_3 dst_unused:UNUSED_PAD src0_sel:DWORD
	s_waitcnt lgkmcnt(0)
	v_cvt_i32_f32_e32 v21, v12
	v_cvt_i32_f32_e32 v24, v13
	ds_read2_b32 v[12:13], v1 offset0:198 offset1:231
	v_or3_b32 v20, v5, v19, v20
	s_cmp_gt_i32 s19, 47
	v_lshlrev_b32_e32 v5, 8, v24
	v_perm_b32 v5, v5, v21, s21
	s_waitcnt lgkmcnt(0)
	v_cvt_i32_f32_sdwa v19, v12 dst_sel:WORD_1 dst_unused:UNUSED_PAD src0_sel:DWORD
	v_cvt_i32_f32_sdwa v21, v13 dst_sel:BYTE_3 dst_unused:UNUSED_PAD src0_sel:DWORD
	ds_read2_b32 v[12:13], v63 offset0:74 offset1:107
	ds_read2_b32 v[24:25], v63 offset0:206 offset1:239
	v_and_b32_e32 v19, 0xff0000, v19
	v_or3_b32 v21, v5, v19, v21
	v_cvt_i32_f32_e32 v5, v22
	v_lshlrev_b32_e32 v19, 8, v23
	s_waitcnt lgkmcnt(1)
	v_cvt_i32_f32_sdwa v22, v12 dst_sel:WORD_1 dst_unused:UNUSED_PAD src0_sel:DWORD
	v_cvt_i32_f32_sdwa v23, v13 dst_sel:BYTE_3 dst_unused:UNUSED_PAD src0_sel:DWORD
	ds_read2_b32 v[12:13], v63 offset0:140 offset1:173
	v_perm_b32 v5, v19, v5, s21
	v_and_b32_e32 v19, 0xff0000, v22
	v_or3_b32 v22, v5, v19, v23
	s_waitcnt lgkmcnt(1)
	v_cvt_i32_f32_sdwa v19, v25 dst_sel:BYTE_3 dst_unused:UNUSED_PAD src0_sel:DWORD
	s_waitcnt lgkmcnt(0)
	v_cvt_i32_f32_e32 v5, v13
	v_cvt_i32_f32_e32 v12, v12
	v_cvt_i32_f32_sdwa v13, v24 dst_sel:WORD_1 dst_unused:UNUSED_PAD src0_sel:DWORD
	s_mov_b64 s[68:69], -1
	v_lshlrev_b32_e32 v5, 8, v5
	v_perm_b32 v5, v5, v12, s21
	v_and_b32_e32 v12, 0xff0000, v13
	v_or3_b32 v23, v5, v12, v19
	v_lshl_add_u64 v[12:13], v[8:9], 0, v[52:53]
	global_store_dwordx4 v[12:13], v[20:23], off sc1
	s_nop 1
	ds_read2_b32 v[12:13], v1 offset0:16 offset1:49
	ds_read2_b32 v[20:21], v1 offset0:82 offset1:115
	ds_read2_b32 v[22:23], v63 offset0:24 offset1:57
	s_waitcnt lgkmcnt(2)
	v_cvt_i32_f32_e32 v5, v13
	v_cvt_i32_f32_e32 v19, v12
	ds_read2_b32 v[12:13], v1 offset0:148 offset1:181
	s_waitcnt lgkmcnt(2)
	v_cvt_i32_f32_sdwa v20, v20 dst_sel:WORD_1 dst_unused:UNUSED_PAD src0_sel:DWORD
	v_lshlrev_b32_e32 v5, 8, v5
	v_perm_b32 v5, v5, v19, s21
	s_waitcnt lgkmcnt(1)
	v_cvt_i32_f32_e32 v23, v23
	v_and_b32_e32 v19, 0xff0000, v20
	v_cvt_i32_f32_sdwa v20, v21 dst_sel:BYTE_3 dst_unused:UNUSED_PAD src0_sel:DWORD
	s_waitcnt lgkmcnt(0)
	v_cvt_i32_f32_e32 v21, v12
	v_cvt_i32_f32_e32 v24, v13
	ds_read2_b32 v[12:13], v1 offset0:214 offset1:247
	v_or3_b32 v20, v5, v19, v20
	v_lshlrev_b32_e32 v5, 8, v24
	v_perm_b32 v5, v5, v21, s21
	s_waitcnt lgkmcnt(0)
	v_cvt_i32_f32_sdwa v19, v12 dst_sel:WORD_1 dst_unused:UNUSED_PAD src0_sel:DWORD
	v_cvt_i32_f32_sdwa v21, v13 dst_sel:BYTE_3 dst_unused:UNUSED_PAD src0_sel:DWORD
	ds_read2_b32 v[12:13], v63 offset0:90 offset1:123
	ds_read2_b32 v[24:25], v63 offset0:222 offset1:255
	v_and_b32_e32 v19, 0xff0000, v19
	v_or3_b32 v21, v5, v19, v21
	v_cvt_i32_f32_e32 v5, v22
	v_lshlrev_b32_e32 v19, 8, v23
	s_waitcnt lgkmcnt(1)
	v_cvt_i32_f32_sdwa v22, v12 dst_sel:WORD_1 dst_unused:UNUSED_PAD src0_sel:DWORD
	v_cvt_i32_f32_sdwa v23, v13 dst_sel:BYTE_3 dst_unused:UNUSED_PAD src0_sel:DWORD
	ds_read2_b32 v[12:13], v63 offset0:156 offset1:189
	v_perm_b32 v5, v19, v5, s21
	v_and_b32_e32 v19, 0xff0000, v22
	v_or3_b32 v22, v5, v19, v23
	s_waitcnt lgkmcnt(1)
	v_cvt_i32_f32_sdwa v19, v25 dst_sel:BYTE_3 dst_unused:UNUSED_PAD src0_sel:DWORD
	s_waitcnt lgkmcnt(0)
	v_cvt_i32_f32_e32 v5, v13
	v_cvt_i32_f32_e32 v12, v12
	v_cvt_i32_f32_sdwa v13, v24 dst_sel:WORD_1 dst_unused:UNUSED_PAD src0_sel:DWORD
	v_lshlrev_b32_e32 v5, 8, v5
	v_perm_b32 v5, v5, v12, s21
	v_and_b32_e32 v12, 0xff0000, v13
	v_or3_b32 v23, v5, v12, v19
	v_lshl_add_u64 v[12:13], v[8:9], 0, v[54:55]
	global_store_dwordx4 v[12:13], v[20:23], off sc1
	s_nop 1
	s_waitcnt lgkmcnt(0)
	s_barrier
	s_cbranch_scc0 .LBB0_54
	s_lshl_b32 s21, s33, 3
	v_readlane_b32 s23, v249, 0
	s_add_i32 s21, s23, s21
	s_addk_i32 s21, 0xfe80
	s_cmpk_gt_i32 s21, 0x1ff
	s_cbranch_scc1 .LBB0_53
	s_ashr_i32 s23, s21, 31
	s_lshr_b32 s23, s23, 27
	s_add_i32 s23, s21, s23
	s_load_dwordx2 s[70:71], s[16:17], 0x20
	s_and_b32 s33, s23, 0x7ffffe0
	s_sub_i32 s21, s21, s33
	s_lshl_b32 s23, s23, 1
	s_lshl_b32 vcc_lo, s21, 5
	s_and_b32 s68, s23, 0xffffffc0
	s_ashr_i32 vcc_hi, vcc_lo, 31
	v_or_b32_e32 v12, s68, v11
	s_mov_b32 s21, s72
	s_mov_b32 s23, s73
	s_lshl_b64 s[72:73], vcc, 2
	s_waitcnt lgkmcnt(0)
	s_add_u32 s70, s70, s72
	v_or_b32_e32 v24, 2, v12
	v_or_b32_e32 v26, 4, v12
	v_or_b32_e32 v28, 6, v12
	v_or_b32_e32 v30, 8, v12
	v_or_b32_e32 v32, 10, v12
	v_or_b32_e32 v34, 12, v12
	v_or_b32_e32 v36, 14, v12
	s_addc_u32 s71, s71, s73
	v_mov_b32_e32 v11, 0
	v_ashrrev_i32_e32 v13, 31, v12
	v_ashrrev_i32_e32 v25, 31, v24
	v_ashrrev_i32_e32 v27, 31, v26
	v_ashrrev_i32_e32 v29, 31, v28
	v_ashrrev_i32_e32 v31, 31, v30
	v_ashrrev_i32_e32 v33, 31, v32
	v_ashrrev_i32_e32 v35, 31, v34
	v_ashrrev_i32_e32 v37, 31, v36
	v_lshl_add_u64 v[20:21], s[70:71], 0, v[10:11]
	v_lshlrev_b64 v[22:23], 12, v[12:13]
	v_lshlrev_b64 v[24:25], 12, v[24:25]
	v_lshlrev_b64 v[26:27], 12, v[26:27]
	v_lshlrev_b64 v[28:29], 12, v[28:29]
	v_lshlrev_b64 v[30:31], 12, v[30:31]
	v_lshlrev_b64 v[32:33], 12, v[32:33]
	v_lshlrev_b64 v[34:35], 12, v[34:35]
	v_lshlrev_b64 v[36:37], 12, v[36:37]
	v_lshl_add_u64 v[22:23], v[20:21], 0, v[22:23]
	v_lshl_add_u64 v[24:25], v[20:21], 0, v[24:25]
	v_lshl_add_u64 v[26:27], v[20:21], 0, v[26:27]
	v_lshl_add_u64 v[28:29], v[20:21], 0, v[28:29]
	v_lshl_add_u64 v[30:31], v[20:21], 0, v[30:31]
	v_lshl_add_u64 v[32:33], v[20:21], 0, v[32:33]
	v_lshl_add_u64 v[34:35], v[20:21], 0, v[34:35]
	v_lshl_add_u64 v[36:37], v[20:21], 0, v[36:37]
	global_load_dword v5, v[22:23], off sc1 nt
	global_load_dword v10, v[24:25], off sc1 nt
	global_load_dword v19, v[26:27], off sc1 nt
	global_load_dword v38, v[28:29], off sc1 nt
	global_load_dword v39, v[30:31], off sc1 nt
	global_load_dword v40, v[32:33], off sc1 nt
	global_load_dword v41, v[34:35], off sc1 nt
	global_load_dword v42, v[36:37], off sc1 nt
	v_or_b32_e32 v22, 16, v12
	v_or_b32_e32 v24, 18, v12
	v_or_b32_e32 v26, 20, v12
	v_or_b32_e32 v28, 22, v12
	v_or_b32_e32 v30, 24, v12
	v_or_b32_e32 v32, 26, v12
	v_or_b32_e32 v34, 28, v12
	v_or_b32_e32 v36, 30, v12
	v_ashrrev_i32_e32 v23, 31, v22
	v_ashrrev_i32_e32 v25, 31, v24
	v_ashrrev_i32_e32 v27, 31, v26
	v_ashrrev_i32_e32 v29, 31, v28
	v_ashrrev_i32_e32 v31, 31, v30
	v_ashrrev_i32_e32 v33, 31, v32
	v_ashrrev_i32_e32 v35, 31, v34
	v_ashrrev_i32_e32 v37, 31, v36
	v_lshlrev_b64 v[22:23], 12, v[22:23]
	v_lshlrev_b64 v[24:25], 12, v[24:25]
	v_lshlrev_b64 v[26:27], 12, v[26:27]
	v_lshlrev_b64 v[28:29], 12, v[28:29]
	v_lshlrev_b64 v[30:31], 12, v[30:31]
	v_lshlrev_b64 v[32:33], 12, v[32:33]
	v_lshlrev_b64 v[34:35], 12, v[34:35]
	v_lshlrev_b64 v[36:37], 12, v[36:37]
	v_lshl_add_u64 v[22:23], v[20:21], 0, v[22:23]
	v_lshl_add_u64 v[24:25], v[20:21], 0, v[24:25]
	v_lshl_add_u64 v[26:27], v[20:21], 0, v[26:27]
	v_lshl_add_u64 v[28:29], v[20:21], 0, v[28:29]
	v_lshl_add_u64 v[30:31], v[20:21], 0, v[30:31]
	v_lshl_add_u64 v[32:33], v[20:21], 0, v[32:33]
	v_lshl_add_u64 v[34:35], v[20:21], 0, v[34:35]
	v_lshl_add_u64 v[36:37], v[20:21], 0, v[36:37]
	global_load_dword v43, v[22:23], off sc1 nt
	global_load_dword v44, v[24:25], off sc1 nt
	global_load_dword v45, v[26:27], off sc1 nt
	global_load_dword v46, v[28:29], off sc1 nt
	global_load_dword v47, v[30:31], off sc1 nt
	global_load_dword v48, v[32:33], off sc1 nt
	global_load_dword v49, v[34:35], off sc1 nt
	global_load_dword v50, v[36:37], off sc1 nt
	v_or_b32_e32 v22, 32, v12
	v_or_b32_e32 v24, 34, v12
	v_or_b32_e32 v26, 36, v12
	v_or_b32_e32 v28, 38, v12
	v_or_b32_e32 v30, 40, v12
	v_or_b32_e32 v32, 42, v12
	v_or_b32_e32 v34, 44, v12
	v_or_b32_e32 v36, 46, v12
	v_ashrrev_i32_e32 v23, 31, v22
	v_ashrrev_i32_e32 v25, 31, v24
	v_ashrrev_i32_e32 v27, 31, v26
	v_ashrrev_i32_e32 v29, 31, v28
	v_ashrrev_i32_e32 v31, 31, v30
	v_ashrrev_i32_e32 v33, 31, v32
	v_ashrrev_i32_e32 v35, 31, v34
	v_ashrrev_i32_e32 v37, 31, v36
	v_lshlrev_b64 v[22:23], 12, v[22:23]
	v_lshlrev_b64 v[24:25], 12, v[24:25]
	v_lshlrev_b64 v[26:27], 12, v[26:27]
	v_lshlrev_b64 v[28:29], 12, v[28:29]
	v_lshlrev_b64 v[30:31], 12, v[30:31]
	v_lshlrev_b64 v[32:33], 12, v[32:33]
	v_lshlrev_b64 v[34:35], 12, v[34:35]
	v_lshlrev_b64 v[36:37], 12, v[36:37]
	v_lshl_add_u64 v[22:23], v[20:21], 0, v[22:23]
	v_lshl_add_u64 v[24:25], v[20:21], 0, v[24:25]
	v_lshl_add_u64 v[26:27], v[20:21], 0, v[26:27]
	v_lshl_add_u64 v[28:29], v[20:21], 0, v[28:29]
	v_lshl_add_u64 v[30:31], v[20:21], 0, v[30:31]
	v_lshl_add_u64 v[32:33], v[20:21], 0, v[32:33]
	v_lshl_add_u64 v[34:35], v[20:21], 0, v[34:35]
	v_lshl_add_u64 v[36:37], v[20:21], 0, v[36:37]
	global_load_dword v51, v[22:23], off sc1 nt
	global_load_dword v52, v[24:25], off sc1 nt
	global_load_dword v53, v[26:27], off sc1 nt
	global_load_dword v54, v[28:29], off sc1 nt
	global_load_dword v55, v[30:31], off sc1 nt
	global_load_dword v56, v[32:33], off sc1 nt
	global_load_dword v57, v[34:35], off sc1 nt
	s_nop 0
	global_load_dword v36, v[36:37], off sc1 nt
	v_or_b32_e32 v22, 48, v12
	v_or_b32_e32 v24, 50, v12
	v_or_b32_e32 v26, 52, v12
	v_or_b32_e32 v28, 54, v12
	v_or_b32_e32 v30, 56, v12
	v_or_b32_e32 v32, 58, v12
	v_or_b32_e32 v34, 60, v12
	v_or_b32_e32 v12, 62, v12
	v_ashrrev_i32_e32 v23, 31, v22
	v_ashrrev_i32_e32 v25, 31, v24
	v_ashrrev_i32_e32 v27, 31, v26
	v_ashrrev_i32_e32 v13, 31, v12
	v_lshlrev_b64 v[22:23], 12, v[22:23]
	v_lshlrev_b64 v[24:25], 12, v[24:25]
	v_lshlrev_b64 v[26:27], 12, v[26:27]
	v_ashrrev_i32_e32 v29, 31, v28
	v_ashrrev_i32_e32 v31, 31, v30
	v_ashrrev_i32_e32 v33, 31, v32
	v_ashrrev_i32_e32 v35, 31, v34
	v_lshlrev_b64 v[12:13], 12, v[12:13]
	v_lshl_add_u64 v[22:23], v[20:21], 0, v[22:23]
	v_lshl_add_u64 v[24:25], v[20:21], 0, v[24:25]
	v_lshl_add_u64 v[26:27], v[20:21], 0, v[26:27]
	v_lshlrev_b64 v[28:29], 12, v[28:29]
	v_lshlrev_b64 v[30:31], 12, v[30:31]
	v_lshlrev_b64 v[32:33], 12, v[32:33]
	v_lshlrev_b64 v[34:35], 12, v[34:35]
	v_lshl_add_u64 v[12:13], v[20:21], 0, v[12:13]
	v_lshl_add_u64 v[28:29], v[20:21], 0, v[28:29]
	v_lshl_add_u64 v[30:31], v[20:21], 0, v[30:31]
	v_lshl_add_u64 v[32:33], v[20:21], 0, v[32:33]
	v_lshl_add_u64 v[34:35], v[20:21], 0, v[34:35]
	global_load_dword v20, v[22:23], off sc1 nt
	global_load_dword v21, v[24:25], off sc1 nt
	s_nop 0
	global_load_dword v22, v[26:27], off sc1 nt
	global_load_dword v23, v[28:29], off sc1 nt
	global_load_dword v24, v[30:31], off sc1 nt
	global_load_dword v25, v[32:33], off sc1 nt
	s_nop 0
	global_load_dword v26, v[34:35], off sc1 nt
	s_nop 0
	global_load_dword v12, v[12:13], off sc1 nt
	s_waitcnt vmcnt(30)
	ds_write2_b32 v14, v5, v10 offset1:66
	s_waitcnt vmcnt(28)
	ds_write2_b32 v14, v19, v38 offset0:132 offset1:198
	v_add_u32_e32 v5, 0x400, v14
	s_waitcnt vmcnt(26)
	ds_write2_b32 v5, v39, v40 offset0:8 offset1:74
	s_waitcnt vmcnt(24)
	ds_write2_b32 v5, v41, v42 offset0:140 offset1:206
	v_add_u32_e32 v5, 0x800, v14
	s_waitcnt vmcnt(22)
	ds_write2_b32 v5, v43, v44 offset0:16 offset1:82
	s_waitcnt vmcnt(20)
	ds_write2_b32 v5, v45, v46 offset0:148 offset1:214
	v_add_u32_e32 v5, 0xc00, v14
	s_waitcnt vmcnt(18)
	ds_write2_b32 v5, v47, v48 offset0:24 offset1:90
	s_waitcnt vmcnt(16)
	ds_write2_b32 v5, v49, v50 offset0:156 offset1:222
	v_add_u32_e32 v5, 0x1000, v14
	s_waitcnt vmcnt(14)
	ds_write2_b32 v5, v51, v52 offset0:32 offset1:98
	s_waitcnt vmcnt(12)
	ds_write2_b32 v5, v53, v54 offset0:164 offset1:230
	v_add_u32_e32 v5, 0x1400, v14
	s_waitcnt vmcnt(10)
	ds_write2_b32 v5, v55, v56 offset0:40 offset1:106
	s_waitcnt vmcnt(8)
	ds_write2_b32 v5, v57, v36 offset0:172 offset1:238
	v_add_u32_e32 v5, 0x1800, v14
	s_waitcnt vmcnt(6)
	ds_write2_b32 v5, v20, v21 offset0:48 offset1:114
	s_waitcnt vmcnt(4)
	ds_write2_b32 v5, v22, v23 offset0:180 offset1:246
	v_add_u32_e32 v5, 0x1c00, v14
	v_lshlrev_b32_e32 v10, 3, v108
	s_waitcnt vmcnt(2)
	ds_write2_b32 v5, v24, v25 offset0:56 offset1:122
	s_waitcnt vmcnt(0)
	ds_write2_b32 v5, v26, v12 offset0:188 offset1:254
	v_lshrrev_b32_e32 v5, 3, v108
	v_and_b32_e32 v10, 56, v10
	s_mov_b32 s72, s21
	s_waitcnt lgkmcnt(0)
	v_mul_u32_u24_e32 v12, 0x84, v10
	v_lshlrev_b32_e32 v13, 2, v5
	v_readlane_b32 s21, v249, 5
	s_ashr_i32 s69, s68, 31
	s_lshl_b64 s[68:69], s[68:69], 1
	v_add3_u32 v19, s21, v12, v13
	ds_read2_b32 v[12:13], v19 offset1:33
	s_add_u32 s68, s10, s68
	s_addc_u32 s69, s11, s69
	v_lshlrev_b32_e32 v10, 1, v10
	ds_read2_b32 v[22:23], v19 offset0:66 offset1:99
	v_lshl_add_u64 v[10:11], s[68:69], 0, v[10:11]
	s_mov_b64 s[68:69], 0x800000
	v_lshl_add_u64 v[20:21], v[10:11], 0, s[68:69]
	s_waitcnt lgkmcnt(1)
	v_bfe_u32 v10, v12, 16, 1
	s_movk_i32 s21, 0x7fff
	v_bfe_u32 v11, v13, 16, 1
	v_add3_u32 v10, v12, v10, s21
	v_add3_u32 v11, v13, v11, s21
	ds_read2_b32 v[12:13], v19 offset0:132 offset1:165
	s_mov_b32 s73, s23
	v_lshrrev_b32_e32 v10, 16, v10
	s_mov_b32 s23, 0xffff0000
	v_and_or_b32 v10, v11, s23, v10
	s_waitcnt lgkmcnt(1)
	v_bfe_u32 v11, v22, 16, 1
	v_add3_u32 v11, v22, v11, s21
	v_bfe_u32 v22, v23, 16, 1
	v_lshrrev_b32_e32 v11, 16, v11
	v_add3_u32 v22, v23, v22, s21
	v_and_or_b32 v11, v22, s23, v11
	s_waitcnt lgkmcnt(0)
	v_bfe_u32 v22, v12, 16, 1
	v_add3_u32 v12, v12, v22, s21
	ds_read2_b32 v[22:23], v19 offset0:198 offset1:231
	v_bfe_u32 v24, v13, 16, 1
	v_lshrrev_b32_e32 v12, 16, v12
	v_add3_u32 v13, v13, v24, s21
	v_and_or_b32 v12, v13, s23, v12
	s_waitcnt lgkmcnt(0)
	v_bfe_u32 v13, v22, 16, 1
	v_add3_u32 v13, v22, v13, s21
	v_bfe_u32 v22, v23, 16, 1
	v_lshrrev_b32_e32 v13, 16, v13
	v_add3_u32 v22, v23, v22, s21
	v_and_or_b32 v13, v22, s23, v13
	v_or_b32_e32 v22, vcc_lo, v5
	v_ashrrev_i32_e32 v23, 31, v22
	v_lshlrev_b64 v[24:25], 11, v[22:23]
	v_lshl_add_u64 v[24:25], v[20:21], 0, v[24:25]
	global_store_dwordx4 v[24:25], v[10:13], off sc1
	s_nop 1
	ds_read2_b32 v[10:11], v19 offset0:8 offset1:41
	ds_read2_b32 v[12:13], v19 offset0:74 offset1:107
	ds_read2_b32 v[24:25], v19 offset0:140 offset1:173
	ds_read2_b32 v[26:27], v19 offset0:206 offset1:239
	s_mov_b32 s33, s19
	s_waitcnt lgkmcnt(3)
	v_bfe_u32 v5, v10, 16, 1
	v_add3_u32 v5, v10, v5, s21
	v_bfe_u32 v10, v11, 16, 1
	v_lshrrev_b32_e32 v5, 16, v5
	v_add3_u32 v10, v11, v10, s21
	v_and_or_b32 v10, v10, s23, v5
	s_waitcnt lgkmcnt(2)
	v_bfe_u32 v5, v12, 16, 1
	v_add3_u32 v5, v12, v5, s21
	v_bfe_u32 v11, v13, 16, 1
	v_lshrrev_b32_e32 v5, 16, v5
	v_add3_u32 v11, v13, v11, s21
	v_and_or_b32 v11, v11, s23, v5
	s_waitcnt lgkmcnt(1)
	v_bfe_u32 v5, v24, 16, 1
	v_add3_u32 v5, v24, v5, s21
	v_bfe_u32 v12, v25, 16, 1
	v_lshrrev_b32_e32 v5, 16, v5
	v_add3_u32 v12, v25, v12, s21
	v_and_or_b32 v12, v12, s23, v5
	s_waitcnt lgkmcnt(0)
	v_bfe_u32 v5, v26, 16, 1
	v_or_b32_e32 v24, 8, v22
	v_add3_u32 v5, v26, v5, s21
	v_bfe_u32 v13, v27, 16, 1
	v_ashrrev_i32_e32 v25, 31, v24
	v_lshrrev_b32_e32 v5, 16, v5
	v_add3_u32 v13, v27, v13, s21
	v_lshlrev_b64 v[24:25], 11, v[24:25]
	v_and_or_b32 v13, v13, s23, v5
	v_lshl_add_u64 v[24:25], v[20:21], 0, v[24:25]
	global_store_dwordx4 v[24:25], v[10:13], off sc1
	s_nop 1
	ds_read2_b32 v[10:11], v19 offset0:16 offset1:49
	ds_read2_b32 v[12:13], v19 offset0:82 offset1:115
	ds_read2_b32 v[24:25], v19 offset0:148 offset1:181
	ds_read2_b32 v[26:27], v19 offset0:214 offset1:247
	s_waitcnt lgkmcnt(3)
	v_bfe_u32 v5, v10, 16, 1
	v_add3_u32 v5, v10, v5, s21
	v_bfe_u32 v10, v11, 16, 1
	v_lshrrev_b32_e32 v5, 16, v5
	v_add3_u32 v10, v11, v10, s21
	v_and_or_b32 v10, v10, s23, v5
	s_waitcnt lgkmcnt(2)
	v_bfe_u32 v5, v12, 16, 1
	v_add3_u32 v5, v12, v5, s21
	v_bfe_u32 v11, v13, 16, 1
	v_lshrrev_b32_e32 v5, 16, v5
	v_add3_u32 v11, v13, v11, s21
	v_and_or_b32 v11, v11, s23, v5
	s_waitcnt lgkmcnt(1)
	v_bfe_u32 v5, v24, 16, 1
	v_add3_u32 v5, v24, v5, s21
	v_bfe_u32 v12, v25, 16, 1
	v_lshrrev_b32_e32 v5, 16, v5
	v_add3_u32 v12, v25, v12, s21
	v_and_or_b32 v12, v12, s23, v5
	s_waitcnt lgkmcnt(0)
	v_bfe_u32 v5, v26, 16, 1
	v_or_b32_e32 v24, 16, v22
	v_add3_u32 v5, v26, v5, s21
	v_bfe_u32 v13, v27, 16, 1
	v_ashrrev_i32_e32 v25, 31, v24
	v_lshrrev_b32_e32 v5, 16, v5
	v_add3_u32 v13, v27, v13, s21
	v_lshlrev_b64 v[24:25], 11, v[24:25]
	v_and_or_b32 v13, v13, s23, v5
	v_lshl_add_u64 v[24:25], v[20:21], 0, v[24:25]
	global_store_dwordx4 v[24:25], v[10:13], off sc1
	s_nop 1
	ds_read2_b32 v[10:11], v19 offset0:24 offset1:57
	ds_read2_b32 v[12:13], v19 offset0:90 offset1:123
	ds_read2_b32 v[24:25], v19 offset0:156 offset1:189
	ds_read2_b32 v[26:27], v19 offset0:222 offset1:255
	v_or_b32_e32 v22, 24, v22
	s_waitcnt lgkmcnt(3)
	v_bfe_u32 v5, v10, 16, 1
	v_add3_u32 v5, v10, v5, s21
	v_bfe_u32 v10, v11, 16, 1
	v_lshrrev_b32_e32 v5, 16, v5
	v_add3_u32 v10, v11, v10, s21
	v_and_or_b32 v10, v10, s23, v5
	s_waitcnt lgkmcnt(2)
	v_bfe_u32 v5, v12, 16, 1
	v_add3_u32 v5, v12, v5, s21
	v_bfe_u32 v11, v13, 16, 1
	v_lshrrev_b32_e32 v5, 16, v5
	v_add3_u32 v11, v13, v11, s21
	v_and_or_b32 v11, v11, s23, v5
	s_waitcnt lgkmcnt(1)
	v_bfe_u32 v5, v24, 16, 1
	v_add3_u32 v5, v24, v5, s21
	v_bfe_u32 v12, v25, 16, 1
	v_lshrrev_b32_e32 v5, 16, v5
	v_add3_u32 v12, v25, v12, s21
	v_and_or_b32 v12, v12, s23, v5
	s_waitcnt lgkmcnt(0)
	v_bfe_u32 v5, v26, 16, 1
	v_add3_u32 v5, v26, v5, s21
	v_bfe_u32 v13, v27, 16, 1
	v_ashrrev_i32_e32 v23, 31, v22
	v_lshrrev_b32_e32 v5, 16, v5
	v_add3_u32 v13, v27, v13, s21
	v_lshlrev_b64 v[22:23], 11, v[22:23]
	v_and_or_b32 v13, v13, s23, v5
	v_lshl_add_u64 v[20:21], v[20:21], 0, v[22:23]
	global_store_dwordx4 v[20:21], v[10:13], off sc1
	s_nop 1
	s_waitcnt lgkmcnt(0)

.LBB0_54:
	s_andn2_b64 vcc, exec, s[68:69]
	v_readlane_b32 s68, v249, 6
	v_readlane_b32 s69, v249, 7
	s_cbranch_vccnz .LBB0_64
	s_mov_b32 s21, s1
	s_mov_b32 s19, s0
	s_mov_b64 s[0:1], s[8:9]
	s_mov_b64 s[8:9], s[4:5]
	s_mov_b64 s[4:5], s[96:97]
	s_mov_b64 s[96:97], s[94:95]
	s_mov_b64 s[94:95], s[92:93]
	s_mov_b64 s[92:93], s[90:91]
	s_mov_b64 s[90:91], s[88:89]
	s_mov_b64 s[88:89], s[86:87]
	s_mov_b64 s[86:87], s[84:85]
	s_mov_b64 s[84:85], s[82:83]
	s_mov_b64 s[82:83], s[80:81]
	s_mov_b64 s[80:81], s[74:75]
	s_mov_b64 s[74:75], s[78:79]
	s_mov_b64 s[70:71], s[76:77]
	s_load_dwordx4 s[76:79], s[16:17], 0x30
	v_readlane_b32 s68, v249, 44
	v_readlane_b32 s69, v249, 45
	v_mov_b32_e32 v10, 1.0
	s_and_b64 vcc, exec, s[68:69]
	v_mov_b32_e32 v11, 1.0
	s_cbranch_vccnz .LBB0_57
	s_waitcnt lgkmcnt(0)
	v_lshl_add_u64 v[12:13], v[2:3], 2, s[76:77]
	global_load_dword v11, v[12:13], off sc1 nt
.LBB0_57:
	s_addk_i32 s22, 0x1000
	s_ashr_i32 s23, s22, 31
	s_lshl_b64 s[68:69], s[22:23], 2
	s_waitcnt lgkmcnt(0)
	s_add_u32 s68, s78, s68
	s_addc_u32 s69, s79, s69
	v_mov_b32_e32 v5, 0
	v_lshl_add_u64 v[4:5], s[68:69], 0, v[4:5]
	v_lshl_add_u64 v[12:13], s[70:71], 2, v[4:5]
	v_lshl_add_u64 v[28:29], s[86:87], 2, v[4:5]
	v_lshl_add_u64 v[20:21], s[74:75], 2, v[4:5]
	v_lshl_add_u64 v[22:23], s[80:81], 2, v[4:5]
	v_lshl_add_u64 v[24:25], s[82:83], 2, v[4:5]
	v_lshl_add_u64 v[26:27], s[84:85], 2, v[4:5]
	v_lshl_add_u64 v[30:31], s[88:89], 2, v[4:5]
	v_lshl_add_u64 v[32:33], s[90:91], 2, v[4:5]
	global_load_dword v43, v[12:13], off sc1 nt
	global_load_dword v44, v[20:21], off sc1 nt
	global_load_dword v49, v[22:23], off sc1 nt
	global_load_dword v46, v[24:25], off sc1 nt
	global_load_dword v47, v[26:27], off sc1 nt
	global_load_dword v48, v[28:29], off sc1 nt
	global_load_dword v51, v[30:31], off sc1 nt
	global_load_dword v52, v[32:33], off sc1 nt
	v_lshl_add_u64 v[28:29], s[0:1], 2, v[4:5]
	v_readlane_b32 s0, v249, 8
	v_readlane_b32 s1, v249, 9
	v_lshl_add_u64 v[12:13], s[92:93], 2, v[4:5]
	v_lshl_add_u64 v[20:21], s[94:95], 2, v[4:5]
	v_lshl_add_u64 v[30:31], s[0:1], 2, v[4:5]
	v_readlane_b32 s0, v249, 10
	v_readlane_b32 s1, v249, 11
	v_lshl_add_u64 v[22:23], s[96:97], 2, v[4:5]
	v_lshl_add_u64 v[24:25], s[4:5], 2, v[4:5]
	v_lshl_add_u64 v[32:33], s[0:1], 2, v[4:5]
	v_readlane_b32 s0, v249, 12
	v_readlane_b32 s1, v249, 13
	v_lshl_add_u64 v[26:27], s[8:9], 2, v[4:5]
	global_load_dword v56, v[12:13], off sc1 nt
	global_load_dword v57, v[20:21], off sc1 nt
	global_load_dword v58, v[22:23], off sc1 nt
	global_load_dword v60, v[24:25], off sc1 nt
	global_load_dword v61, v[26:27], off sc1 nt
	s_nop 0
	global_load_dword v12, v[28:29], off sc1 nt
	global_load_dword v53, v[30:31], off sc1 nt
	global_load_dword v55, v[32:33], off sc1 nt
	v_lshl_add_u64 v[20:21], s[0:1], 2, v[4:5]
	v_readlane_b32 s0, v249, 14
	v_readlane_b32 s1, v249, 15
	v_or_b32_e32 v80, 8, v15
	v_or_b32_e32 v79, 16, v15
	v_lshl_add_u64 v[22:23], s[0:1], 2, v[4:5]
	v_readlane_b32 s0, v249, 16
	v_readlane_b32 s1, v249, 17
	v_or_b32_e32 v78, 24, v15
	v_or_b32_e32 v77, 32, v15
	v_lshl_add_u64 v[24:25], s[0:1], 2, v[4:5]
	v_readlane_b32 s0, v249, 18
	v_readlane_b32 s1, v249, 19
	v_or_b32_e32 v76, 40, v15
	v_or_b32_e32 v67, 48, v15
	v_lshl_add_u64 v[26:27], s[0:1], 2, v[4:5]
	v_readlane_b32 s0, v249, 20
	v_readlane_b32 s1, v249, 21
	v_or_b32_e32 v13, 56, v15
	v_or_b32_e32 v19, 0x58, v15
	v_lshl_add_u64 v[28:29], s[0:1], 2, v[4:5]
	v_readlane_b32 s0, v249, 22
	v_readlane_b32 s1, v249, 23
	v_or_b32_e32 v38, 0xc0, v15
	v_or_b32_e32 v37, 0xc8, v15
	v_lshl_add_u64 v[30:31], s[0:1], 2, v[4:5]
	v_readlane_b32 s0, v249, 24
	v_readlane_b32 s1, v249, 25
	v_or_b32_e32 v36, 0xd0, v15
	v_or_b32_e32 v42, 0xe0, v15
	v_lshl_add_u64 v[32:33], s[0:1], 2, v[4:5]
	v_readlane_b32 s0, v249, 26
	v_readlane_b32 s1, v249, 27
	v_or_b32_e32 v41, 0xe8, v15
	v_or_b32_e32 v39, 0xf0, v15
	v_lshl_add_u64 v[34:35], s[0:1], 2, v[4:5]
	v_readlane_b32 s0, v249, 28
	v_readlane_b32 s1, v249, 29
	global_load_dword v66, v[20:21], off sc1 nt
	global_load_dword v68, v[22:23], off sc1 nt
	global_load_dword v63, v[24:25], off sc1 nt
	global_load_dword v64, v[26:27], off sc1 nt
	global_load_dword v69, v[28:29], off sc1 nt
	global_load_dword v70, v[30:31], off sc1 nt
	global_load_dword v71, v[32:33], off sc1 nt
	global_load_dword v62, v[34:35], off sc1 nt
	v_lshl_add_u64 v[20:21], s[0:1], 2, v[4:5]
	v_readlane_b32 s0, v249, 30
	v_readlane_b32 s1, v249, 31
	v_or_b32_e32 v40, 0xf8, v15
	s_nop 0
	v_lshl_add_u64 v[22:23], s[0:1], 2, v[4:5]
	v_readlane_b32 s0, v249, 32
	v_readlane_b32 s1, v249, 33
	s_nop 1
	v_lshl_add_u64 v[24:25], s[0:1], 2, v[4:5]
	v_readlane_b32 s0, v249, 34
	v_readlane_b32 s1, v249, 35
	s_nop 1
	v_lshl_add_u64 v[26:27], s[0:1], 2, v[4:5]
	v_readlane_b32 s0, v249, 36
	v_readlane_b32 s1, v249, 37
	s_nop 1
	v_lshl_add_u64 v[28:29], s[0:1], 2, v[4:5]
	v_readlane_b32 s0, v249, 38
	v_readlane_b32 s1, v249, 39
	s_nop 1
	v_lshl_add_u64 v[30:31], s[0:1], 2, v[4:5]
	v_readlane_b32 s0, v249, 40
	v_readlane_b32 s1, v249, 41
	s_nop 1
	v_lshl_add_u64 v[32:33], s[0:1], 2, v[4:5]
	v_readlane_b32 s0, v249, 42
	v_readlane_b32 s1, v249, 43
	s_nop 1
	v_lshl_add_u64 v[34:35], s[0:1], 2, v[4:5]
	global_load_dword v75, v[20:21], off sc1 nt
	global_load_dword v83, v[22:23], off sc1 nt
	global_load_dword v84, v[24:25], off sc1 nt
	global_load_dword v85, v[26:27], off sc1 nt
	global_load_dword v73, v[28:29], off sc1 nt
	global_load_dword v74, v[30:31], off sc1 nt
	global_load_dword v81, v[32:33], off sc1 nt
	global_load_dword v82, v[34:35], off sc1 nt
	v_readlane_b32 s0, v249, 44
	v_readlane_b32 s1, v249, 45
	v_or_b32_e32 v22, 64, v15
	v_or_b32_e32 v21, 0x48, v15
	v_or_b32_e32 v20, 0x50, v15
	v_or_b32_e32 v26, 0x60, v15
	v_or_b32_e32 v25, 0x68, v15
	v_or_b32_e32 v24, 0x70, v15
	v_or_b32_e32 v23, 0x78, v15
	v_or_b32_e32 v30, 0x80, v15
	v_or_b32_e32 v29, 0x88, v15
	v_or_b32_e32 v28, 0x90, v15
	v_or_b32_e32 v27, 0x98, v15
	v_or_b32_e32 v34, 0xa0, v15
	v_or_b32_e32 v33, 0xa8, v15
	v_or_b32_e32 v32, 0xb0, v15
	v_or_b32_e32 v31, 0xb8, v15
	v_or_b32_e32 v35, 0xd8, v15
	s_and_b64 vcc, exec, s[0:1]
	s_cbranch_vccnz .LBB0_59
	v_lshl_add_u64 v[2:3], v[2:3], 2, s[76:77]
	global_load_dword v10, v[2:3], off offset:256 sc1 nt
.LBB0_59:
	v_readlane_b32 s0, v249, 46
	v_readlane_b32 s1, v249, 47
	v_lshl_add_u64 v[98:99], s[12:13], 2, v[4:5]
	s_waitcnt vmcnt(32)
	ds_bpermute_b32 v45, v15, v11
	v_lshl_add_u64 v[2:3], s[0:1], 2, v[4:5]
	v_readlane_b32 s0, v249, 48
	v_readlane_b32 s1, v249, 49
	ds_bpermute_b32 v54, v79, v11
	ds_bpermute_b32 v50, v80, v11
	v_lshl_add_u64 v[86:87], s[0:1], 2, v[4:5]
	v_readlane_b32 s0, v249, 50
	v_readlane_b32 s1, v249, 51
	s_waitcnt vmcnt(31) lgkmcnt(2)
	v_mul_f32_e32 v45, v43, v45
	s_waitcnt vmcnt(29) lgkmcnt(1)
	v_mul_f32_e32 v43, v49, v54
	v_lshl_add_u64 v[88:89], s[0:1], 2, v[4:5]
	v_readlane_b32 s0, v249, 52
	v_readlane_b32 s1, v249, 53
	ds_bpermute_b32 v59, v13, v11
	s_waitcnt lgkmcnt(1)
	v_mul_f32_e32 v44, v44, v50
	v_lshl_add_u64 v[90:91], s[0:1], 2, v[4:5]
	v_readlane_b32 s0, v249, 54
	v_readlane_b32 s1, v249, 55
	s_waitcnt vmcnt(0)
	ds_bpermute_b32 v13, v13, v10
	v_lshl_add_u64 v[92:93], s[0:1], 2, v[4:5]
	v_readlane_b32 s0, v249, 56
	v_readlane_b32 s1, v249, 57
	s_nop 1
	v_lshl_add_u64 v[94:95], s[0:1], 2, v[4:5]
	v_readlane_b32 s0, v249, 58
	v_readlane_b32 s1, v249, 59
	s_nop 1
	v_lshl_add_u64 v[96:97], s[0:1], 2, v[4:5]
	global_load_dword v100, v[2:3], off sc1 nt
	global_load_dword v101, v[86:87], off sc1 nt
	global_load_dword v102, v[88:89], off sc1 nt
	global_load_dword v103, v[90:91], off sc1 nt
	global_load_dword v104, v[92:93], off sc1 nt
	global_load_dword v105, v[94:95], off sc1 nt
	global_load_dword v106, v[96:97], off sc1 nt
	global_load_dword v107, v[98:99], off sc1 nt
	v_lshl_add_u64 v[2:3], s[14:15], 2, v[4:5]
	v_lshl_add_u64 v[86:87], s[6:7], 2, v[4:5]
	v_lshl_add_u64 v[88:89], s[2:3], 2, v[4:5]
	v_lshl_add_u64 v[90:91], s[24:25], 2, v[4:5]
	v_lshl_add_u64 v[92:93], s[26:27], 2, v[4:5]
	v_lshl_add_u64 v[94:95], s[28:29], 2, v[4:5]
	v_lshl_add_u64 v[96:97], s[30:31], 2, v[4:5]
	v_lshl_add_u64 v[98:99], s[34:35], 2, v[4:5]
	global_load_dword v109, v[2:3], off sc1 nt
	global_load_dword v110, v[86:87], off sc1 nt
	global_load_dword v111, v[88:89], off sc1 nt
	global_load_dword v112, v[90:91], off sc1 nt
	global_load_dword v113, v[92:93], off sc1 nt
	global_load_dword v114, v[94:95], off sc1 nt
	global_load_dword v115, v[96:97], off sc1 nt
	global_load_dword v116, v[98:99], off sc1 nt
	v_lshl_add_u64 v[2:3], s[36:37], 2, v[4:5]
	v_lshl_add_u64 v[86:87], s[38:39], 2, v[4:5]
	v_lshl_add_u64 v[88:89], s[40:41], 2, v[4:5]
	v_lshl_add_u64 v[90:91], s[42:43], 2, v[4:5]
	v_lshl_add_u64 v[92:93], s[44:45], 2, v[4:5]
	v_lshl_add_u64 v[94:95], s[46:47], 2, v[4:5]
	v_lshl_add_u64 v[96:97], s[48:49], 2, v[4:5]
	v_lshl_add_u64 v[98:99], s[52:53], 2, v[4:5]
	global_load_dword v117, v[2:3], off sc1 nt
	global_load_dword v118, v[86:87], off sc1 nt
	global_load_dword v119, v[88:89], off sc1 nt
	global_load_dword v120, v[90:91], off sc1 nt
	global_load_dword v121, v[92:93], off sc1 nt
	global_load_dword v122, v[94:95], off sc1 nt
	global_load_dword v123, v[96:97], off sc1 nt
	global_load_dword v124, v[98:99], off sc1 nt
	v_lshl_add_u64 v[2:3], s[50:51], 2, v[4:5]
	v_lshl_add_u64 v[86:87], s[54:55], 2, v[4:5]
	v_lshl_add_u64 v[88:89], s[56:57], 2, v[4:5]
	v_lshl_add_u64 v[90:91], s[58:59], 2, v[4:5]
	v_lshl_add_u64 v[92:93], s[60:61], 2, v[4:5]
	v_lshl_add_u64 v[94:95], s[62:63], 2, v[4:5]
	v_lshl_add_u64 v[96:97], s[64:65], 2, v[4:5]
	v_lshl_add_u64 v[4:5], s[66:67], 2, v[4:5]
	global_load_dword v98, v[2:3], off sc1 nt
	global_load_dword v99, v[86:87], off sc1 nt
	global_load_dword v125, v[88:89], off sc1 nt
	global_load_dword v126, v[90:91], off sc1 nt
	global_load_dword v127, v[92:93], off sc1 nt
	global_load_dword v128, v[94:95], off sc1 nt
	global_load_dword v129, v[96:97], off sc1 nt
	global_load_dword v130, v[4:5], off sc1 nt
	ds_bpermute_b32 v2, v78, v11
	ds_bpermute_b32 v4, v76, v11
	ds_bpermute_b32 v3, v77, v11
	ds_bpermute_b32 v5, v67, v11
	ds_bpermute_b32 v76, v76, v10
	s_waitcnt lgkmcnt(4)
	v_mul_f32_e32 v54, v46, v2
	s_waitcnt lgkmcnt(3)
	v_mul_f32_e32 v49, v48, v4
	ds_bpermute_b32 v2, v22, v11
	ds_bpermute_b32 v4, v20, v11
	s_waitcnt lgkmcnt(4)
	v_mul_f32_e32 v50, v47, v3
	s_waitcnt lgkmcnt(3)
	v_mul_f32_e32 v47, v51, v5
	v_mul_f32_e32 v46, v52, v59
	ds_bpermute_b32 v3, v21, v11
	ds_bpermute_b32 v5, v19, v11
	s_waitcnt lgkmcnt(3)
	v_mul_f32_e32 v59, v56, v2
	s_waitcnt lgkmcnt(2)
	v_mul_f32_e32 v52, v58, v4
	ds_bpermute_b32 v2, v25, v11
	ds_bpermute_b32 v4, v23, v11
	s_waitcnt lgkmcnt(3)
	v_mul_f32_e32 v57, v57, v3
	s_waitcnt lgkmcnt(2)
	v_mul_f32_e32 v51, v60, v5
	ds_bpermute_b32 v3, v24, v11
	ds_bpermute_b32 v5, v30, v11
	ds_bpermute_b32 v56, v29, v11
	s_waitcnt lgkmcnt(4)
	v_mul_f32_e32 v65, v12, v2
	s_waitcnt lgkmcnt(3)
	v_mul_f32_e32 v58, v55, v4
	ds_bpermute_b32 v2, v28, v11
	ds_bpermute_b32 v4, v34, v11
	ds_bpermute_b32 v48, v26, v11
	s_waitcnt lgkmcnt(5)
	v_mul_f32_e32 v60, v53, v3
	s_waitcnt lgkmcnt(4)
	v_mul_f32_e32 v55, v66, v5
	s_waitcnt lgkmcnt(3)
	v_mul_f32_e32 v53, v68, v56
	ds_bpermute_b32 v3, v27, v11
	ds_bpermute_b32 v5, v33, v11
	s_waitcnt lgkmcnt(4)
	v_mul_f32_e32 v68, v63, v2
	s_waitcnt lgkmcnt(3)
	v_mul_f32_e32 v63, v69, v4
	ds_bpermute_b32 v2, v31, v11
	ds_bpermute_b32 v4, v37, v11
	s_waitcnt lgkmcnt(4)
	v_mul_f32_e32 v48, v61, v48
	ds_bpermute_b32 v12, v32, v11
	s_waitcnt lgkmcnt(4)
	v_mul_f32_e32 v66, v64, v3
	s_waitcnt lgkmcnt(3)
	v_mul_f32_e32 v61, v70, v5
	ds_bpermute_b32 v3, v38, v11
	ds_bpermute_b32 v5, v36, v11
	s_waitcnt lgkmcnt(4)
	v_mul_f32_e32 v72, v62, v2
	s_waitcnt lgkmcnt(3)
	v_mul_f32_e32 v69, v83, v4
	ds_bpermute_b32 v2, v42, v11
	ds_bpermute_b32 v4, v39, v11
	s_waitcnt lgkmcnt(4)
	v_mul_f32_e32 v56, v71, v12
	ds_bpermute_b32 v12, v35, v11
	s_waitcnt lgkmcnt(4)
	v_mul_f32_e32 v70, v75, v3
	s_waitcnt lgkmcnt(3)
	v_mul_f32_e32 v64, v84, v5
	ds_bpermute_b32 v3, v41, v11
	ds_bpermute_b32 v5, v40, v11
	ds_bpermute_b32 v11, v15, v10
	s_waitcnt lgkmcnt(5)
	v_mul_f32_e32 v75, v73, v2
	s_waitcnt lgkmcnt(4)
	v_mul_f32_e32 v73, v81, v4
	ds_bpermute_b32 v4, v79, v10
	ds_bpermute_b32 v15, v77, v10
	s_waitcnt vmcnt(31) lgkmcnt(2)
	v_mul_f32_e32 v2, v100, v11
	v_mul_f32_e32 v74, v74, v3
	ds_bpermute_b32 v3, v80, v10
	s_waitcnt vmcnt(29) lgkmcnt(2)
	v_mul_f32_e32 v11, v102, v4
	s_waitcnt vmcnt(27) lgkmcnt(1)
	v_mul_f32_e32 v4, v104, v15
	v_max3_f32 v15, |v45|, 0, |v44|
	v_max3_f32 v15, v15, |v43|, |v54|
	v_max3_f32 v15, v15, |v50|, |v49|
	v_max3_f32 v15, v15, |v47|, |v46|
	v_max3_f32 v15, v15, |v59|, |v57|
	v_max3_f32 v15, v15, |v52|, |v51|
	v_max3_f32 v15, v15, |v48|, |v65|
	v_max3_f32 v15, v15, |v60|, |v58|
	v_max3_f32 v15, v15, |v55|, |v53|
	v_max3_f32 v15, v15, |v68|, |v66|
	v_max3_f32 v15, v15, |v63|, |v61|
	v_mul_f32_e32 v71, v82, v5
	ds_bpermute_b32 v5, v78, v10
	v_max3_f32 v15, v15, |v56|, |v72|
	v_mul_f32_e32 v62, v85, v12
	v_max3_f32 v15, v15, |v70|, |v69|
	v_max3_f32 v15, v15, |v64|, |v62|
	ds_bpermute_b32 v67, v67, v10
	v_max3_f32 v15, v15, |v75|, |v74|
	ds_bpermute_b32 v22, v22, v10
	ds_bpermute_b32 v21, v21, v10
	s_waitcnt lgkmcnt(4)
	v_mul_f32_e32 v12, v101, v3
	v_max3_f32 v15, v15, |v73|, |v71|
	ds_bpermute_b32 v20, v20, v10
	ds_bpermute_b32 v19, v19, v10
	s_waitcnt lgkmcnt(5)
	v_mul_f32_e32 v5, v103, v5
	v_max3_f32 v15, v15, |v2|, |v12|
	ds_bpermute_b32 v26, v26, v10
	ds_bpermute_b32 v25, v25, v10
	s_waitcnt vmcnt(26)
	v_mul_f32_e32 v3, v105, v76
	v_max3_f32 v15, v15, |v11|, |v5|
	ds_bpermute_b32 v24, v24, v10
	ds_bpermute_b32 v23, v23, v10
	v_max3_f32 v76, v15, |v4|, |v3|
	s_waitcnt vmcnt(25) lgkmcnt(8)
	v_mul_f32_e32 v15, v106, v67
	s_waitcnt vmcnt(24)
	v_mul_f32_e32 v13, v107, v13
	ds_bpermute_b32 v30, v30, v10
	ds_bpermute_b32 v29, v29, v10
	v_max3_f32 v67, v76, |v15|, |v13|
	s_waitcnt vmcnt(23) lgkmcnt(9)
	v_mul_f32_e32 v22, v109, v22
	s_waitcnt vmcnt(22) lgkmcnt(8)
	v_mul_f32_e32 v21, v110, v21
	ds_bpermute_b32 v28, v28, v10
	ds_bpermute_b32 v27, v27, v10
	v_max3_f32 v67, v67, |v22|, |v21|
	s_waitcnt vmcnt(21) lgkmcnt(9)
	v_mul_f32_e32 v20, v111, v20
	s_waitcnt vmcnt(20) lgkmcnt(8)
	v_mul_f32_e32 v19, v112, v19
	ds_bpermute_b32 v34, v34, v10
	ds_bpermute_b32 v33, v33, v10
	v_max3_f32 v67, v67, |v20|, |v19|
	s_waitcnt vmcnt(19) lgkmcnt(9)
	v_mul_f32_e32 v26, v113, v26
	s_waitcnt vmcnt(18) lgkmcnt(8)
	v_mul_f32_e32 v25, v114, v25
	ds_bpermute_b32 v32, v32, v10
	ds_bpermute_b32 v31, v31, v10
	v_max3_f32 v67, v67, |v26|, |v25|
	s_waitcnt vmcnt(17) lgkmcnt(9)
	v_mul_f32_e32 v24, v115, v24
	s_waitcnt vmcnt(16) lgkmcnt(8)
	v_mul_f32_e32 v23, v116, v23
	ds_bpermute_b32 v38, v38, v10
	ds_bpermute_b32 v37, v37, v10
	v_max3_f32 v67, v67, |v24|, |v23|
	s_waitcnt vmcnt(15) lgkmcnt(9)
	v_mul_f32_e32 v30, v117, v30
	s_waitcnt vmcnt(14) lgkmcnt(8)
	v_mul_f32_e32 v29, v118, v29
	ds_bpermute_b32 v36, v36, v10
	ds_bpermute_b32 v35, v35, v10
	v_max3_f32 v67, v67, |v30|, |v29|
	s_waitcnt vmcnt(13) lgkmcnt(9)
	v_mul_f32_e32 v28, v119, v28
	s_waitcnt vmcnt(12) lgkmcnt(8)
	v_mul_f32_e32 v27, v120, v27
	ds_bpermute_b32 v42, v42, v10
	ds_bpermute_b32 v76, v41, v10
	v_max3_f32 v67, v67, |v28|, |v27|
	s_waitcnt vmcnt(11) lgkmcnt(9)
	v_mul_f32_e32 v34, v121, v34
	s_waitcnt vmcnt(10) lgkmcnt(8)
	v_mul_f32_e32 v33, v122, v33
	ds_bpermute_b32 v39, v39, v10
	ds_bpermute_b32 v10, v40, v10
	v_max3_f32 v67, v67, |v34|, |v33|
	s_waitcnt vmcnt(9) lgkmcnt(9)
	v_mul_f32_e32 v32, v123, v32
	s_waitcnt vmcnt(8) lgkmcnt(8)
	v_mul_f32_e32 v31, v124, v31
	v_max3_f32 v67, v67, |v32|, |v31|
	s_waitcnt vmcnt(7) lgkmcnt(7)
	v_mul_f32_e32 v38, v98, v38
	s_waitcnt vmcnt(6) lgkmcnt(6)
	v_mul_f32_e32 v37, v99, v37
	v_max3_f32 v67, v67, |v38|, |v37|
	s_waitcnt vmcnt(5) lgkmcnt(5)
	v_mul_f32_e32 v36, v125, v36
	s_waitcnt vmcnt(4) lgkmcnt(4)
	v_mul_f32_e32 v35, v126, v35
	v_max3_f32 v67, v67, |v36|, |v35|
	s_waitcnt vmcnt(3) lgkmcnt(3)
	v_mul_f32_e32 v41, v127, v42
	s_waitcnt vmcnt(2) lgkmcnt(2)
	v_mul_f32_e32 v40, v128, v76
	v_max3_f32 v42, v67, |v41|, |v40|
	s_waitcnt vmcnt(1) lgkmcnt(1)
	v_mul_f32_e32 v39, v129, v39
	s_waitcnt vmcnt(0) lgkmcnt(0)
	v_mul_f32_e32 v10, v130, v10
	v_max3_f32 v42, v42, |v39|, |v10|
	v_mov_b32_e32 v67, v42
	s_nop 1
	v_permlane32_swap_b32_e32 v42, v67
	s_mov_b64 s[0:1], exec
	v_readlane_b32 s2, v249, 60
	v_readlane_b32 s3, v249, 61
	s_and_b64 s[2:3], s[0:1], s[2:3]
	s_mov_b64 exec, s[2:3]
	s_cbranch_execz .LBB0_61
	v_max_f32_e32 v42, v42, v42
	v_max_f32_e32 v67, v67, v67
	s_add_i32 s2, s20, 0
	v_max_f32_e32 v42, v42, v67
	v_lshl_add_u32 v67, v108, 2, s2
	v_add_u32_e32 v67, 0x20000, v67
	ds_write_b32 v67, v42

.LBB0_360:
	s_ashr_i32 s11, s27, 6
	s_lshl_b32 s1, s11, 14
	s_add_i32 s10, s1, 0
	s_lshl_b32 s1, s29, 1
	s_add_i32 s12, s0, s1
	s_add_i32 s12, s12, -2
	s_cmp_gt_u32 s12, 63
	v_and_b32_e32 v6, 63, v144
	s_cbranch_scc0 .LBB0_383
	s_and_b32 s13, s12, 63
	s_cmp_gt_u32 s13, 31
	s_cbranch_scc0 .LBB0_384
	s_mov_b64 s[0:1], 0
	s_cmp_lt_u32 s13, 48
	s_mov_b64 s[2:3], 0
	s_cbranch_scc0 .LBB0_372
	s_load_dwordx4 s[4:7], s[18:19], 0x50
	s_lshl_b32 s2, s11, 7
	v_or_b32_e32 v4, s2, v6
	v_mov_b32_e32 v10, 1.0
	v_ashrrev_i32_e32 v5, 31, v4
	s_waitcnt lgkmcnt(0)
	s_cmp_lg_u64 s[4:5], 0
	s_cselect_b64 s[8:9], -1, 0
	s_cmp_eq_u64 s[4:5], 0
	v_mov_b32_e32 v11, 1.0
	s_cbranch_scc1 .LBB0_365
	v_lshl_add_u64 v[2:3], v[4:5], 2, s[4:5]
	global_load_dword v11, v[2:3], off sc1 nt
.LBB0_365:
	v_and_b32_e32 v9, 31, v144
	s_lshl_b32 s3, s13, 7
	v_lshrrev_b32_e32 v7, 5, v6
	s_add_u32 s6, s6, s3
	v_lshlrev_b32_e32 v8, 2, v9
	s_addc_u32 s7, s7, 0
	v_lshl_or_b32 v2, v7, 11, v8
	v_mov_b32_e32 v3, 0
	s_ashr_i32 s3, s2, 31
	v_lshl_add_u64 v[2:3], s[6:7], 0, v[2:3]
	s_lshl_b64 s[6:7], s[2:3], 11
	v_lshl_add_u64 v[20:21], v[2:3], 0, s[6:7]
	s_or_b32 s6, s2, 2
	s_ashr_i32 s7, s6, 31
	s_lshl_b64 s[6:7], s[6:7], 11
	v_lshl_add_u64 v[22:23], v[2:3], 0, s[6:7]
	s_or_b32 s6, s2, 4
	s_ashr_i32 s7, s6, 31
	s_lshl_b64 s[6:7], s[6:7], 11
	v_lshl_add_u64 v[24:25], v[2:3], 0, s[6:7]
	s_or_b32 s6, s2, 6
	s_ashr_i32 s7, s6, 31
	s_lshl_b64 s[6:7], s[6:7], 11
	v_lshl_add_u64 v[26:27], v[2:3], 0, s[6:7]
	s_or_b32 s6, s2, 8
	s_ashr_i32 s7, s6, 31
	s_lshl_b64 s[6:7], s[6:7], 11
	v_lshl_add_u64 v[28:29], v[2:3], 0, s[6:7]
	s_or_b32 s6, s2, 10
	s_ashr_i32 s7, s6, 31
	s_lshl_b64 s[6:7], s[6:7], 11
	v_lshl_add_u64 v[30:31], v[2:3], 0, s[6:7]
	s_or_b32 s6, s2, 12
	s_ashr_i32 s7, s6, 31
	s_lshl_b64 s[6:7], s[6:7], 11
	v_lshl_add_u64 v[32:33], v[2:3], 0, s[6:7]
	s_or_b32 s6, s2, 14
	s_ashr_i32 s7, s6, 31
	s_lshl_b64 s[6:7], s[6:7], 11
	v_lshl_add_u64 v[34:35], v[2:3], 0, s[6:7]
	s_or_b32 s6, s2, 16
	s_ashr_i32 s7, s6, 31
	s_lshl_b64 s[6:7], s[6:7], 11
	global_load_dword v18, v[20:21], off offset:-4096 sc1 nt
	global_load_dword v19, v[22:23], off offset:-4096 sc1 nt
	global_load_dword v16, v[24:25], off offset:-4096 sc1 nt
	global_load_dword v17, v[26:27], off offset:-4096 sc1 nt
	global_load_dword v14, v[28:29], off offset:-4096 sc1 nt
	global_load_dword v15, v[30:31], off offset:-4096 sc1 nt
	global_load_dword v12, v[32:33], off offset:-4096 sc1 nt
	global_load_dword v13, v[34:35], off offset:-4096 sc1 nt
	v_lshl_add_u64 v[28:29], v[2:3], 0, s[6:7]
	s_or_b32 s6, s2, 18
	s_ashr_i32 s7, s6, 31
	s_lshl_b64 s[6:7], s[6:7], 11
	v_lshl_add_u64 v[30:31], v[2:3], 0, s[6:7]
	s_or_b32 s6, s2, 20
	s_ashr_i32 s7, s6, 31
	s_lshl_b64 s[6:7], s[6:7], 11
	v_lshl_add_u64 v[32:33], v[2:3], 0, s[6:7]
	s_or_b32 s6, s2, 22
	s_ashr_i32 s7, s6, 31
	s_lshl_b64 s[6:7], s[6:7], 11
	v_lshl_add_u64 v[34:35], v[2:3], 0, s[6:7]
	s_or_b32 s6, s2, 24
	s_ashr_i32 s7, s6, 31
	s_lshl_b64 s[6:7], s[6:7], 11
	v_lshl_add_u64 v[36:37], v[2:3], 0, s[6:7]
	s_or_b32 s6, s2, 26
	s_ashr_i32 s7, s6, 31
	s_lshl_b64 s[6:7], s[6:7], 11
	v_lshl_add_u64 v[38:39], v[2:3], 0, s[6:7]
	s_or_b32 s6, s2, 28
	s_ashr_i32 s7, s6, 31
	s_lshl_b64 s[6:7], s[6:7], 11
	v_lshl_add_u64 v[40:41], v[2:3], 0, s[6:7]
	s_or_b32 s6, s2, 30
	s_ashr_i32 s7, s6, 31
	s_lshl_b64 s[6:7], s[6:7], 11
	v_lshl_add_u64 v[42:43], v[2:3], 0, s[6:7]
	s_or_b32 s6, s2, 32
	s_ashr_i32 s7, s6, 31
	s_lshl_b64 s[6:7], s[6:7], 11
	global_load_dword v26, v[28:29], off offset:-4096 sc1 nt
	global_load_dword v27, v[30:31], off offset:-4096 sc1 nt
	global_load_dword v24, v[32:33], off offset:-4096 sc1 nt
	global_load_dword v25, v[34:35], off offset:-4096 sc1 nt
	global_load_dword v22, v[36:37], off offset:-4096 sc1 nt
	global_load_dword v23, v[38:39], off offset:-4096 sc1 nt
	global_load_dword v20, v[40:41], off offset:-4096 sc1 nt
	global_load_dword v21, v[42:43], off offset:-4096 sc1 nt
	v_lshl_add_u64 v[36:37], v[2:3], 0, s[6:7]
	s_or_b32 s6, s2, 34
	s_ashr_i32 s7, s6, 31
	s_lshl_b64 s[6:7], s[6:7], 11
	v_lshl_add_u64 v[38:39], v[2:3], 0, s[6:7]
	s_or_b32 s6, s2, 36
	s_ashr_i32 s7, s6, 31
	s_lshl_b64 s[6:7], s[6:7], 11
	v_lshl_add_u64 v[40:41], v[2:3], 0, s[6:7]
	s_or_b32 s6, s2, 38
	s_ashr_i32 s7, s6, 31
	s_lshl_b64 s[6:7], s[6:7], 11
	v_lshl_add_u64 v[42:43], v[2:3], 0, s[6:7]
	s_or_b32 s6, s2, 40
	s_ashr_i32 s7, s6, 31
	s_lshl_b64 s[6:7], s[6:7], 11
	v_lshl_add_u64 v[44:45], v[2:3], 0, s[6:7]
	s_or_b32 s6, s2, 42
	s_ashr_i32 s7, s6, 31
	s_lshl_b64 s[6:7], s[6:7], 11
	v_lshl_add_u64 v[46:47], v[2:3], 0, s[6:7]
	s_or_b32 s6, s2, 44
	s_ashr_i32 s7, s6, 31
	s_lshl_b64 s[6:7], s[6:7], 11
	v_lshl_add_u64 v[48:49], v[2:3], 0, s[6:7]
	s_or_b32 s6, s2, 46
	s_ashr_i32 s7, s6, 31
	s_lshl_b64 s[6:7], s[6:7], 11
	v_lshl_add_u64 v[50:51], v[2:3], 0, s[6:7]
	s_or_b32 s6, s2, 48
	s_ashr_i32 s7, s6, 31
	s_lshl_b64 s[6:7], s[6:7], 11
	global_load_dword v34, v[36:37], off offset:-4096 sc1 nt
	global_load_dword v35, v[38:39], off offset:-4096 sc1 nt
	global_load_dword v32, v[40:41], off offset:-4096 sc1 nt
	global_load_dword v33, v[42:43], off offset:-4096 sc1 nt
	global_load_dword v30, v[44:45], off offset:-4096 sc1 nt
	global_load_dword v31, v[46:47], off offset:-4096 sc1 nt
	global_load_dword v28, v[48:49], off offset:-4096 sc1 nt
	global_load_dword v29, v[50:51], off offset:-4096 sc1 nt
	v_lshl_add_u64 v[44:45], v[2:3], 0, s[6:7]
	s_or_b32 s6, s2, 50
	s_ashr_i32 s7, s6, 31
	s_lshl_b64 s[6:7], s[6:7], 11
	v_lshl_add_u64 v[46:47], v[2:3], 0, s[6:7]
	s_or_b32 s6, s2, 52
	s_ashr_i32 s7, s6, 31
	s_lshl_b64 s[6:7], s[6:7], 11
	v_lshl_add_u64 v[48:49], v[2:3], 0, s[6:7]
	s_or_b32 s6, s2, 54
	s_ashr_i32 s7, s6, 31
	s_lshl_b64 s[6:7], s[6:7], 11
	v_lshl_add_u64 v[50:51], v[2:3], 0, s[6:7]
	s_or_b32 s6, s2, 56
	s_ashr_i32 s7, s6, 31
	s_lshl_b64 s[6:7], s[6:7], 11
	v_lshl_add_u64 v[52:53], v[2:3], 0, s[6:7]
	s_or_b32 s6, s2, 58
	s_ashr_i32 s7, s6, 31
	s_lshl_b64 s[6:7], s[6:7], 11
	v_lshl_add_u64 v[54:55], v[2:3], 0, s[6:7]
	s_or_b32 s6, s2, 60
	s_ashr_i32 s7, s6, 31
	s_lshl_b64 s[6:7], s[6:7], 11
	v_lshl_add_u64 v[56:57], v[2:3], 0, s[6:7]
	s_or_b32 s6, s2, 62
	s_ashr_i32 s7, s6, 31
	s_lshl_b64 s[6:7], s[6:7], 11
	v_lshl_add_u64 v[58:59], v[2:3], 0, s[6:7]
	global_load_dword v42, v[44:45], off offset:-4096 sc1 nt
	global_load_dword v43, v[46:47], off offset:-4096 sc1 nt
	global_load_dword v40, v[48:49], off offset:-4096 sc1 nt
	global_load_dword v41, v[50:51], off offset:-4096 sc1 nt
	global_load_dword v38, v[52:53], off offset:-4096 sc1 nt
	global_load_dword v39, v[54:55], off offset:-4096 sc1 nt
	global_load_dword v36, v[56:57], off offset:-4096 sc1 nt
	global_load_dword v37, v[58:59], off offset:-4096 sc1 nt
	s_andn2_b64 vcc, exec, s[8:9]
	s_cbranch_vccnz .LBB0_367
	v_lshl_add_u64 v[4:5], v[4:5], 2, s[4:5]
	global_load_dword v10, v[4:5], off offset:256 sc1 nt
.LBB0_367:
	s_or_b32 s4, s2, 64
	s_ashr_i32 s5, s4, 31
	s_lshl_b64 s[4:5], s[4:5], 11
	v_lshl_add_u64 v[4:5], v[2:3], 0, s[4:5]
	s_or_b32 s4, s2, 0x42
	s_ashr_i32 s5, s4, 31
	s_lshl_b64 s[4:5], s[4:5], 11
	v_lshl_add_u64 v[44:45], v[2:3], 0, s[4:5]
	s_or_b32 s4, s2, 0x44
	s_ashr_i32 s5, s4, 31
	s_lshl_b64 s[4:5], s[4:5], 11
	v_lshl_add_u64 v[46:47], v[2:3], 0, s[4:5]
	s_or_b32 s4, s2, 0x46
	s_ashr_i32 s5, s4, 31
	s_lshl_b64 s[4:5], s[4:5], 11
	v_lshl_add_u64 v[48:49], v[2:3], 0, s[4:5]
	s_or_b32 s4, s2, 0x48
	s_ashr_i32 s5, s4, 31
	s_lshl_b64 s[4:5], s[4:5], 11
	v_lshl_add_u64 v[50:51], v[2:3], 0, s[4:5]
	s_or_b32 s4, s2, 0x4a
	s_ashr_i32 s5, s4, 31
	s_lshl_b64 s[4:5], s[4:5], 11
	v_lshl_add_u64 v[52:53], v[2:3], 0, s[4:5]
	s_or_b32 s4, s2, 0x4c
	s_ashr_i32 s5, s4, 31
	s_lshl_b64 s[4:5], s[4:5], 11
	v_lshl_add_u64 v[54:55], v[2:3], 0, s[4:5]
	s_or_b32 s4, s2, 0x4e
	s_ashr_i32 s5, s4, 31
	s_lshl_b64 s[4:5], s[4:5], 11
	v_lshl_add_u64 v[56:57], v[2:3], 0, s[4:5]
	s_or_b32 s4, s2, 0x50
	s_ashr_i32 s5, s4, 31
	s_lshl_b64 s[4:5], s[4:5], 11
	global_load_dword v71, v[4:5], off offset:-4096 sc1 nt
	global_load_dword v72, v[44:45], off offset:-4096 sc1 nt
	global_load_dword v73, v[46:47], off offset:-4096 sc1 nt
	global_load_dword v74, v[48:49], off offset:-4096 sc1 nt
	global_load_dword v75, v[50:51], off offset:-4096 sc1 nt
	global_load_dword v76, v[52:53], off offset:-4096 sc1 nt
	global_load_dword v77, v[54:55], off offset:-4096 sc1 nt
	global_load_dword v78, v[56:57], off offset:-4096 sc1 nt
	v_lshl_add_u64 v[4:5], v[2:3], 0, s[4:5]
	s_or_b32 s4, s2, 0x52
	s_ashr_i32 s5, s4, 31
	s_lshl_b64 s[4:5], s[4:5], 11
	v_lshl_add_u64 v[44:45], v[2:3], 0, s[4:5]
	s_or_b32 s4, s2, 0x54
	s_ashr_i32 s5, s4, 31
	s_lshl_b64 s[4:5], s[4:5], 11
	v_lshl_add_u64 v[46:47], v[2:3], 0, s[4:5]
	s_or_b32 s4, s2, 0x56
	s_ashr_i32 s5, s4, 31
	s_lshl_b64 s[4:5], s[4:5], 11
	v_lshl_add_u64 v[48:49], v[2:3], 0, s[4:5]
	s_or_b32 s4, s2, 0x58
	s_ashr_i32 s5, s4, 31
	s_lshl_b64 s[4:5], s[4:5], 11
	v_lshl_add_u64 v[50:51], v[2:3], 0, s[4:5]
	s_or_b32 s4, s2, 0x5a
	s_ashr_i32 s5, s4, 31
	s_lshl_b64 s[4:5], s[4:5], 11
	v_lshl_add_u64 v[52:53], v[2:3], 0, s[4:5]
	s_or_b32 s4, s2, 0x5c
	s_ashr_i32 s5, s4, 31
	s_lshl_b64 s[4:5], s[4:5], 11
	v_lshl_add_u64 v[54:55], v[2:3], 0, s[4:5]
	s_or_b32 s4, s2, 0x5e
	s_ashr_i32 s5, s4, 31
	s_lshl_b64 s[4:5], s[4:5], 11
	v_lshl_add_u64 v[56:57], v[2:3], 0, s[4:5]
	s_or_b32 s4, s2, 0x60
	s_ashr_i32 s5, s4, 31
	s_lshl_b64 s[4:5], s[4:5], 11
	global_load_dword v79, v[4:5], off offset:-4096 sc1 nt
	global_load_dword v80, v[44:45], off offset:-4096 sc1 nt
	global_load_dword v81, v[46:47], off offset:-4096 sc1 nt
	global_load_dword v82, v[48:49], off offset:-4096 sc1 nt
	global_load_dword v83, v[50:51], off offset:-4096 sc1 nt
	global_load_dword v84, v[52:53], off offset:-4096 sc1 nt
	global_load_dword v85, v[54:55], off offset:-4096 sc1 nt
	global_load_dword v86, v[56:57], off offset:-4096 sc1 nt
	v_lshl_add_u64 v[4:5], v[2:3], 0, s[4:5]
	s_or_b32 s4, s2, 0x62
	s_ashr_i32 s5, s4, 31
	s_lshl_b64 s[4:5], s[4:5], 11
	v_lshl_add_u64 v[44:45], v[2:3], 0, s[4:5]
	s_or_b32 s4, s2, 0x64
	s_ashr_i32 s5, s4, 31
	s_lshl_b64 s[4:5], s[4:5], 11
	v_lshl_add_u64 v[46:47], v[2:3], 0, s[4:5]
	s_or_b32 s4, s2, 0x66
	s_ashr_i32 s5, s4, 31
	s_lshl_b64 s[4:5], s[4:5], 11
	v_lshl_add_u64 v[48:49], v[2:3], 0, s[4:5]
	s_or_b32 s4, s2, 0x68
	s_ashr_i32 s5, s4, 31
	s_lshl_b64 s[4:5], s[4:5], 11
	v_lshl_add_u64 v[50:51], v[2:3], 0, s[4:5]
	s_or_b32 s4, s2, 0x6a
	s_ashr_i32 s5, s4, 31
	s_lshl_b64 s[4:5], s[4:5], 11
	v_lshl_add_u64 v[52:53], v[2:3], 0, s[4:5]
	s_or_b32 s4, s2, 0x6c
	s_ashr_i32 s5, s4, 31
	s_lshl_b64 s[4:5], s[4:5], 11
	v_lshl_add_u64 v[54:55], v[2:3], 0, s[4:5]
	s_or_b32 s4, s2, 0x6e
	s_ashr_i32 s5, s4, 31
	s_lshl_b64 s[4:5], s[4:5], 11
	v_lshl_add_u64 v[56:57], v[2:3], 0, s[4:5]
	s_or_b32 s4, s2, 0x70
	s_ashr_i32 s5, s4, 31
	s_lshl_b64 s[4:5], s[4:5], 11
	global_load_dword v87, v[4:5], off offset:-4096 sc1 nt
	global_load_dword v88, v[44:45], off offset:-4096 sc1 nt
	global_load_dword v89, v[46:47], off offset:-4096 sc1 nt
	global_load_dword v90, v[48:49], off offset:-4096 sc1 nt
	global_load_dword v91, v[50:51], off offset:-4096 sc1 nt
	global_load_dword v92, v[52:53], off offset:-4096 sc1 nt
	global_load_dword v93, v[54:55], off offset:-4096 sc1 nt
	global_load_dword v94, v[56:57], off offset:-4096 sc1 nt
	v_lshl_add_u64 v[4:5], v[2:3], 0, s[4:5]
	s_or_b32 s4, s2, 0x72
	s_ashr_i32 s5, s4, 31
	s_lshl_b64 s[4:5], s[4:5], 11
	v_lshl_add_u64 v[44:45], v[2:3], 0, s[4:5]
	s_or_b32 s4, s2, 0x74
	s_ashr_i32 s5, s4, 31
	s_lshl_b64 s[4:5], s[4:5], 11
	v_lshl_add_u64 v[46:47], v[2:3], 0, s[4:5]
	s_or_b32 s4, s2, 0x76
	s_ashr_i32 s5, s4, 31
	s_lshl_b64 s[4:5], s[4:5], 11
	v_lshl_add_u64 v[48:49], v[2:3], 0, s[4:5]
	s_or_b32 s4, s2, 0x78
	s_ashr_i32 s5, s4, 31
	s_lshl_b64 s[4:5], s[4:5], 11
	v_lshl_add_u64 v[50:51], v[2:3], 0, s[4:5]
	s_or_b32 s4, s2, 0x7a
	s_ashr_i32 s5, s4, 31
	s_lshl_b64 s[4:5], s[4:5], 11
	v_lshl_add_u64 v[52:53], v[2:3], 0, s[4:5]
	s_or_b32 s4, s2, 0x7c
	s_ashr_i32 s5, s4, 31
	s_lshl_b64 s[4:5], s[4:5], 11
	v_lshl_add_u64 v[54:55], v[2:3], 0, s[4:5]
	s_or_b32 s4, s2, 0x7e
	s_ashr_i32 s5, s4, 31
	s_lshl_b64 s[4:5], s[4:5], 11
	v_lshlrev_b32_e32 v95, 2, v7
	v_lshl_add_u64 v[2:3], v[2:3], 0, s[4:5]
	s_waitcnt vmcnt(0)
	ds_bpermute_b32 v56, v95, v11
	ds_bpermute_b32 v57, v95, v11 offset:8
	global_load_dword v96, v[4:5], off offset:-4096 sc1 nt
	global_load_dword v97, v[44:45], off offset:-4096 sc1 nt
	global_load_dword v98, v[46:47], off offset:-4096 sc1 nt
	global_load_dword v99, v[48:49], off offset:-4096 sc1 nt
	global_load_dword v100, v[50:51], off offset:-4096 sc1 nt
	global_load_dword v101, v[52:53], off offset:-4096 sc1 nt
	global_load_dword v102, v[54:55], off offset:-4096 sc1 nt
	global_load_dword v103, v[2:3], off offset:-4096 sc1 nt
	ds_bpermute_b32 v2, v95, v11 offset:16
	ds_bpermute_b32 v3, v95, v11 offset:24
	s_waitcnt lgkmcnt(3)
	v_mul_f32_e32 v45, v18, v56
	s_waitcnt lgkmcnt(2)
	v_mul_f32_e32 v5, v19, v57
	v_max3_f32 v18, |v45|, 0, |v5|
	s_waitcnt lgkmcnt(1)
	v_mul_f32_e32 v4, v16, v2
	s_waitcnt lgkmcnt(0)
	v_mul_f32_e32 v3, v17, v3
	ds_bpermute_b32 v2, v95, v11 offset:32
	v_max3_f32 v17, v18, |v4|, |v3|
	ds_bpermute_b32 v18, v95, v11 offset:48
	ds_bpermute_b32 v19, v95, v11 offset:56
	ds_bpermute_b32 v16, v95, v11 offset:40
	s_waitcnt lgkmcnt(3)
	v_mul_f32_e32 v48, v14, v2
	ds_bpermute_b32 v14, v95, v11 offset:80
	s_waitcnt lgkmcnt(3)
	v_mul_f32_e32 v46, v12, v18
	s_waitcnt lgkmcnt(2)
	v_mul_f32_e32 v44, v13, v19
	ds_bpermute_b32 v12, v95, v11 offset:64
	ds_bpermute_b32 v13, v95, v11 offset:72
	s_waitcnt lgkmcnt(3)
	v_mul_f32_e32 v47, v15, v16
	ds_bpermute_b32 v15, v95, v11 offset:88
	s_waitcnt lgkmcnt(3)
	v_mul_f32_e32 v50, v24, v14
	s_waitcnt lgkmcnt(2)
	v_mul_f32_e32 v52, v26, v12
	s_waitcnt lgkmcnt(1)
	v_mul_f32_e32 v51, v27, v13
	ds_bpermute_b32 v12, v95, v11 offset:96
	ds_bpermute_b32 v13, v95, v11 offset:104
	ds_bpermute_b32 v14, v95, v11 offset:112
	s_waitcnt lgkmcnt(3)
	v_mul_f32_e32 v49, v25, v15
	ds_bpermute_b32 v15, v95, v11 offset:120
	s_waitcnt lgkmcnt(3)
	v_mul_f32_e32 v56, v22, v12
	s_waitcnt lgkmcnt(2)
	v_mul_f32_e32 v55, v23, v13
	s_waitcnt lgkmcnt(1)
	v_mul_f32_e32 v54, v20, v14
	ds_bpermute_b32 v12, v95, v11 offset:128
	ds_bpermute_b32 v13, v95, v11 offset:136
	ds_bpermute_b32 v14, v95, v11 offset:144
	s_waitcnt lgkmcnt(3)
	v_mul_f32_e32 v53, v21, v15
	ds_bpermute_b32 v15, v95, v11 offset:152
	s_waitcnt lgkmcnt(3)
	v_mul_f32_e32 v60, v34, v12
	s_waitcnt lgkmcnt(2)
	v_mul_f32_e32 v59, v35, v13
	s_waitcnt lgkmcnt(1)
	v_mul_f32_e32 v58, v32, v14
	ds_bpermute_b32 v12, v95, v11 offset:160
	ds_bpermute_b32 v13, v95, v11 offset:168
	ds_bpermute_b32 v14, v95, v11 offset:176
	s_waitcnt lgkmcnt(3)
	v_mul_f32_e32 v57, v33, v15
	ds_bpermute_b32 v15, v95, v11 offset:184
	s_waitcnt lgkmcnt(3)
	v_mul_f32_e32 v64, v30, v12
	s_waitcnt lgkmcnt(2)
	v_mul_f32_e32 v63, v31, v13
	s_waitcnt lgkmcnt(1)
	v_mul_f32_e32 v62, v28, v14
	ds_bpermute_b32 v12, v95, v11 offset:192
	ds_bpermute_b32 v13, v95, v11 offset:200
	ds_bpermute_b32 v14, v95, v11 offset:208
	s_waitcnt lgkmcnt(3)
	v_mul_f32_e32 v61, v29, v15
	ds_bpermute_b32 v15, v95, v11 offset:216
	s_waitcnt lgkmcnt(3)
	v_mul_f32_e32 v66, v42, v12
	s_waitcnt lgkmcnt(2)
	v_mul_f32_e32 v65, v43, v13
	s_waitcnt lgkmcnt(1)
	v_mul_f32_e32 v43, v40, v14
	ds_bpermute_b32 v12, v95, v11 offset:224
	ds_bpermute_b32 v13, v95, v11 offset:232
	ds_bpermute_b32 v14, v95, v11 offset:240
	ds_bpermute_b32 v11, v95, v11 offset:248
	s_waitcnt lgkmcnt(4)
	v_mul_f32_e32 v42, v41, v15
	s_waitcnt lgkmcnt(3)
	v_mul_f32_e32 v70, v38, v12
	ds_bpermute_b32 v12, v95, v10 offset:8
	ds_bpermute_b32 v15, v95, v10 offset:16
	s_waitcnt lgkmcnt(2)
	v_mul_f32_e32 v67, v37, v11
	ds_bpermute_b32 v11, v95, v10
	ds_bpermute_b32 v16, v95, v10 offset:24
	v_mul_f32_e32 v69, v39, v13
	v_mul_f32_e32 v68, v36, v14
	s_waitcnt lgkmcnt(3)
	v_mul_f32_e32 v13, v72, v12
	s_waitcnt lgkmcnt(1)
	v_mul_f32_e32 v14, v71, v11
	v_mul_f32_e32 v12, v73, v15
	s_waitcnt lgkmcnt(0)
	v_mul_f32_e32 v11, v74, v16
	ds_bpermute_b32 v15, v95, v10 offset:32
	ds_bpermute_b32 v16, v95, v10 offset:40
	ds_bpermute_b32 v19, v95, v10 offset:48
	ds_bpermute_b32 v20, v95, v10 offset:56
	v_max3_f32 v2, v17, |v48|, |v47|
	s_waitcnt lgkmcnt(3)
	v_mul_f32_e32 v18, v75, v15
	s_waitcnt lgkmcnt(2)
	v_mul_f32_e32 v17, v76, v16
	s_waitcnt lgkmcnt(1)
	v_mul_f32_e32 v16, v77, v19
	s_waitcnt lgkmcnt(0)
	v_mul_f32_e32 v15, v78, v20
	ds_bpermute_b32 v19, v95, v10 offset:64
	ds_bpermute_b32 v20, v95, v10 offset:72
	ds_bpermute_b32 v23, v95, v10 offset:80
	ds_bpermute_b32 v24, v95, v10 offset:88
	v_max3_f32 v2, v2, |v46|, |v44|
	v_max3_f32 v2, v2, |v52|, |v51|
	s_waitcnt lgkmcnt(3)
	v_mul_f32_e32 v22, v79, v19
	s_waitcnt lgkmcnt(2)
	v_mul_f32_e32 v21, v80, v20
	s_waitcnt lgkmcnt(1)
	v_mul_f32_e32 v20, v81, v23
	s_waitcnt lgkmcnt(0)
	v_mul_f32_e32 v19, v82, v24
	ds_bpermute_b32 v23, v95, v10 offset:96
	ds_bpermute_b32 v24, v95, v10 offset:104
	ds_bpermute_b32 v27, v95, v10 offset:112
	ds_bpermute_b32 v28, v95, v10 offset:120
	v_max3_f32 v2, v2, |v50|, |v49|
	v_max3_f32 v2, v2, |v56|, |v55|
	v_max3_f32 v2, v2, |v54|, |v53|
	v_max3_f32 v2, v2, |v60|, |v59|
	v_max3_f32 v2, v2, |v58|, |v57|
	s_waitcnt lgkmcnt(3)
	v_mul_f32_e32 v26, v83, v23
	s_waitcnt lgkmcnt(2)
	v_mul_f32_e32 v25, v84, v24
	s_waitcnt lgkmcnt(1)
	v_mul_f32_e32 v24, v85, v27
	s_waitcnt lgkmcnt(0)
	v_mul_f32_e32 v23, v86, v28
	ds_bpermute_b32 v27, v95, v10 offset:128
	ds_bpermute_b32 v28, v95, v10 offset:136
	ds_bpermute_b32 v31, v95, v10 offset:144
	ds_bpermute_b32 v32, v95, v10 offset:152
	v_max3_f32 v2, v2, |v64|, |v63|
	v_max3_f32 v2, v2, |v62|, |v61|
	v_max3_f32 v2, v2, |v66|, |v65|
	v_max3_f32 v2, v2, |v43|, |v42|
	v_max3_f32 v2, v2, |v70|, |v69|
	s_waitcnt lgkmcnt(3)
	v_mul_f32_e32 v30, v87, v27
	s_waitcnt lgkmcnt(2)
	v_mul_f32_e32 v29, v88, v28
	s_waitcnt lgkmcnt(1)
	v_mul_f32_e32 v28, v89, v31
	s_waitcnt lgkmcnt(0)
	v_mul_f32_e32 v27, v90, v32
	ds_bpermute_b32 v31, v95, v10 offset:160
	ds_bpermute_b32 v32, v95, v10 offset:168
	ds_bpermute_b32 v35, v95, v10 offset:176
	ds_bpermute_b32 v36, v95, v10 offset:184
	v_max3_f32 v2, v2, |v68|, |v67|
	v_max3_f32 v2, v2, |v14|, |v13|
	v_max3_f32 v2, v2, |v12|, |v11|
	v_max3_f32 v2, v2, |v18|, |v17|
	v_max3_f32 v2, v2, |v16|, |v15|
	s_waitcnt lgkmcnt(3)
	v_mul_f32_e32 v34, v91, v31
	s_waitcnt lgkmcnt(2)
	v_mul_f32_e32 v33, v92, v32
	s_waitcnt lgkmcnt(1)
	v_mul_f32_e32 v32, v93, v35
	s_waitcnt lgkmcnt(0)
	v_mul_f32_e32 v31, v94, v36
	ds_bpermute_b32 v35, v95, v10 offset:192
	ds_bpermute_b32 v36, v95, v10 offset:200
	ds_bpermute_b32 v39, v95, v10 offset:208
	ds_bpermute_b32 v40, v95, v10 offset:216
	v_max3_f32 v2, v2, |v22|, |v21|
	v_max3_f32 v2, v2, |v20|, |v19|
	v_max3_f32 v2, v2, |v26|, |v25|
	v_max3_f32 v2, v2, |v24|, |v23|
	v_max3_f32 v2, v2, |v30|, |v29|
	s_waitcnt vmcnt(7) lgkmcnt(3)
	v_mul_f32_e32 v38, v96, v35
	s_waitcnt vmcnt(6) lgkmcnt(2)
	v_mul_f32_e32 v37, v97, v36
	s_waitcnt vmcnt(5) lgkmcnt(1)
	v_mul_f32_e32 v36, v98, v39
	s_waitcnt vmcnt(4) lgkmcnt(0)
	v_mul_f32_e32 v35, v99, v40
	ds_bpermute_b32 v39, v95, v10 offset:224
	ds_bpermute_b32 v40, v95, v10 offset:232
	v_max3_f32 v2, v2, |v28|, |v27|
	ds_bpermute_b32 v71, v95, v10 offset:240
	ds_bpermute_b32 v10, v95, v10 offset:248
	v_max3_f32 v2, v2, |v34|, |v33|
	v_max3_f32 v2, v2, |v32|, |v31|
	v_max3_f32 v2, v2, |v38|, |v37|
	v_max3_f32 v2, v2, |v36|, |v35|
	s_waitcnt vmcnt(3) lgkmcnt(3)
	v_mul_f32_e32 v41, v100, v39
	s_waitcnt vmcnt(2) lgkmcnt(2)
	v_mul_f32_e32 v40, v101, v40
	v_max3_f32 v2, v2, |v41|, |v40|
	s_waitcnt vmcnt(1) lgkmcnt(1)
	v_mul_f32_e32 v39, v102, v71
	s_waitcnt vmcnt(0) lgkmcnt(0)
	v_mul_f32_e32 v10, v103, v10
	v_max3_f32 v2, v2, |v39|, |v10|
	v_mov_b32_e32 v71, v2
	s_lshl_b32 s6, s13, 5
	s_nop 0
	v_permlane32_swap_b32_e32 v2, v71
	v_cmp_gt_u32_e32 vcc, 32, v6
	s_and_saveexec_b64 s[4:5], vcc
	s_cbranch_execz .LBB0_369
	v_max_f32_e32 v2, v2, v2
	v_max_f32_e32 v71, v71, v71
	s_add_i32 s7, s2, 0
	v_max_f32_e32 v2, v2, v71
	v_lshl_add_u32 v71, v6, 2, s7
	v_add_u32_e32 v71, 0x20000, v71
	ds_write_b32 v71, v2

.LBB0_373:
	s_load_dwordx4 s[4:7], s[18:19], 0x60
	s_lshl_b32 s0, s11, 7
	v_or_b32_e32 v4, s0, v6
	v_mov_b32_e32 v10, 1.0
	v_ashrrev_i32_e32 v5, 31, v4
	s_waitcnt lgkmcnt(0)
	s_cmp_lg_u64 s[4:5], 0
	s_cselect_b64 s[2:3], -1, 0
	s_cmp_eq_u64 s[4:5], 0
	v_mov_b32_e32 v11, 1.0
	s_cbranch_scc1 .LBB0_375
	v_lshl_add_u64 v[2:3], v[4:5], 2, s[4:5]
	global_load_dword v11, v[2:3], off sc1 nt
.LBB0_375:
	v_and_b32_e32 v9, 31, v144
	s_lshl_b32 s1, s13, 7
	v_lshrrev_b32_e32 v7, 5, v6
	s_add_u32 s6, s6, s1
	v_lshlrev_b32_e32 v8, 2, v9
	s_addc_u32 s7, s7, 0
	v_lshl_or_b32 v2, v7, 12, v8
	v_mov_b32_e32 v3, 0
	s_ashr_i32 s1, s0, 31
	v_lshl_add_u64 v[2:3], s[6:7], 0, v[2:3]
	s_lshl_b64 s[6:7], s[0:1], 12
	v_lshl_add_u64 v[20:21], v[2:3], 0, s[6:7]
	s_or_b32 s6, s0, 2
	s_ashr_i32 s7, s6, 31
	s_lshl_b64 s[6:7], s[6:7], 12
	v_lshl_add_u64 v[22:23], v[2:3], 0, s[6:7]
	s_or_b32 s6, s0, 4
	s_ashr_i32 s7, s6, 31
	s_lshl_b64 s[6:7], s[6:7], 12
	v_lshl_add_u64 v[24:25], v[2:3], 0, s[6:7]
	s_or_b32 s6, s0, 6
	s_ashr_i32 s7, s6, 31
	s_lshl_b64 s[6:7], s[6:7], 12
	v_lshl_add_u64 v[26:27], v[2:3], 0, s[6:7]
	s_or_b32 s6, s0, 8
	s_ashr_i32 s7, s6, 31
	s_lshl_b64 s[6:7], s[6:7], 12
	v_lshl_add_u64 v[28:29], v[2:3], 0, s[6:7]
	s_or_b32 s6, s0, 10
	s_ashr_i32 s7, s6, 31
	s_lshl_b64 s[6:7], s[6:7], 12
	v_lshl_add_u64 v[30:31], v[2:3], 0, s[6:7]
	s_or_b32 s6, s0, 12
	s_ashr_i32 s7, s6, 31
	s_lshl_b64 s[6:7], s[6:7], 12
	v_lshl_add_u64 v[32:33], v[2:3], 0, s[6:7]
	s_or_b32 s6, s0, 14
	s_ashr_i32 s7, s6, 31
	s_lshl_b64 s[6:7], s[6:7], 12
	v_lshl_add_u64 v[34:35], v[2:3], 0, s[6:7]
	s_or_b32 s6, s0, 16
	s_ashr_i32 s7, s6, 31
	s_lshl_b64 s[6:7], s[6:7], 12
	global_load_dword v18, v[20:21], off sc1 nt
	global_load_dword v19, v[22:23], off sc1 nt
	global_load_dword v16, v[24:25], off sc1 nt
	global_load_dword v17, v[26:27], off sc1 nt
	global_load_dword v14, v[28:29], off sc1 nt
	global_load_dword v15, v[30:31], off sc1 nt
	global_load_dword v12, v[32:33], off sc1 nt
	global_load_dword v13, v[34:35], off sc1 nt
	v_lshl_add_u64 v[28:29], v[2:3], 0, s[6:7]
	s_or_b32 s6, s0, 18
	s_ashr_i32 s7, s6, 31
	s_lshl_b64 s[6:7], s[6:7], 12
	v_lshl_add_u64 v[30:31], v[2:3], 0, s[6:7]
	s_or_b32 s6, s0, 20
	s_ashr_i32 s7, s6, 31
	s_lshl_b64 s[6:7], s[6:7], 12
	v_lshl_add_u64 v[32:33], v[2:3], 0, s[6:7]
	s_or_b32 s6, s0, 22
	s_ashr_i32 s7, s6, 31
	s_lshl_b64 s[6:7], s[6:7], 12
	v_lshl_add_u64 v[34:35], v[2:3], 0, s[6:7]
	s_or_b32 s6, s0, 24
	s_ashr_i32 s7, s6, 31
	s_lshl_b64 s[6:7], s[6:7], 12
	v_lshl_add_u64 v[36:37], v[2:3], 0, s[6:7]
	s_or_b32 s6, s0, 26
	s_ashr_i32 s7, s6, 31
	s_lshl_b64 s[6:7], s[6:7], 12
	v_lshl_add_u64 v[38:39], v[2:3], 0, s[6:7]
	s_or_b32 s6, s0, 28
	s_ashr_i32 s7, s6, 31
	s_lshl_b64 s[6:7], s[6:7], 12
	v_lshl_add_u64 v[40:41], v[2:3], 0, s[6:7]
	s_or_b32 s6, s0, 30
	s_ashr_i32 s7, s6, 31
	s_lshl_b64 s[6:7], s[6:7], 12
	v_lshl_add_u64 v[42:43], v[2:3], 0, s[6:7]
	s_or_b32 s6, s0, 32
	s_ashr_i32 s7, s6, 31
	s_lshl_b64 s[6:7], s[6:7], 12
	global_load_dword v26, v[28:29], off sc1 nt
	global_load_dword v27, v[30:31], off sc1 nt
	global_load_dword v24, v[32:33], off sc1 nt
	global_load_dword v25, v[34:35], off sc1 nt
	global_load_dword v22, v[36:37], off sc1 nt
	global_load_dword v23, v[38:39], off sc1 nt
	global_load_dword v20, v[40:41], off sc1 nt
	global_load_dword v21, v[42:43], off sc1 nt
	v_lshl_add_u64 v[36:37], v[2:3], 0, s[6:7]
	s_or_b32 s6, s0, 34
	s_ashr_i32 s7, s6, 31
	s_lshl_b64 s[6:7], s[6:7], 12
	v_lshl_add_u64 v[38:39], v[2:3], 0, s[6:7]
	s_or_b32 s6, s0, 36
	s_ashr_i32 s7, s6, 31
	s_lshl_b64 s[6:7], s[6:7], 12
	v_lshl_add_u64 v[40:41], v[2:3], 0, s[6:7]
	s_or_b32 s6, s0, 38
	s_ashr_i32 s7, s6, 31
	s_lshl_b64 s[6:7], s[6:7], 12
	v_lshl_add_u64 v[42:43], v[2:3], 0, s[6:7]
	s_or_b32 s6, s0, 40
	s_ashr_i32 s7, s6, 31
	s_lshl_b64 s[6:7], s[6:7], 12
	v_lshl_add_u64 v[44:45], v[2:3], 0, s[6:7]
	s_or_b32 s6, s0, 42
	s_ashr_i32 s7, s6, 31
	s_lshl_b64 s[6:7], s[6:7], 12
	v_lshl_add_u64 v[46:47], v[2:3], 0, s[6:7]
	s_or_b32 s6, s0, 44
	s_ashr_i32 s7, s6, 31
	s_lshl_b64 s[6:7], s[6:7], 12
	v_lshl_add_u64 v[48:49], v[2:3], 0, s[6:7]
	s_or_b32 s6, s0, 46
	s_ashr_i32 s7, s6, 31
	s_lshl_b64 s[6:7], s[6:7], 12
	v_lshl_add_u64 v[50:51], v[2:3], 0, s[6:7]
	s_or_b32 s6, s0, 48
	s_ashr_i32 s7, s6, 31
	s_lshl_b64 s[6:7], s[6:7], 12
	global_load_dword v34, v[36:37], off sc1 nt
	global_load_dword v35, v[38:39], off sc1 nt
	global_load_dword v32, v[40:41], off sc1 nt
	global_load_dword v33, v[42:43], off sc1 nt
	global_load_dword v30, v[44:45], off sc1 nt
	global_load_dword v31, v[46:47], off sc1 nt
	global_load_dword v28, v[48:49], off sc1 nt
	global_load_dword v29, v[50:51], off sc1 nt
	v_lshl_add_u64 v[44:45], v[2:3], 0, s[6:7]
	s_or_b32 s6, s0, 50
	s_ashr_i32 s7, s6, 31
	s_lshl_b64 s[6:7], s[6:7], 12
	v_lshl_add_u64 v[46:47], v[2:3], 0, s[6:7]
	s_or_b32 s6, s0, 52
	s_ashr_i32 s7, s6, 31
	s_lshl_b64 s[6:7], s[6:7], 12
	v_lshl_add_u64 v[48:49], v[2:3], 0, s[6:7]
	s_or_b32 s6, s0, 54
	s_ashr_i32 s7, s6, 31
	s_lshl_b64 s[6:7], s[6:7], 12
	v_lshl_add_u64 v[50:51], v[2:3], 0, s[6:7]
	s_or_b32 s6, s0, 56
	s_ashr_i32 s7, s6, 31
	s_lshl_b64 s[6:7], s[6:7], 12
	v_lshl_add_u64 v[52:53], v[2:3], 0, s[6:7]
	s_or_b32 s6, s0, 58
	s_ashr_i32 s7, s6, 31
	s_lshl_b64 s[6:7], s[6:7], 12
	v_lshl_add_u64 v[54:55], v[2:3], 0, s[6:7]
	s_or_b32 s6, s0, 60
	s_ashr_i32 s7, s6, 31
	s_lshl_b64 s[6:7], s[6:7], 12
	v_lshl_add_u64 v[56:57], v[2:3], 0, s[6:7]
	s_or_b32 s6, s0, 62
	s_ashr_i32 s7, s6, 31
	s_lshl_b64 s[6:7], s[6:7], 12
	v_lshl_add_u64 v[58:59], v[2:3], 0, s[6:7]
	global_load_dword v42, v[44:45], off sc1 nt
	global_load_dword v43, v[46:47], off sc1 nt
	global_load_dword v40, v[48:49], off sc1 nt
	global_load_dword v41, v[50:51], off sc1 nt
	global_load_dword v38, v[52:53], off sc1 nt
	global_load_dword v39, v[54:55], off sc1 nt
	global_load_dword v36, v[56:57], off sc1 nt
	global_load_dword v37, v[58:59], off sc1 nt
	s_andn2_b64 vcc, exec, s[2:3]
	s_cbranch_vccnz .LBB0_377
	v_lshl_add_u64 v[4:5], v[4:5], 2, s[4:5]
	global_load_dword v10, v[4:5], off offset:256 sc1 nt
.LBB0_377:
	s_or_b32 s2, s0, 64
	s_ashr_i32 s3, s2, 31
	s_lshl_b64 s[2:3], s[2:3], 12
	v_lshl_add_u64 v[4:5], v[2:3], 0, s[2:3]
	s_or_b32 s2, s0, 0x42
	s_ashr_i32 s3, s2, 31
	s_lshl_b64 s[2:3], s[2:3], 12
	v_lshl_add_u64 v[44:45], v[2:3], 0, s[2:3]
	s_or_b32 s2, s0, 0x44
	s_ashr_i32 s3, s2, 31
	s_lshl_b64 s[2:3], s[2:3], 12
	v_lshl_add_u64 v[46:47], v[2:3], 0, s[2:3]
	s_or_b32 s2, s0, 0x46
	s_ashr_i32 s3, s2, 31
	s_lshl_b64 s[2:3], s[2:3], 12
	v_lshl_add_u64 v[48:49], v[2:3], 0, s[2:3]
	s_or_b32 s2, s0, 0x48
	s_ashr_i32 s3, s2, 31
	s_lshl_b64 s[2:3], s[2:3], 12
	v_lshl_add_u64 v[50:51], v[2:3], 0, s[2:3]
	s_or_b32 s2, s0, 0x4a
	s_ashr_i32 s3, s2, 31
	s_lshl_b64 s[2:3], s[2:3], 12
	v_lshl_add_u64 v[52:53], v[2:3], 0, s[2:3]
	s_or_b32 s2, s0, 0x4c
	s_ashr_i32 s3, s2, 31
	s_lshl_b64 s[2:3], s[2:3], 12
	v_lshl_add_u64 v[54:55], v[2:3], 0, s[2:3]
	s_or_b32 s2, s0, 0x4e
	s_ashr_i32 s3, s2, 31
	s_lshl_b64 s[2:3], s[2:3], 12
	v_lshl_add_u64 v[56:57], v[2:3], 0, s[2:3]
	s_or_b32 s2, s0, 0x50
	s_ashr_i32 s3, s2, 31
	s_lshl_b64 s[2:3], s[2:3], 12
	global_load_dword v71, v[4:5], off sc1 nt
	global_load_dword v72, v[44:45], off sc1 nt
	global_load_dword v73, v[46:47], off sc1 nt
	global_load_dword v74, v[48:49], off sc1 nt
	global_load_dword v75, v[50:51], off sc1 nt
	global_load_dword v76, v[52:53], off sc1 nt
	global_load_dword v77, v[54:55], off sc1 nt
	global_load_dword v78, v[56:57], off sc1 nt
	v_lshl_add_u64 v[4:5], v[2:3], 0, s[2:3]
	s_or_b32 s2, s0, 0x52
	s_ashr_i32 s3, s2, 31
	s_lshl_b64 s[2:3], s[2:3], 12
	v_lshl_add_u64 v[44:45], v[2:3], 0, s[2:3]
	s_or_b32 s2, s0, 0x54
	s_ashr_i32 s3, s2, 31
	s_lshl_b64 s[2:3], s[2:3], 12
	v_lshl_add_u64 v[46:47], v[2:3], 0, s[2:3]
	s_or_b32 s2, s0, 0x56
	s_ashr_i32 s3, s2, 31
	s_lshl_b64 s[2:3], s[2:3], 12
	v_lshl_add_u64 v[48:49], v[2:3], 0, s[2:3]
	s_or_b32 s2, s0, 0x58
	s_ashr_i32 s3, s2, 31
	s_lshl_b64 s[2:3], s[2:3], 12
	v_lshl_add_u64 v[50:51], v[2:3], 0, s[2:3]
	s_or_b32 s2, s0, 0x5a
	s_ashr_i32 s3, s2, 31
	s_lshl_b64 s[2:3], s[2:3], 12
	v_lshl_add_u64 v[52:53], v[2:3], 0, s[2:3]
	s_or_b32 s2, s0, 0x5c
	s_ashr_i32 s3, s2, 31
	s_lshl_b64 s[2:3], s[2:3], 12
	v_lshl_add_u64 v[54:55], v[2:3], 0, s[2:3]
	s_or_b32 s2, s0, 0x5e
	s_ashr_i32 s3, s2, 31
	s_lshl_b64 s[2:3], s[2:3], 12
	v_lshl_add_u64 v[56:57], v[2:3], 0, s[2:3]
	s_or_b32 s2, s0, 0x60
	s_ashr_i32 s3, s2, 31
	s_lshl_b64 s[2:3], s[2:3], 12
	global_load_dword v79, v[4:5], off sc1 nt
	global_load_dword v80, v[44:45], off sc1 nt
	global_load_dword v81, v[46:47], off sc1 nt
	global_load_dword v82, v[48:49], off sc1 nt
	global_load_dword v83, v[50:51], off sc1 nt
	global_load_dword v84, v[52:53], off sc1 nt
	global_load_dword v85, v[54:55], off sc1 nt
	global_load_dword v86, v[56:57], off sc1 nt
	v_lshl_add_u64 v[4:5], v[2:3], 0, s[2:3]
	s_or_b32 s2, s0, 0x62
	s_ashr_i32 s3, s2, 31
	s_lshl_b64 s[2:3], s[2:3], 12
	v_lshl_add_u64 v[44:45], v[2:3], 0, s[2:3]
	s_or_b32 s2, s0, 0x64
	s_ashr_i32 s3, s2, 31
	s_lshl_b64 s[2:3], s[2:3], 12
	v_lshl_add_u64 v[46:47], v[2:3], 0, s[2:3]
	s_or_b32 s2, s0, 0x66
	s_ashr_i32 s3, s2, 31
	s_lshl_b64 s[2:3], s[2:3], 12
	v_lshl_add_u64 v[48:49], v[2:3], 0, s[2:3]
	s_or_b32 s2, s0, 0x68
	s_ashr_i32 s3, s2, 31
	s_lshl_b64 s[2:3], s[2:3], 12
	v_lshl_add_u64 v[50:51], v[2:3], 0, s[2:3]
	s_or_b32 s2, s0, 0x6a
	s_ashr_i32 s3, s2, 31
	s_lshl_b64 s[2:3], s[2:3], 12
	v_lshl_add_u64 v[52:53], v[2:3], 0, s[2:3]
	s_or_b32 s2, s0, 0x6c
	s_ashr_i32 s3, s2, 31
	s_lshl_b64 s[2:3], s[2:3], 12
	v_lshl_add_u64 v[54:55], v[2:3], 0, s[2:3]
	s_or_b32 s2, s0, 0x6e
	s_ashr_i32 s3, s2, 31
	s_lshl_b64 s[2:3], s[2:3], 12
	v_lshl_add_u64 v[56:57], v[2:3], 0, s[2:3]
	s_or_b32 s2, s0, 0x70
	s_ashr_i32 s3, s2, 31
	s_lshl_b64 s[2:3], s[2:3], 12
	global_load_dword v87, v[4:5], off sc1 nt
	global_load_dword v88, v[44:45], off sc1 nt
	global_load_dword v89, v[46:47], off sc1 nt
	global_load_dword v90, v[48:49], off sc1 nt
	global_load_dword v91, v[50:51], off sc1 nt
	global_load_dword v92, v[52:53], off sc1 nt
	global_load_dword v93, v[54:55], off sc1 nt
	global_load_dword v94, v[56:57], off sc1 nt
	v_lshl_add_u64 v[4:5], v[2:3], 0, s[2:3]
	s_or_b32 s2, s0, 0x72
	s_ashr_i32 s3, s2, 31
	s_lshl_b64 s[2:3], s[2:3], 12
	v_lshl_add_u64 v[44:45], v[2:3], 0, s[2:3]
	s_or_b32 s2, s0, 0x74
	s_ashr_i32 s3, s2, 31
	s_lshl_b64 s[2:3], s[2:3], 12
	v_lshl_add_u64 v[46:47], v[2:3], 0, s[2:3]
	s_or_b32 s2, s0, 0x76
	s_ashr_i32 s3, s2, 31
	s_lshl_b64 s[2:3], s[2:3], 12
	v_lshl_add_u64 v[48:49], v[2:3], 0, s[2:3]
	s_or_b32 s2, s0, 0x78
	s_ashr_i32 s3, s2, 31
	s_lshl_b64 s[2:3], s[2:3], 12
	v_lshl_add_u64 v[50:51], v[2:3], 0, s[2:3]
	s_or_b32 s2, s0, 0x7a
	s_ashr_i32 s3, s2, 31
	s_lshl_b64 s[2:3], s[2:3], 12
	v_lshl_add_u64 v[52:53], v[2:3], 0, s[2:3]
	s_or_b32 s2, s0, 0x7c
	s_ashr_i32 s3, s2, 31
	s_lshl_b64 s[2:3], s[2:3], 12
	v_lshl_add_u64 v[54:55], v[2:3], 0, s[2:3]
	s_or_b32 s2, s0, 0x7e
	s_ashr_i32 s3, s2, 31
	s_lshl_b64 s[2:3], s[2:3], 12
	v_lshlrev_b32_e32 v95, 2, v7
	v_lshl_add_u64 v[2:3], v[2:3], 0, s[2:3]
	s_waitcnt vmcnt(0)
	ds_bpermute_b32 v56, v95, v11
	ds_bpermute_b32 v57, v95, v11 offset:8
	global_load_dword v96, v[4:5], off sc1 nt
	global_load_dword v97, v[44:45], off sc1 nt
	global_load_dword v98, v[46:47], off sc1 nt
	global_load_dword v99, v[48:49], off sc1 nt
	global_load_dword v100, v[50:51], off sc1 nt
	global_load_dword v101, v[52:53], off sc1 nt
	global_load_dword v102, v[54:55], off sc1 nt
	global_load_dword v103, v[2:3], off sc1 nt
	ds_bpermute_b32 v2, v95, v11 offset:16
	ds_bpermute_b32 v3, v95, v11 offset:24
	s_waitcnt lgkmcnt(3)
	v_mul_f32_e32 v45, v18, v56
	s_waitcnt lgkmcnt(2)
	v_mul_f32_e32 v5, v19, v57
	v_max3_f32 v18, |v45|, 0, |v5|
	s_waitcnt lgkmcnt(1)
	v_mul_f32_e32 v4, v16, v2
	s_waitcnt lgkmcnt(0)
	v_mul_f32_e32 v3, v17, v3
	ds_bpermute_b32 v2, v95, v11 offset:32
	v_max3_f32 v17, v18, |v4|, |v3|
	ds_bpermute_b32 v18, v95, v11 offset:48
	ds_bpermute_b32 v19, v95, v11 offset:56
	ds_bpermute_b32 v16, v95, v11 offset:40
	s_waitcnt lgkmcnt(3)
	v_mul_f32_e32 v48, v14, v2
	ds_bpermute_b32 v14, v95, v11 offset:80
	s_waitcnt lgkmcnt(3)
	v_mul_f32_e32 v46, v12, v18
	s_waitcnt lgkmcnt(2)
	v_mul_f32_e32 v44, v13, v19
	ds_bpermute_b32 v12, v95, v11 offset:64
	ds_bpermute_b32 v13, v95, v11 offset:72
	s_waitcnt lgkmcnt(3)
	v_mul_f32_e32 v47, v15, v16
	ds_bpermute_b32 v15, v95, v11 offset:88
	s_waitcnt lgkmcnt(3)
	v_mul_f32_e32 v50, v24, v14
	s_waitcnt lgkmcnt(2)
	v_mul_f32_e32 v52, v26, v12
	s_waitcnt lgkmcnt(1)
	v_mul_f32_e32 v51, v27, v13
	ds_bpermute_b32 v12, v95, v11 offset:96
	ds_bpermute_b32 v13, v95, v11 offset:104
	ds_bpermute_b32 v14, v95, v11 offset:112
	s_waitcnt lgkmcnt(3)
	v_mul_f32_e32 v49, v25, v15
	ds_bpermute_b32 v15, v95, v11 offset:120
	s_waitcnt lgkmcnt(3)
	v_mul_f32_e32 v56, v22, v12
	s_waitcnt lgkmcnt(2)
	v_mul_f32_e32 v55, v23, v13
	s_waitcnt lgkmcnt(1)
	v_mul_f32_e32 v54, v20, v14
	ds_bpermute_b32 v12, v95, v11 offset:128
	ds_bpermute_b32 v13, v95, v11 offset:136
	ds_bpermute_b32 v14, v95, v11 offset:144
	s_waitcnt lgkmcnt(3)
	v_mul_f32_e32 v53, v21, v15
	ds_bpermute_b32 v15, v95, v11 offset:152
	s_waitcnt lgkmcnt(3)
	v_mul_f32_e32 v60, v34, v12
	s_waitcnt lgkmcnt(2)
	v_mul_f32_e32 v59, v35, v13
	s_waitcnt lgkmcnt(1)
	v_mul_f32_e32 v58, v32, v14
	ds_bpermute_b32 v12, v95, v11 offset:160
	ds_bpermute_b32 v13, v95, v11 offset:168
	ds_bpermute_b32 v14, v95, v11 offset:176
	s_waitcnt lgkmcnt(3)
	v_mul_f32_e32 v57, v33, v15
	ds_bpermute_b32 v15, v95, v11 offset:184
	s_waitcnt lgkmcnt(3)
	v_mul_f32_e32 v64, v30, v12
	s_waitcnt lgkmcnt(2)
	v_mul_f32_e32 v63, v31, v13
	s_waitcnt lgkmcnt(1)
	v_mul_f32_e32 v62, v28, v14
	ds_bpermute_b32 v12, v95, v11 offset:192
	ds_bpermute_b32 v13, v95, v11 offset:200
	ds_bpermute_b32 v14, v95, v11 offset:208
	s_waitcnt lgkmcnt(3)
	v_mul_f32_e32 v61, v29, v15
	ds_bpermute_b32 v15, v95, v11 offset:216
	s_waitcnt lgkmcnt(3)
	v_mul_f32_e32 v66, v42, v12
	s_waitcnt lgkmcnt(2)
	v_mul_f32_e32 v65, v43, v13
	s_waitcnt lgkmcnt(1)
	v_mul_f32_e32 v43, v40, v14
	ds_bpermute_b32 v12, v95, v11 offset:224
	ds_bpermute_b32 v13, v95, v11 offset:232
	ds_bpermute_b32 v14, v95, v11 offset:240
	ds_bpermute_b32 v11, v95, v11 offset:248
	s_waitcnt lgkmcnt(4)
	v_mul_f32_e32 v42, v41, v15
	s_waitcnt lgkmcnt(3)
	v_mul_f32_e32 v70, v38, v12
	ds_bpermute_b32 v12, v95, v10 offset:8
	ds_bpermute_b32 v15, v95, v10 offset:16
	s_waitcnt lgkmcnt(2)
	v_mul_f32_e32 v67, v37, v11
	ds_bpermute_b32 v11, v95, v10
	ds_bpermute_b32 v16, v95, v10 offset:24
	v_mul_f32_e32 v69, v39, v13
	v_mul_f32_e32 v68, v36, v14
	s_waitcnt lgkmcnt(3)
	v_mul_f32_e32 v13, v72, v12
	s_waitcnt lgkmcnt(1)
	v_mul_f32_e32 v14, v71, v11
	v_mul_f32_e32 v12, v73, v15
	s_waitcnt lgkmcnt(0)
	v_mul_f32_e32 v11, v74, v16
	ds_bpermute_b32 v15, v95, v10 offset:32
	ds_bpermute_b32 v16, v95, v10 offset:40
	ds_bpermute_b32 v19, v95, v10 offset:48
	ds_bpermute_b32 v20, v95, v10 offset:56
	v_max3_f32 v2, v17, |v48|, |v47|
	s_waitcnt lgkmcnt(3)
	v_mul_f32_e32 v18, v75, v15
	s_waitcnt lgkmcnt(2)
	v_mul_f32_e32 v17, v76, v16
	s_waitcnt lgkmcnt(1)
	v_mul_f32_e32 v16, v77, v19
	s_waitcnt lgkmcnt(0)
	v_mul_f32_e32 v15, v78, v20
	ds_bpermute_b32 v19, v95, v10 offset:64
	ds_bpermute_b32 v20, v95, v10 offset:72
	ds_bpermute_b32 v23, v95, v10 offset:80
	ds_bpermute_b32 v24, v95, v10 offset:88
	v_max3_f32 v2, v2, |v46|, |v44|
	v_max3_f32 v2, v2, |v52|, |v51|
	s_waitcnt lgkmcnt(3)
	v_mul_f32_e32 v22, v79, v19
	s_waitcnt lgkmcnt(2)
	v_mul_f32_e32 v21, v80, v20
	s_waitcnt lgkmcnt(1)
	v_mul_f32_e32 v20, v81, v23
	s_waitcnt lgkmcnt(0)
	v_mul_f32_e32 v19, v82, v24
	ds_bpermute_b32 v23, v95, v10 offset:96
	ds_bpermute_b32 v24, v95, v10 offset:104
	ds_bpermute_b32 v27, v95, v10 offset:112
	ds_bpermute_b32 v28, v95, v10 offset:120
	v_max3_f32 v2, v2, |v50|, |v49|
	v_max3_f32 v2, v2, |v56|, |v55|
	v_max3_f32 v2, v2, |v54|, |v53|
	v_max3_f32 v2, v2, |v60|, |v59|
	v_max3_f32 v2, v2, |v58|, |v57|
	s_waitcnt lgkmcnt(3)
	v_mul_f32_e32 v26, v83, v23
	s_waitcnt lgkmcnt(2)
	v_mul_f32_e32 v25, v84, v24
	s_waitcnt lgkmcnt(1)
	v_mul_f32_e32 v24, v85, v27
	s_waitcnt lgkmcnt(0)
	v_mul_f32_e32 v23, v86, v28
	ds_bpermute_b32 v27, v95, v10 offset:128
	ds_bpermute_b32 v28, v95, v10 offset:136
	ds_bpermute_b32 v31, v95, v10 offset:144
	ds_bpermute_b32 v32, v95, v10 offset:152
	v_max3_f32 v2, v2, |v64|, |v63|
	v_max3_f32 v2, v2, |v62|, |v61|
	v_max3_f32 v2, v2, |v66|, |v65|
	v_max3_f32 v2, v2, |v43|, |v42|
	v_max3_f32 v2, v2, |v70|, |v69|
	s_waitcnt lgkmcnt(3)
	v_mul_f32_e32 v30, v87, v27
	s_waitcnt lgkmcnt(2)
	v_mul_f32_e32 v29, v88, v28
	s_waitcnt lgkmcnt(1)
	v_mul_f32_e32 v28, v89, v31
	s_waitcnt lgkmcnt(0)
	v_mul_f32_e32 v27, v90, v32
	ds_bpermute_b32 v31, v95, v10 offset:160
	ds_bpermute_b32 v32, v95, v10 offset:168
	ds_bpermute_b32 v35, v95, v10 offset:176
	ds_bpermute_b32 v36, v95, v10 offset:184
	v_max3_f32 v2, v2, |v68|, |v67|
	v_max3_f32 v2, v2, |v14|, |v13|
	v_max3_f32 v2, v2, |v12|, |v11|
	v_max3_f32 v2, v2, |v18|, |v17|
	v_max3_f32 v2, v2, |v16|, |v15|
	s_waitcnt lgkmcnt(3)
	v_mul_f32_e32 v34, v91, v31
	s_waitcnt lgkmcnt(2)
	v_mul_f32_e32 v33, v92, v32
	s_waitcnt lgkmcnt(1)
	v_mul_f32_e32 v32, v93, v35
	s_waitcnt lgkmcnt(0)
	v_mul_f32_e32 v31, v94, v36
	ds_bpermute_b32 v35, v95, v10 offset:192
	ds_bpermute_b32 v36, v95, v10 offset:200
	ds_bpermute_b32 v39, v95, v10 offset:208
	ds_bpermute_b32 v40, v95, v10 offset:216
	v_max3_f32 v2, v2, |v22|, |v21|
	v_max3_f32 v2, v2, |v20|, |v19|
	v_max3_f32 v2, v2, |v26|, |v25|
	v_max3_f32 v2, v2, |v24|, |v23|
	v_max3_f32 v2, v2, |v30|, |v29|
	s_waitcnt vmcnt(7) lgkmcnt(3)
	v_mul_f32_e32 v38, v96, v35
	s_waitcnt vmcnt(6) lgkmcnt(2)
	v_mul_f32_e32 v37, v97, v36
	s_waitcnt vmcnt(5) lgkmcnt(1)
	v_mul_f32_e32 v36, v98, v39
	s_waitcnt vmcnt(4) lgkmcnt(0)
	v_mul_f32_e32 v35, v99, v40
	ds_bpermute_b32 v39, v95, v10 offset:224
	ds_bpermute_b32 v40, v95, v10 offset:232
	v_max3_f32 v2, v2, |v28|, |v27|
	ds_bpermute_b32 v71, v95, v10 offset:240
	ds_bpermute_b32 v10, v95, v10 offset:248
	v_max3_f32 v2, v2, |v34|, |v33|
	v_max3_f32 v2, v2, |v32|, |v31|
	v_max3_f32 v2, v2, |v38|, |v37|
	v_max3_f32 v2, v2, |v36|, |v35|
	s_waitcnt vmcnt(3) lgkmcnt(3)
	v_mul_f32_e32 v41, v100, v39
	s_waitcnt vmcnt(2) lgkmcnt(2)
	v_mul_f32_e32 v40, v101, v40
	v_max3_f32 v2, v2, |v41|, |v40|
	s_waitcnt vmcnt(1) lgkmcnt(1)
	v_mul_f32_e32 v39, v102, v71
	s_waitcnt vmcnt(0) lgkmcnt(0)
	v_mul_f32_e32 v10, v103, v10
	v_max3_f32 v2, v2, |v39|, |v10|
	v_mov_b32_e32 v71, v2
	s_lshl_b32 s4, s13, 5
	s_nop 0
	v_permlane32_swap_b32_e32 v2, v71
	v_cmp_gt_u32_e32 vcc, 32, v6
	s_and_saveexec_b64 s[2:3], vcc
	s_cbranch_execz .LBB0_379
	v_max_f32_e32 v2, v2, v2
	v_max_f32_e32 v71, v71, v71
	s_add_i32 s5, s0, 0
	v_max_f32_e32 v2, v2, v71
	v_lshl_add_u32 v71, v6, 2, s5
	v_add_u32_e32 v71, 0x20000, v71
	ds_write_b32 v71, v2

.LBB0_388:
	s_ashr_i32 s4, s0, 31
	s_lshr_b32 s4, s4, 27
	s_add_i32 s4, s0, s4
	s_ashr_i32 s4, s4, 5
	s_lshl_b32 s6, s4, 6
	s_lshl_b32 s7, s4, 10
	s_mul_i32 s4, s4, 0xffd40000
	v_or_b32_e32 v18, s6, v7
	s_sub_i32 s8, s1, s7
	s_ashr_i32 s7, s6, 31
	v_add_u32_e32 v20, s4, v9
	v_or_b32_e32 v22, 2, v18
	v_or_b32_e32 v24, 4, v18
	v_or_b32_e32 v26, 6, v18
	v_or_b32_e32 v28, 8, v18
	v_or_b32_e32 v30, 10, v18
	v_or_b32_e32 v32, 12, v18
	v_or_b32_e32 v34, 14, v18
	v_or_b32_e32 v36, 16, v18
	s_ashr_i32 s9, s8, 31
	v_ashrrev_i32_e32 v19, 31, v18
	v_or_b32_e32 v38, 18, v18
	v_or_b32_e32 v40, 20, v18
	v_or_b32_e32 v42, 22, v18
	v_or_b32_e32 v44, 24, v18
	v_or_b32_e32 v46, 26, v18
	v_or_b32_e32 v48, 28, v18
	v_or_b32_e32 v50, 30, v18
	v_or_b32_e32 v52, 32, v18
	v_or_b32_e32 v54, 34, v18
	v_or_b32_e32 v56, 36, v18
	v_or_b32_e32 v58, 38, v18
	v_or_b32_e32 v60, 40, v18
	v_or_b32_e32 v62, 42, v18
	v_or_b32_e32 v64, 44, v18
	v_or_b32_e32 v66, 46, v18
	v_or_b32_e32 v68, 48, v18
	v_or_b32_e32 v70, 50, v18
	v_or_b32_e32 v72, 52, v18
	v_or_b32_e32 v74, 54, v18
	v_or_b32_e32 v76, 56, v18
	v_or_b32_e32 v78, 58, v18
	v_or_b32_e32 v80, 60, v18
	v_or_b32_e32 v82, 62, v18
	v_lshl_add_u64 v[84:85], s[6:7], 1, v[4:5]
	v_ashrrev_i32_e32 v21, 31, v20
	v_ashrrev_i32_e32 v23, 31, v22
	v_ashrrev_i32_e32 v25, 31, v24
	v_ashrrev_i32_e32 v27, 31, v26
	v_ashrrev_i32_e32 v29, 31, v28
	v_ashrrev_i32_e32 v31, 31, v30
	v_ashrrev_i32_e32 v33, 31, v32
	v_ashrrev_i32_e32 v35, 31, v34
	v_ashrrev_i32_e32 v37, 31, v36
	v_add_u32_e32 v86, 0x5800, v20
	v_add_u32_e32 v88, 0xb000, v20
	v_add_u32_e32 v90, 0x10800, v20
	v_lshl_add_u64 v[92:93], s[8:9], 2, v[2:3]
	v_lshlrev_b64 v[18:19], 12, v[18:19]
	v_ashrrev_i32_e32 v39, 31, v38
	v_ashrrev_i32_e32 v41, 31, v40
	v_ashrrev_i32_e32 v43, 31, v42
	v_ashrrev_i32_e32 v45, 31, v44
	v_ashrrev_i32_e32 v47, 31, v46
	v_ashrrev_i32_e32 v49, 31, v48
	v_ashrrev_i32_e32 v51, 31, v50
	v_ashrrev_i32_e32 v53, 31, v52
	v_ashrrev_i32_e32 v55, 31, v54
	v_ashrrev_i32_e32 v57, 31, v56
	v_ashrrev_i32_e32 v59, 31, v58
	v_ashrrev_i32_e32 v61, 31, v60
	v_ashrrev_i32_e32 v63, 31, v62
	v_ashrrev_i32_e32 v65, 31, v64
	v_ashrrev_i32_e32 v67, 31, v66
	v_ashrrev_i32_e32 v69, 31, v68
	v_ashrrev_i32_e32 v71, 31, v70
	v_ashrrev_i32_e32 v73, 31, v72
	v_ashrrev_i32_e32 v75, 31, v74
	v_ashrrev_i32_e32 v77, 31, v76
	v_ashrrev_i32_e32 v79, 31, v78
	v_ashrrev_i32_e32 v81, 31, v80
	v_ashrrev_i32_e32 v83, 31, v82
	v_lshl_add_u64 v[94:95], v[20:21], 1, v[84:85]
	v_lshlrev_b64 v[20:21], 12, v[22:23]
	v_lshlrev_b64 v[22:23], 12, v[24:25]
	v_lshlrev_b64 v[24:25], 12, v[26:27]
	v_lshlrev_b64 v[26:27], 12, v[28:29]
	v_lshlrev_b64 v[28:29], 12, v[30:31]
	v_lshlrev_b64 v[30:31], 12, v[32:33]
	v_lshlrev_b64 v[32:33], 12, v[34:35]
	v_lshlrev_b64 v[34:35], 12, v[36:37]
	v_ashrrev_i32_e32 v87, 31, v86
	v_ashrrev_i32_e32 v89, 31, v88
	v_ashrrev_i32_e32 v91, 31, v90
	v_lshl_add_u64 v[18:19], v[92:93], 0, v[18:19]
	v_lshlrev_b64 v[36:37], 12, v[38:39]
	v_lshlrev_b64 v[38:39], 12, v[40:41]
	v_lshlrev_b64 v[40:41], 12, v[42:43]
	v_lshlrev_b64 v[42:43], 12, v[44:45]
	v_lshlrev_b64 v[44:45], 12, v[46:47]
	v_lshlrev_b64 v[46:47], 12, v[48:49]
	v_lshlrev_b64 v[48:49], 12, v[50:51]
	v_lshlrev_b64 v[50:51], 12, v[52:53]
	v_lshlrev_b64 v[52:53], 12, v[54:55]
	v_lshlrev_b64 v[54:55], 12, v[56:57]
	v_lshlrev_b64 v[56:57], 12, v[58:59]
	v_lshlrev_b64 v[58:59], 12, v[60:61]
	v_lshlrev_b64 v[60:61], 12, v[62:63]
	v_lshlrev_b64 v[62:63], 12, v[64:65]
	v_lshlrev_b64 v[64:65], 12, v[66:67]
	v_lshlrev_b64 v[66:67], 12, v[68:69]
	v_lshlrev_b64 v[68:69], 12, v[70:71]
	v_lshlrev_b64 v[70:71], 12, v[72:73]
	v_lshlrev_b64 v[72:73], 12, v[74:75]
	v_lshlrev_b64 v[74:75], 12, v[76:77]
	v_lshlrev_b64 v[76:77], 12, v[78:79]
	v_lshlrev_b64 v[78:79], 12, v[80:81]
	v_lshlrev_b64 v[80:81], 12, v[82:83]
	v_lshl_add_u64 v[20:21], v[92:93], 0, v[20:21]
	v_lshl_add_u64 v[22:23], v[92:93], 0, v[22:23]
	v_lshl_add_u64 v[24:25], v[92:93], 0, v[24:25]
	v_lshl_add_u64 v[26:27], v[92:93], 0, v[26:27]
	v_lshl_add_u64 v[28:29], v[92:93], 0, v[28:29]
	v_lshl_add_u64 v[30:31], v[92:93], 0, v[30:31]
	v_lshl_add_u64 v[32:33], v[92:93], 0, v[32:33]
	v_lshl_add_u64 v[34:35], v[92:93], 0, v[34:35]
	v_lshl_add_u64 v[82:83], v[86:87], 1, v[84:85]
	v_lshl_add_u64 v[86:87], v[88:89], 1, v[84:85]
	v_lshl_add_u64 v[84:85], v[90:91], 1, v[84:85]
	v_lshl_add_u64 v[36:37], v[92:93], 0, v[36:37]
	v_lshl_add_u64 v[38:39], v[92:93], 0, v[38:39]
	v_lshl_add_u64 v[40:41], v[92:93], 0, v[40:41]
	v_lshl_add_u64 v[42:43], v[92:93], 0, v[42:43]
	v_lshl_add_u64 v[44:45], v[92:93], 0, v[44:45]
	v_lshl_add_u64 v[46:47], v[92:93], 0, v[46:47]
	v_lshl_add_u64 v[48:49], v[92:93], 0, v[48:49]
	v_lshl_add_u64 v[50:51], v[92:93], 0, v[50:51]
	v_lshl_add_u64 v[52:53], v[92:93], 0, v[52:53]
	v_lshl_add_u64 v[54:55], v[92:93], 0, v[54:55]
	v_lshl_add_u64 v[56:57], v[92:93], 0, v[56:57]
	v_lshl_add_u64 v[58:59], v[92:93], 0, v[58:59]
	v_lshl_add_u64 v[60:61], v[92:93], 0, v[60:61]
	v_lshl_add_u64 v[62:63], v[92:93], 0, v[62:63]
	v_lshl_add_u64 v[64:65], v[92:93], 0, v[64:65]
	v_lshl_add_u64 v[66:67], v[92:93], 0, v[66:67]
	v_lshl_add_u64 v[68:69], v[92:93], 0, v[68:69]
	v_lshl_add_u64 v[70:71], v[92:93], 0, v[70:71]
	v_lshl_add_u64 v[72:73], v[92:93], 0, v[72:73]
	v_lshl_add_u64 v[74:75], v[92:93], 0, v[74:75]
	v_lshl_add_u64 v[76:77], v[92:93], 0, v[76:77]
	v_lshl_add_u64 v[78:79], v[92:93], 0, v[78:79]
	v_lshl_add_u64 v[80:81], v[92:93], 0, v[80:81]
	global_load_dword v88, v[18:19], off sc1 nt
	global_load_dword v89, v[20:21], off sc1 nt
	global_load_dword v90, v[22:23], off sc1 nt
	global_load_dword v91, v[24:25], off sc1 nt
	global_load_dword v92, v[26:27], off sc1 nt
	global_load_dword v93, v[28:29], off sc1 nt
	global_load_dword v96, v[30:31], off sc1 nt
	global_load_dword v97, v[32:33], off sc1 nt
	global_load_dword v98, v[34:35], off sc1 nt
	global_load_dword v99, v[36:37], off sc1 nt
	global_load_dword v100, v[38:39], off sc1 nt
	global_load_dword v101, v[40:41], off sc1 nt
	global_load_dword v102, v[42:43], off sc1 nt
	global_load_dword v103, v[44:45], off sc1 nt
	global_load_dword v104, v[46:47], off sc1 nt
	global_load_dword v18, v[48:49], off sc1 nt
	global_load_dword v19, v[50:51], off sc1 nt
	global_load_dword v20, v[52:53], off sc1 nt
	global_load_dword v21, v[54:55], off sc1 nt
	global_load_dword v22, v[56:57], off sc1 nt
	global_load_dword v23, v[58:59], off sc1 nt
	global_load_dword v24, v[60:61], off sc1 nt
	global_load_dword v25, v[62:63], off sc1 nt
	global_load_dword v26, v[64:65], off sc1 nt
	global_load_dword v27, v[66:67], off sc1 nt
	global_load_dword v28, v[68:69], off sc1 nt
	global_load_dword v29, v[70:71], off sc1 nt
	global_load_dword v30, v[72:73], off sc1 nt
	global_load_dword v31, v[74:75], off sc1 nt
	global_load_dword v32, v[76:77], off sc1 nt
	global_load_dword v33, v[78:79], off sc1 nt
	global_load_dword v34, v[80:81], off sc1 nt
	s_waitcnt vmcnt(0)
	ds_write2_b32 v10, v88, v89 offset1:66
	ds_write2_b32 v10, v90, v91 offset0:132 offset1:198
	ds_write2_b32 v11, v92, v93 offset0:8 offset1:74
	ds_write2_b32 v11, v96, v97 offset0:140 offset1:206
	ds_write2_b32 v12, v98, v99 offset0:16 offset1:82
	ds_write2_b32 v12, v100, v101 offset0:148 offset1:214
	ds_write2_b32 v13, v102, v103 offset0:24 offset1:90
	ds_write2_b32 v13, v104, v18 offset0:156 offset1:222
	ds_write2_b32 v14, v19, v20 offset0:32 offset1:98
	ds_write2_b32 v14, v21, v22 offset0:164 offset1:230
	ds_write2_b32 v15, v23, v24 offset0:40 offset1:106
	ds_write2_b32 v15, v25, v26 offset0:172 offset1:238
	ds_write2_b32 v16, v27, v28 offset0:48 offset1:114
	ds_write2_b32 v16, v29, v30 offset0:180 offset1:246
	ds_write2_b32 v17, v31, v32 offset0:56 offset1:122
	ds_write2_b32 v17, v33, v34 offset0:188 offset1:254
	s_waitcnt lgkmcnt(0)
	ds_read2_b32 v[18:19], v8 offset1:33
	ds_read2_b32 v[20:21], v8 offset0:66 offset1:99
	ds_read2_b32 v[22:23], v8 offset0:132 offset1:165
	ds_read2_b32 v[24:25], v8 offset0:198 offset1:231
	s_add_i32 s5, s0, 0x200
	s_waitcnt lgkmcnt(3)
	v_bfe_u32 v26, v18, 16, 1
	s_waitcnt lgkmcnt(2)
	v_bfe_u32 v28, v20, 16, 1
	s_waitcnt lgkmcnt(1)
	v_bfe_u32 v30, v22, 16, 1
	s_waitcnt lgkmcnt(0)
	v_bfe_u32 v32, v24, 16, 1
	v_bfe_u32 v27, v19, 16, 1
	v_bfe_u32 v29, v21, 16, 1
	v_bfe_u32 v31, v23, 16, 1
	v_bfe_u32 v33, v25, 16, 1
	v_add3_u32 v18, v18, v26, s2
	v_add3_u32 v20, v20, v28, s2
	v_add3_u32 v22, v22, v30, s2
	v_add3_u32 v24, v24, v32, s2
	v_add3_u32 v19, v19, v27, s2
	v_add3_u32 v21, v21, v29, s2
	v_add3_u32 v23, v23, v31, s2
	v_add3_u32 v25, v25, v33, s2
	v_lshrrev_b32_e32 v18, 16, v18
	v_lshrrev_b32_e32 v20, 16, v20
	v_lshrrev_b32_e32 v22, 16, v22
	v_lshrrev_b32_e32 v24, 16, v24
	v_and_or_b32 v18, v19, s3, v18
	v_and_or_b32 v19, v21, s3, v20
	v_and_or_b32 v20, v23, s3, v22
	v_and_or_b32 v21, v25, s3, v24
	global_store_dwordx4 v[94:95], v[18:21], off sc1
	s_nop 1
	ds_read2_b32 v[18:19], v8 offset0:8 offset1:41
	ds_read2_b32 v[20:21], v8 offset0:74 offset1:107
	ds_read2_b32 v[22:23], v8 offset0:140 offset1:173
	ds_read2_b32 v[24:25], v8 offset0:206 offset1:239
	s_addk_i32 s1, 0x4000
	s_waitcnt lgkmcnt(3)
	v_bfe_u32 v26, v18, 16, 1
	s_waitcnt lgkmcnt(2)
	v_bfe_u32 v28, v20, 16, 1
	s_waitcnt lgkmcnt(1)
	v_bfe_u32 v30, v22, 16, 1
	s_waitcnt lgkmcnt(0)
	v_bfe_u32 v32, v24, 16, 1
	v_bfe_u32 v27, v19, 16, 1
	v_bfe_u32 v29, v21, 16, 1
	v_bfe_u32 v31, v23, 16, 1
	v_bfe_u32 v33, v25, 16, 1
	v_add3_u32 v18, v18, v26, s2
	v_add3_u32 v20, v20, v28, s2
	v_add3_u32 v22, v22, v30, s2
	v_add3_u32 v24, v24, v32, s2
	v_add3_u32 v19, v19, v27, s2
	v_add3_u32 v21, v21, v29, s2
	v_add3_u32 v23, v23, v31, s2
	v_add3_u32 v25, v25, v33, s2
	v_lshrrev_b32_e32 v18, 16, v18
	v_lshrrev_b32_e32 v20, 16, v20
	v_lshrrev_b32_e32 v22, 16, v22
	v_lshrrev_b32_e32 v24, 16, v24
	v_and_or_b32 v18, v19, s3, v18
	v_and_or_b32 v19, v21, s3, v20
	v_and_or_b32 v20, v23, s3, v22
	v_and_or_b32 v21, v25, s3, v24
	global_store_dwordx4 v[82:83], v[18:21], off sc1
	s_nop 1
	ds_read2_b32 v[18:19], v8 offset0:16 offset1:49
	ds_read2_b32 v[20:21], v8 offset0:82 offset1:115
	ds_read2_b32 v[22:23], v8 offset0:148 offset1:181
	ds_read2_b32 v[24:25], v8 offset0:214 offset1:247
	v_add_u32_e32 v9, 0x2c00000, v9
	s_waitcnt lgkmcnt(3)
	v_bfe_u32 v26, v18, 16, 1
	s_waitcnt lgkmcnt(2)
	v_bfe_u32 v28, v20, 16, 1
	s_waitcnt lgkmcnt(1)
	v_bfe_u32 v30, v22, 16, 1
	s_waitcnt lgkmcnt(0)
	v_bfe_u32 v32, v24, 16, 1
	v_bfe_u32 v27, v19, 16, 1
	v_bfe_u32 v29, v21, 16, 1
	v_bfe_u32 v31, v23, 16, 1
	v_bfe_u32 v33, v25, 16, 1
	v_add3_u32 v18, v18, v26, s2
	v_add3_u32 v20, v20, v28, s2
	v_add3_u32 v22, v22, v30, s2
	v_add3_u32 v24, v24, v32, s2
	v_add3_u32 v19, v19, v27, s2
	v_add3_u32 v21, v21, v29, s2
	v_add3_u32 v23, v23, v31, s2
	v_add3_u32 v25, v25, v33, s2
	v_lshrrev_b32_e32 v18, 16, v18
	v_lshrrev_b32_e32 v20, 16, v20
	v_lshrrev_b32_e32 v22, 16, v22
	v_lshrrev_b32_e32 v24, 16, v24
	v_and_or_b32 v18, v19, s3, v18
	v_and_or_b32 v19, v21, s3, v20
	v_and_or_b32 v20, v23, s3, v22
	v_and_or_b32 v21, v25, s3, v24
	global_store_dwordx4 v[86:87], v[18:21], off sc1
	s_nop 1
	ds_read2_b32 v[18:19], v8 offset0:24 offset1:57
	ds_read2_b32 v[20:21], v8 offset0:90 offset1:123
	ds_read2_b32 v[22:23], v8 offset0:156 offset1:189
	ds_read2_b32 v[24:25], v8 offset0:222 offset1:255
	s_cmpk_gt_i32 s0, 0x37f
	s_waitcnt lgkmcnt(3)
	v_bfe_u32 v26, v18, 16, 1
	s_waitcnt lgkmcnt(2)
	v_bfe_u32 v28, v20, 16, 1
	s_waitcnt lgkmcnt(1)
	v_bfe_u32 v30, v22, 16, 1
	s_waitcnt lgkmcnt(0)
	v_bfe_u32 v32, v24, 16, 1
	v_bfe_u32 v27, v19, 16, 1
	v_bfe_u32 v29, v21, 16, 1
	v_bfe_u32 v31, v23, 16, 1
	v_bfe_u32 v33, v25, 16, 1
	v_add3_u32 v18, v18, v26, s2
	v_add3_u32 v20, v20, v28, s2
	v_add3_u32 v22, v22, v30, s2
	v_add3_u32 v24, v24, v32, s2
	v_add3_u32 v19, v19, v27, s2
	v_add3_u32 v21, v21, v29, s2
	v_add3_u32 v23, v23, v31, s2
	v_add3_u32 v25, v25, v33, s2
	v_lshrrev_b32_e32 v18, 16, v18
	v_lshrrev_b32_e32 v20, 16, v20
	v_lshrrev_b32_e32 v22, 16, v22
	v_lshrrev_b32_e32 v24, 16, v24
	v_and_or_b32 v18, v19, s3, v18
	v_and_or_b32 v19, v21, s3, v20
	v_and_or_b32 v20, v23, s3, v22
	v_and_or_b32 v21, v25, s3, v24
	global_store_dwordx4 v[84:85], v[18:21], off sc1
	s_nop 1
	s_waitcnt lgkmcnt(0)
	s_mov_b32 s0, s5
	s_cbranch_scc0 .LBB0_388

.LBB0_392:
	s_ashr_i32 s4, s0, 31
	s_lshr_b32 s4, s4, 27
	s_add_i32 s4, s0, s4
	s_ashr_i32 s4, s4, 5
	s_lshl_b32 s6, s4, 6
	s_lshl_b32 s7, s4, 10
	s_mul_i32 s4, s4, 0xffd40000
	v_or_b32_e32 v18, s6, v7
	s_sub_i32 s8, s1, s7
	s_ashr_i32 s7, s6, 31
	v_add_u32_e32 v20, s4, v8
	v_or_b32_e32 v22, 2, v18
	v_or_b32_e32 v24, 4, v18
	v_or_b32_e32 v26, 6, v18
	v_or_b32_e32 v28, 8, v18
	v_or_b32_e32 v30, 10, v18
	v_or_b32_e32 v32, 12, v18
	v_or_b32_e32 v34, 14, v18
	v_or_b32_e32 v36, 16, v18
	s_ashr_i32 s9, s8, 31
	v_ashrrev_i32_e32 v19, 31, v18
	v_or_b32_e32 v38, 18, v18
	v_or_b32_e32 v40, 20, v18
	v_or_b32_e32 v42, 22, v18
	v_or_b32_e32 v44, 24, v18
	v_or_b32_e32 v46, 26, v18
	v_or_b32_e32 v48, 28, v18
	v_or_b32_e32 v50, 30, v18
	v_or_b32_e32 v52, 32, v18
	v_or_b32_e32 v54, 34, v18
	v_or_b32_e32 v56, 36, v18
	v_or_b32_e32 v58, 38, v18
	v_or_b32_e32 v60, 40, v18
	v_or_b32_e32 v62, 42, v18
	v_or_b32_e32 v64, 44, v18
	v_or_b32_e32 v66, 46, v18
	v_or_b32_e32 v68, 48, v18
	v_or_b32_e32 v70, 50, v18
	v_or_b32_e32 v72, 52, v18
	v_or_b32_e32 v74, 54, v18
	v_or_b32_e32 v76, 56, v18
	v_or_b32_e32 v78, 58, v18
	v_or_b32_e32 v80, 60, v18
	v_or_b32_e32 v82, 62, v18
	v_lshl_add_u64 v[84:85], s[6:7], 1, v[4:5]
	v_ashrrev_i32_e32 v21, 31, v20
	v_ashrrev_i32_e32 v23, 31, v22
	v_ashrrev_i32_e32 v25, 31, v24
	v_ashrrev_i32_e32 v27, 31, v26
	v_ashrrev_i32_e32 v29, 31, v28
	v_ashrrev_i32_e32 v31, 31, v30
	v_ashrrev_i32_e32 v33, 31, v32
	v_ashrrev_i32_e32 v35, 31, v34
	v_ashrrev_i32_e32 v37, 31, v36
	v_add_u32_e32 v86, 0x5800, v20
	v_add_u32_e32 v88, 0xb000, v20
	v_add_u32_e32 v90, 0x10800, v20
	v_lshl_add_u64 v[92:93], s[8:9], 2, v[2:3]
	v_lshlrev_b64 v[18:19], 12, v[18:19]
	v_ashrrev_i32_e32 v39, 31, v38
	v_ashrrev_i32_e32 v41, 31, v40
	v_ashrrev_i32_e32 v43, 31, v42
	v_ashrrev_i32_e32 v45, 31, v44
	v_ashrrev_i32_e32 v47, 31, v46
	v_ashrrev_i32_e32 v49, 31, v48
	v_ashrrev_i32_e32 v51, 31, v50
	v_ashrrev_i32_e32 v53, 31, v52
	v_ashrrev_i32_e32 v55, 31, v54
	v_ashrrev_i32_e32 v57, 31, v56
	v_ashrrev_i32_e32 v59, 31, v58
	v_ashrrev_i32_e32 v61, 31, v60
	v_ashrrev_i32_e32 v63, 31, v62
	v_ashrrev_i32_e32 v65, 31, v64
	v_ashrrev_i32_e32 v67, 31, v66
	v_ashrrev_i32_e32 v69, 31, v68
	v_ashrrev_i32_e32 v71, 31, v70
	v_ashrrev_i32_e32 v73, 31, v72
	v_ashrrev_i32_e32 v75, 31, v74
	v_ashrrev_i32_e32 v77, 31, v76
	v_ashrrev_i32_e32 v79, 31, v78
	v_ashrrev_i32_e32 v81, 31, v80
	v_ashrrev_i32_e32 v83, 31, v82
	v_lshl_add_u64 v[94:95], v[20:21], 1, v[84:85]
	v_lshlrev_b64 v[20:21], 12, v[22:23]
	v_lshlrev_b64 v[22:23], 12, v[24:25]
	v_lshlrev_b64 v[24:25], 12, v[26:27]
	v_lshlrev_b64 v[26:27], 12, v[28:29]
	v_lshlrev_b64 v[28:29], 12, v[30:31]
	v_lshlrev_b64 v[30:31], 12, v[32:33]
	v_lshlrev_b64 v[32:33], 12, v[34:35]
	v_lshlrev_b64 v[34:35], 12, v[36:37]
	v_ashrrev_i32_e32 v87, 31, v86
	v_ashrrev_i32_e32 v89, 31, v88
	v_ashrrev_i32_e32 v91, 31, v90
	v_lshl_add_u64 v[18:19], v[92:93], 0, v[18:19]
	v_lshlrev_b64 v[36:37], 12, v[38:39]
	v_lshlrev_b64 v[38:39], 12, v[40:41]
	v_lshlrev_b64 v[40:41], 12, v[42:43]
	v_lshlrev_b64 v[42:43], 12, v[44:45]
	v_lshlrev_b64 v[44:45], 12, v[46:47]
	v_lshlrev_b64 v[46:47], 12, v[48:49]
	v_lshlrev_b64 v[48:49], 12, v[50:51]
	v_lshlrev_b64 v[50:51], 12, v[52:53]
	v_lshlrev_b64 v[52:53], 12, v[54:55]
	v_lshlrev_b64 v[54:55], 12, v[56:57]
	v_lshlrev_b64 v[56:57], 12, v[58:59]
	v_lshlrev_b64 v[58:59], 12, v[60:61]
	v_lshlrev_b64 v[60:61], 12, v[62:63]
	v_lshlrev_b64 v[62:63], 12, v[64:65]
	v_lshlrev_b64 v[64:65], 12, v[66:67]
	v_lshlrev_b64 v[66:67], 12, v[68:69]
	v_lshlrev_b64 v[68:69], 12, v[70:71]
	v_lshlrev_b64 v[70:71], 12, v[72:73]
	v_lshlrev_b64 v[72:73], 12, v[74:75]
	v_lshlrev_b64 v[74:75], 12, v[76:77]
	v_lshlrev_b64 v[76:77], 12, v[78:79]
	v_lshlrev_b64 v[78:79], 12, v[80:81]
	v_lshlrev_b64 v[80:81], 12, v[82:83]
	v_lshl_add_u64 v[20:21], v[92:93], 0, v[20:21]
	v_lshl_add_u64 v[22:23], v[92:93], 0, v[22:23]
	v_lshl_add_u64 v[24:25], v[92:93], 0, v[24:25]
	v_lshl_add_u64 v[26:27], v[92:93], 0, v[26:27]
	v_lshl_add_u64 v[28:29], v[92:93], 0, v[28:29]
	v_lshl_add_u64 v[30:31], v[92:93], 0, v[30:31]
	v_lshl_add_u64 v[32:33], v[92:93], 0, v[32:33]
	v_lshl_add_u64 v[34:35], v[92:93], 0, v[34:35]
	v_lshl_add_u64 v[82:83], v[86:87], 1, v[84:85]
	v_lshl_add_u64 v[86:87], v[88:89], 1, v[84:85]
	v_lshl_add_u64 v[84:85], v[90:91], 1, v[84:85]
	v_lshl_add_u64 v[36:37], v[92:93], 0, v[36:37]
	v_lshl_add_u64 v[38:39], v[92:93], 0, v[38:39]
	v_lshl_add_u64 v[40:41], v[92:93], 0, v[40:41]
	v_lshl_add_u64 v[42:43], v[92:93], 0, v[42:43]
	v_lshl_add_u64 v[44:45], v[92:93], 0, v[44:45]
	v_lshl_add_u64 v[46:47], v[92:93], 0, v[46:47]
	v_lshl_add_u64 v[48:49], v[92:93], 0, v[48:49]
	v_lshl_add_u64 v[50:51], v[92:93], 0, v[50:51]
	v_lshl_add_u64 v[52:53], v[92:93], 0, v[52:53]
	v_lshl_add_u64 v[54:55], v[92:93], 0, v[54:55]
	v_lshl_add_u64 v[56:57], v[92:93], 0, v[56:57]
	v_lshl_add_u64 v[58:59], v[92:93], 0, v[58:59]
	v_lshl_add_u64 v[60:61], v[92:93], 0, v[60:61]
	v_lshl_add_u64 v[62:63], v[92:93], 0, v[62:63]
	v_lshl_add_u64 v[64:65], v[92:93], 0, v[64:65]
	v_lshl_add_u64 v[66:67], v[92:93], 0, v[66:67]
	v_lshl_add_u64 v[68:69], v[92:93], 0, v[68:69]
	v_lshl_add_u64 v[70:71], v[92:93], 0, v[70:71]
	v_lshl_add_u64 v[72:73], v[92:93], 0, v[72:73]
	v_lshl_add_u64 v[74:75], v[92:93], 0, v[74:75]
	v_lshl_add_u64 v[76:77], v[92:93], 0, v[76:77]
	v_lshl_add_u64 v[78:79], v[92:93], 0, v[78:79]
	v_lshl_add_u64 v[80:81], v[92:93], 0, v[80:81]
	global_load_dword v17, v[18:19], off sc1 nt
	global_load_dword v88, v[20:21], off sc1 nt
	global_load_dword v89, v[22:23], off sc1 nt
	global_load_dword v90, v[24:25], off sc1 nt
	global_load_dword v91, v[26:27], off sc1 nt
	global_load_dword v92, v[28:29], off sc1 nt
	global_load_dword v93, v[30:31], off sc1 nt
	global_load_dword v96, v[32:33], off sc1 nt
	global_load_dword v97, v[34:35], off sc1 nt
	global_load_dword v98, v[36:37], off sc1 nt
	global_load_dword v99, v[38:39], off sc1 nt
	global_load_dword v100, v[40:41], off sc1 nt
	global_load_dword v101, v[42:43], off sc1 nt
	global_load_dword v102, v[44:45], off sc1 nt
	global_load_dword v103, v[46:47], off sc1 nt
	global_load_dword v18, v[48:49], off sc1 nt
	global_load_dword v19, v[50:51], off sc1 nt
	global_load_dword v20, v[52:53], off sc1 nt
	global_load_dword v21, v[54:55], off sc1 nt
	global_load_dword v22, v[56:57], off sc1 nt
	global_load_dword v23, v[58:59], off sc1 nt
	global_load_dword v24, v[60:61], off sc1 nt
	global_load_dword v25, v[62:63], off sc1 nt
	global_load_dword v26, v[64:65], off sc1 nt
	global_load_dword v27, v[66:67], off sc1 nt
	global_load_dword v28, v[68:69], off sc1 nt
	global_load_dword v29, v[70:71], off sc1 nt
	global_load_dword v30, v[72:73], off sc1 nt
	global_load_dword v31, v[74:75], off sc1 nt
	global_load_dword v32, v[76:77], off sc1 nt
	global_load_dword v33, v[78:79], off sc1 nt
	global_load_dword v34, v[80:81], off sc1 nt
	s_waitcnt vmcnt(0)
	ds_write2_b32 v9, v17, v88 offset1:66
	ds_write2_b32 v9, v89, v90 offset0:132 offset1:198
	ds_write2_b32 v10, v91, v92 offset0:8 offset1:74
	ds_write2_b32 v10, v93, v96 offset0:140 offset1:206
	ds_write2_b32 v11, v97, v98 offset0:16 offset1:82
	ds_write2_b32 v11, v99, v100 offset0:148 offset1:214
	ds_write2_b32 v12, v101, v102 offset0:24 offset1:90
	ds_write2_b32 v12, v103, v18 offset0:156 offset1:222
	ds_write2_b32 v13, v19, v20 offset0:32 offset1:98
	ds_write2_b32 v13, v21, v22 offset0:164 offset1:230
	ds_write2_b32 v14, v23, v24 offset0:40 offset1:106
	ds_write2_b32 v14, v25, v26 offset0:172 offset1:238
	ds_write2_b32 v15, v27, v28 offset0:48 offset1:114
	ds_write2_b32 v15, v29, v30 offset0:180 offset1:246
	ds_write2_b32 v16, v31, v32 offset0:56 offset1:122
	ds_write2_b32 v16, v33, v34 offset0:188 offset1:254
	s_waitcnt lgkmcnt(0)
	ds_read2_b32 v[18:19], v6 offset1:33
	ds_read2_b32 v[20:21], v6 offset0:66 offset1:99
	ds_read2_b32 v[22:23], v6 offset0:132 offset1:165
	ds_read2_b32 v[24:25], v6 offset0:198 offset1:231
	s_add_i32 s5, s0, 0x200
	s_waitcnt lgkmcnt(3)
	v_bfe_u32 v17, v18, 16, 1
	v_bfe_u32 v26, v19, 16, 1
	s_waitcnt lgkmcnt(2)
	v_bfe_u32 v27, v20, 16, 1
	v_bfe_u32 v28, v21, 16, 1
	s_waitcnt lgkmcnt(1)
	v_bfe_u32 v29, v22, 16, 1
	v_bfe_u32 v30, v23, 16, 1
	s_waitcnt lgkmcnt(0)
	v_bfe_u32 v31, v24, 16, 1
	v_bfe_u32 v32, v25, 16, 1
	v_add3_u32 v17, v18, v17, s2
	v_add3_u32 v18, v19, v26, s2
	v_add3_u32 v19, v20, v27, s2
	v_add3_u32 v20, v21, v28, s2
	v_add3_u32 v21, v22, v29, s2
	v_add3_u32 v22, v23, v30, s2
	v_add3_u32 v23, v24, v31, s2
	v_add3_u32 v24, v25, v32, s2
	v_lshrrev_b32_e32 v17, 16, v17
	v_lshrrev_b32_e32 v19, 16, v19
	v_lshrrev_b32_e32 v21, 16, v21
	v_lshrrev_b32_e32 v23, 16, v23
	v_and_or_b32 v18, v18, s3, v17
	v_and_or_b32 v19, v20, s3, v19
	v_and_or_b32 v20, v22, s3, v21
	v_and_or_b32 v21, v24, s3, v23
	global_store_dwordx4 v[94:95], v[18:21], off sc1
	s_nop 1
	ds_read2_b32 v[18:19], v6 offset0:8 offset1:41
	ds_read2_b32 v[20:21], v6 offset0:74 offset1:107
	ds_read2_b32 v[22:23], v6 offset0:140 offset1:173
	ds_read2_b32 v[24:25], v6 offset0:206 offset1:239
	s_addk_i32 s1, 0x4000
	s_waitcnt lgkmcnt(3)
	v_bfe_u32 v17, v18, 16, 1
	v_bfe_u32 v26, v19, 16, 1
	s_waitcnt lgkmcnt(2)
	v_bfe_u32 v27, v20, 16, 1
	v_bfe_u32 v28, v21, 16, 1
	s_waitcnt lgkmcnt(1)
	v_bfe_u32 v29, v22, 16, 1
	v_bfe_u32 v30, v23, 16, 1
	s_waitcnt lgkmcnt(0)
	v_bfe_u32 v31, v24, 16, 1
	v_bfe_u32 v32, v25, 16, 1
	v_add3_u32 v17, v18, v17, s2
	v_add3_u32 v18, v19, v26, s2
	v_add3_u32 v19, v20, v27, s2
	v_add3_u32 v20, v21, v28, s2
	v_add3_u32 v21, v22, v29, s2
	v_add3_u32 v22, v23, v30, s2
	v_add3_u32 v23, v24, v31, s2
	v_add3_u32 v24, v25, v32, s2
	v_lshrrev_b32_e32 v17, 16, v17
	v_lshrrev_b32_e32 v19, 16, v19
	v_lshrrev_b32_e32 v21, 16, v21
	v_lshrrev_b32_e32 v23, 16, v23
	v_and_or_b32 v18, v18, s3, v17
	v_and_or_b32 v19, v20, s3, v19
	v_and_or_b32 v20, v22, s3, v21
	v_and_or_b32 v21, v24, s3, v23
	global_store_dwordx4 v[82:83], v[18:21], off sc1
	s_nop 1
	ds_read2_b32 v[18:19], v6 offset0:16 offset1:49
	ds_read2_b32 v[20:21], v6 offset0:82 offset1:115
	ds_read2_b32 v[22:23], v6 offset0:148 offset1:181
	ds_read2_b32 v[24:25], v6 offset0:214 offset1:247
	v_add_u32_e32 v8, 0x2c00000, v8
	s_waitcnt lgkmcnt(3)
	v_bfe_u32 v17, v18, 16, 1
	v_bfe_u32 v26, v19, 16, 1
	s_waitcnt lgkmcnt(2)
	v_bfe_u32 v27, v20, 16, 1
	v_bfe_u32 v28, v21, 16, 1
	s_waitcnt lgkmcnt(1)
	v_bfe_u32 v29, v22, 16, 1
	v_bfe_u32 v30, v23, 16, 1
	s_waitcnt lgkmcnt(0)
	v_bfe_u32 v31, v24, 16, 1
	v_bfe_u32 v32, v25, 16, 1
	v_add3_u32 v17, v18, v17, s2
	v_add3_u32 v18, v19, v26, s2
	v_add3_u32 v19, v20, v27, s2
	v_add3_u32 v20, v21, v28, s2
	v_add3_u32 v21, v22, v29, s2
	v_add3_u32 v22, v23, v30, s2
	v_add3_u32 v23, v24, v31, s2
	v_add3_u32 v24, v25, v32, s2
	v_lshrrev_b32_e32 v17, 16, v17
	v_lshrrev_b32_e32 v19, 16, v19
	v_lshrrev_b32_e32 v21, 16, v21
	v_lshrrev_b32_e32 v23, 16, v23
	v_and_or_b32 v18, v18, s3, v17
	v_and_or_b32 v19, v20, s3, v19
	v_and_or_b32 v20, v22, s3, v21
	v_and_or_b32 v21, v24, s3, v23
	global_store_dwordx4 v[86:87], v[18:21], off sc1
	s_nop 1
	ds_read2_b32 v[18:19], v6 offset0:24 offset1:57
	ds_read2_b32 v[20:21], v6 offset0:90 offset1:123
	ds_read2_b32 v[22:23], v6 offset0:156 offset1:189
	ds_read2_b32 v[24:25], v6 offset0:222 offset1:255
	s_cmpk_gt_i32 s0, 0x37f
	s_waitcnt lgkmcnt(3)
	v_bfe_u32 v17, v18, 16, 1
	v_bfe_u32 v26, v19, 16, 1
	s_waitcnt lgkmcnt(2)
	v_bfe_u32 v27, v20, 16, 1
	v_bfe_u32 v28, v21, 16, 1
	s_waitcnt lgkmcnt(1)
	v_bfe_u32 v29, v22, 16, 1
	v_bfe_u32 v30, v23, 16, 1
	s_waitcnt lgkmcnt(0)
	v_bfe_u32 v31, v24, 16, 1
	v_bfe_u32 v32, v25, 16, 1
	v_add3_u32 v17, v18, v17, s2
	v_add3_u32 v18, v19, v26, s2
	v_add3_u32 v19, v20, v27, s2
	v_add3_u32 v20, v21, v28, s2
	v_add3_u32 v21, v22, v29, s2
	v_add3_u32 v22, v23, v30, s2
	v_add3_u32 v23, v24, v31, s2
	v_add3_u32 v24, v25, v32, s2
	v_lshrrev_b32_e32 v17, 16, v17
	v_lshrrev_b32_e32 v19, 16, v19
	v_lshrrev_b32_e32 v21, 16, v21
	v_lshrrev_b32_e32 v23, 16, v23
	v_and_or_b32 v18, v18, s3, v17
	v_and_or_b32 v19, v20, s3, v19
	v_and_or_b32 v20, v22, s3, v21
	v_and_or_b32 v21, v24, s3, v23
	global_store_dwordx4 v[84:85], v[18:21], off sc1
	s_nop 1
	s_waitcnt lgkmcnt(0)
	s_mov_b32 s0, s5
	s_cbranch_scc0 .LBB0_392

.LBB0_776:
	v_add_co_u32_e32 v66, vcc, 0xb000, v10
	global_load_dword v55, v[10:11], off sc1 nt
	s_nop 0
	v_addc_co_u32_e32 v67, vcc, 0, v11, vcc
	v_add_co_u32_e32 v68, vcc, 0x16000, v10
	s_nop 1
	v_addc_co_u32_e32 v69, vcc, 0, v11, vcc
	v_add_co_u32_e32 v70, vcc, 0x21000, v10
	s_nop 1
	v_addc_co_u32_e32 v71, vcc, 0, v11, vcc
	v_add_co_u32_e32 v72, vcc, 0x2c000, v10
	s_nop 1
	v_addc_co_u32_e32 v73, vcc, 0, v11, vcc
	v_add_co_u32_e32 v74, vcc, 0x37000, v10
	s_nop 1
	v_addc_co_u32_e32 v75, vcc, 0, v11, vcc
	v_add_co_u32_e32 v76, vcc, 0x42000, v10
	s_nop 1
	v_addc_co_u32_e32 v77, vcc, 0, v11, vcc
	v_add_co_u32_e32 v78, vcc, 0x4d000, v10
	s_nop 1
	v_addc_co_u32_e32 v79, vcc, 0, v11, vcc
	v_add_co_u32_e32 v80, vcc, 0x58000, v10
	s_nop 1
	v_addc_co_u32_e32 v81, vcc, 0, v11, vcc
	global_load_dword v64, v[66:67], off sc1 nt
	global_load_dword v62, v[68:69], off sc1 nt
	global_load_dword v63, v[70:71], off sc1 nt
	global_load_dword v60, v[72:73], off sc1 nt
	global_load_dword v61, v[74:75], off sc1 nt
	global_load_dword v58, v[76:77], off sc1 nt
	global_load_dword v59, v[78:79], off sc1 nt
	global_load_dword v56, v[80:81], off sc1 nt
	v_add_co_u32_e32 v66, vcc, 0x63000, v10
	s_nop 1
	v_addc_co_u32_e32 v67, vcc, 0, v11, vcc
	v_add_co_u32_e32 v68, vcc, 0x6e000, v10
	s_nop 1
	v_addc_co_u32_e32 v69, vcc, 0, v11, vcc
	v_add_co_u32_e32 v70, vcc, 0x79000, v10
	s_nop 1
	v_addc_co_u32_e32 v71, vcc, 0, v11, vcc
	v_add_co_u32_e32 v72, vcc, 0x84000, v10
	s_nop 1
	v_addc_co_u32_e32 v73, vcc, 0, v11, vcc
	v_add_co_u32_e32 v74, vcc, 0x8f000, v10
	s_nop 1
	v_addc_co_u32_e32 v75, vcc, 0, v11, vcc
	v_add_co_u32_e32 v76, vcc, 0x9a000, v10
	s_nop 1
	v_addc_co_u32_e32 v77, vcc, 0, v11, vcc
	v_add_co_u32_e32 v78, vcc, 0xa5000, v10
	s_nop 1
	v_addc_co_u32_e32 v79, vcc, 0, v11, vcc
	v_add_co_u32_e32 v80, vcc, 0xb0000, v10
	s_nop 1
	v_addc_co_u32_e32 v81, vcc, 0, v11, vcc
	global_load_dword v65, v[66:67], off sc1 nt
	global_load_dword v82, v[68:69], off sc1 nt
	global_load_dword v83, v[70:71], off sc1 nt
	global_load_dword v84, v[72:73], off sc1 nt
	global_load_dword v85, v[74:75], off sc1 nt
	global_load_dword v86, v[76:77], off sc1 nt
	global_load_dword v99, v[78:79], off sc1 nt
	global_load_dword v103, v[80:81], off sc1 nt
	v_add_co_u32_e32 v66, vcc, 0xbb000, v10
	s_nop 1
	v_addc_co_u32_e32 v67, vcc, 0, v11, vcc
	v_add_co_u32_e32 v68, vcc, 0xc6000, v10
	s_nop 1
	v_addc_co_u32_e32 v69, vcc, 0, v11, vcc
	v_add_co_u32_e32 v70, vcc, 0xd1000, v10
	s_nop 1
	v_addc_co_u32_e32 v71, vcc, 0, v11, vcc
	v_add_co_u32_e32 v72, vcc, 0xdc000, v10
	s_nop 1
	v_addc_co_u32_e32 v73, vcc, 0, v11, vcc
	v_add_co_u32_e32 v74, vcc, 0xe7000, v10
	s_nop 1
	v_addc_co_u32_e32 v75, vcc, 0, v11, vcc
	v_add_co_u32_e32 v76, vcc, 0xf2000, v10
	s_nop 1
	v_addc_co_u32_e32 v77, vcc, 0, v11, vcc
	v_add_co_u32_e32 v78, vcc, 0xfd000, v10
	s_nop 1
	v_addc_co_u32_e32 v79, vcc, 0, v11, vcc
	v_add_co_u32_e32 v80, vcc, 0x108000, v10
	s_nop 1
	v_addc_co_u32_e32 v81, vcc, 0, v11, vcc
	global_load_dword v104, v[66:67], off sc1 nt
	global_load_dword v107, v[68:69], off sc1 nt
	global_load_dword v108, v[70:71], off sc1 nt
	global_load_dword v109, v[72:73], off sc1 nt
	global_load_dword v111, v[74:75], off sc1 nt
	global_load_dword v112, v[76:77], off sc1 nt
	global_load_dword v113, v[78:79], off sc1 nt
	global_load_dword v114, v[80:81], off sc1 nt
	global_load_dword v115, v[2:3], off sc1 nt
	global_load_dword v57, v[2:3], off offset:256 sc1 nt
	v_add_co_u32_e32 v66, vcc, 0x113000, v10
	s_nop 1
	v_addc_co_u32_e32 v67, vcc, 0, v11, vcc
	v_add_co_u32_e32 v68, vcc, 0x11e000, v10
	s_nop 1
	v_addc_co_u32_e32 v69, vcc, 0, v11, vcc
	v_add_co_u32_e32 v70, vcc, 0x129000, v10
	s_nop 1
	v_addc_co_u32_e32 v71, vcc, 0, v11, vcc
	v_add_co_u32_e32 v72, vcc, 0x134000, v10
	s_nop 1
	v_addc_co_u32_e32 v73, vcc, 0, v11, vcc
	v_add_co_u32_e32 v74, vcc, 0x13f000, v10
	s_nop 1
	v_addc_co_u32_e32 v75, vcc, 0, v11, vcc
	v_add_co_u32_e32 v76, vcc, 0x14a000, v10
	s_nop 1
	v_addc_co_u32_e32 v77, vcc, 0, v11, vcc
	v_add_co_u32_e32 v78, vcc, 0x155000, v10
	s_nop 1
	v_addc_co_u32_e32 v79, vcc, 0, v11, vcc
	v_add_co_u32_e32 v80, vcc, 0x160000, v10
	s_nop 1
	v_addc_co_u32_e32 v81, vcc, 0, v11, vcc
	global_load_dword v116, v[66:67], off sc1 nt
	global_load_dword v117, v[68:69], off sc1 nt
	global_load_dword v118, v[70:71], off sc1 nt
	global_load_dword v119, v[72:73], off sc1 nt
	global_load_dword v120, v[74:75], off sc1 nt
	global_load_dword v121, v[76:77], off sc1 nt
	global_load_dword v122, v[78:79], off sc1 nt
	global_load_dword v123, v[80:81], off sc1 nt
	v_add_co_u32_e32 v66, vcc, 0x16b000, v10
	s_nop 1
	v_addc_co_u32_e32 v67, vcc, 0, v11, vcc
	v_add_co_u32_e32 v68, vcc, 0x176000, v10
	s_nop 1
	v_addc_co_u32_e32 v69, vcc, 0, v11, vcc
	v_add_co_u32_e32 v70, vcc, 0x181000, v10
	s_nop 1
	v_addc_co_u32_e32 v71, vcc, 0, v11, vcc
	v_add_co_u32_e32 v72, vcc, 0x18c000, v10
	s_nop 1
	v_addc_co_u32_e32 v73, vcc, 0, v11, vcc
	v_add_co_u32_e32 v74, vcc, 0x197000, v10
	s_nop 1
	v_addc_co_u32_e32 v75, vcc, 0, v11, vcc
	v_add_co_u32_e32 v76, vcc, 0x1a2000, v10
	s_nop 1
	v_addc_co_u32_e32 v77, vcc, 0, v11, vcc
	v_add_co_u32_e32 v78, vcc, 0x1ad000, v10
	s_nop 1
	v_addc_co_u32_e32 v79, vcc, 0, v11, vcc
	v_add_co_u32_e32 v80, vcc, 0x1b8000, v10
	s_nop 1
	v_addc_co_u32_e32 v81, vcc, 0, v11, vcc
	global_load_dword v124, v[66:67], off sc1 nt
	global_load_dword v125, v[68:69], off sc1 nt
	global_load_dword v126, v[70:71], off sc1 nt
	global_load_dword v127, v[72:73], off sc1 nt
	global_load_dword v128, v[74:75], off sc1 nt
	global_load_dword v129, v[76:77], off sc1 nt
	global_load_dword v130, v[78:79], off sc1 nt
	global_load_dword v131, v[80:81], off sc1 nt
	v_add_co_u32_e32 v66, vcc, 0x1c3000, v10
	s_nop 1
	v_addc_co_u32_e32 v67, vcc, 0, v11, vcc
	v_add_co_u32_e32 v68, vcc, 0x1ce000, v10
	s_nop 1
	v_addc_co_u32_e32 v69, vcc, 0, v11, vcc
	v_add_co_u32_e32 v70, vcc, 0x1d9000, v10
	s_nop 1
	v_addc_co_u32_e32 v71, vcc, 0, v11, vcc
	v_add_co_u32_e32 v72, vcc, 0x1e4000, v10
	s_nop 1
	v_addc_co_u32_e32 v73, vcc, 0, v11, vcc
	v_add_co_u32_e32 v74, vcc, 0x1ef000, v10
	s_nop 1
	v_addc_co_u32_e32 v75, vcc, 0, v11, vcc
	v_add_co_u32_e32 v76, vcc, 0x1fa000, v10
	s_nop 1
	v_addc_co_u32_e32 v77, vcc, 0, v11, vcc
	v_add_co_u32_e32 v78, vcc, 0x205000, v10
	s_nop 1
	v_addc_co_u32_e32 v79, vcc, 0, v11, vcc
	v_add_co_u32_e32 v80, vcc, 0x210000, v10
	s_nop 1
	v_addc_co_u32_e32 v81, vcc, 0, v11, vcc
	global_load_dword v132, v[66:67], off sc1 nt
	global_load_dword v133, v[68:69], off sc1 nt
	global_load_dword v134, v[70:71], off sc1 nt
	global_load_dword v135, v[72:73], off sc1 nt
	global_load_dword v136, v[74:75], off sc1 nt
	global_load_dword v137, v[76:77], off sc1 nt
	global_load_dword v138, v[78:79], off sc1 nt
	global_load_dword v139, v[80:81], off sc1 nt
	v_add_co_u32_e32 v66, vcc, 0x21b000, v10
	s_nop 1
	v_addc_co_u32_e32 v67, vcc, 0, v11, vcc
	v_add_co_u32_e32 v68, vcc, 0x226000, v10
	s_nop 1
	v_addc_co_u32_e32 v69, vcc, 0, v11, vcc
	v_add_co_u32_e32 v70, vcc, 0x231000, v10
	s_nop 1
	v_addc_co_u32_e32 v71, vcc, 0, v11, vcc
	v_add_co_u32_e32 v72, vcc, 0x23c000, v10
	s_nop 1
	v_addc_co_u32_e32 v73, vcc, 0, v11, vcc
	v_add_co_u32_e32 v74, vcc, 0x247000, v10
	s_nop 1
	v_addc_co_u32_e32 v75, vcc, 0, v11, vcc
	v_add_co_u32_e32 v76, vcc, 0x252000, v10
	s_nop 1
	v_addc_co_u32_e32 v77, vcc, 0, v11, vcc
	v_add_co_u32_e32 v78, vcc, 0x25d000, v10
	s_nop 1
	v_addc_co_u32_e32 v79, vcc, 0, v11, vcc
	v_add_co_u32_e32 v80, vcc, 0x268000, v10
	s_nop 1
	v_addc_co_u32_e32 v81, vcc, 0, v11, vcc
	global_load_dword v140, v[66:67], off sc1 nt
	global_load_dword v141, v[68:69], off sc1 nt
	global_load_dword v142, v[70:71], off sc1 nt
	global_load_dword v143, v[72:73], off sc1 nt
	global_load_dword v144, v[74:75], off sc1 nt
	global_load_dword v145, v[76:77], off sc1 nt
	global_load_dword v146, v[78:79], off sc1 nt
	global_load_dword v147, v[80:81], off sc1 nt
	v_add_co_u32_e32 v66, vcc, 0x273000, v10
	s_waitcnt vmcnt(33)
	ds_bpermute_b32 v81, v19, v115
	v_addc_co_u32_e32 v67, vcc, 0, v11, vcc
	v_add_co_u32_e32 v68, vcc, 0x27e000, v10
	s_waitcnt lgkmcnt(0)
	v_mul_f32_e32 v89, v64, v81
	v_addc_co_u32_e32 v69, vcc, 0, v11, vcc
	v_add_co_u32_e32 v70, vcc, 0x289000, v10
	ds_bpermute_b32 v64, v24, v115
	s_nop 0
	v_addc_co_u32_e32 v71, vcc, 0, v11, vcc
	v_add_co_u32_e32 v72, vcc, 0x294000, v10
	s_waitcnt lgkmcnt(0)
	v_mul_f32_e32 v92, v58, v64
	v_addc_co_u32_e32 v73, vcc, 0, v11, vcc
	v_add_co_u32_e32 v74, vcc, 0x29f000, v10
	ds_bpermute_b32 v58, v26, v115
	s_nop 0
	v_addc_co_u32_e32 v75, vcc, 0, v11, vcc
	v_add_co_u32_e32 v76, vcc, 0x2aa000, v10
	s_waitcnt lgkmcnt(0)
	v_mul_f32_e32 v98, v56, v58
	v_addc_co_u32_e32 v77, vcc, 0, v11, vcc
	v_add_co_u32_e32 v78, vcc, 0x2b5000, v10
	ds_bpermute_b32 v56, v30, v115
	s_nop 0
	v_addc_co_u32_e32 v79, vcc, 0, v11, vcc
	global_load_dword v148, v[66:67], off sc1 nt
	global_load_dword v149, v[68:69], off sc1 nt
	global_load_dword v150, v[70:71], off sc1 nt
	global_load_dword v151, v[72:73], off sc1 nt
	global_load_dword v152, v[74:75], off sc1 nt
	global_load_dword v153, v[76:77], off sc1 nt
	global_load_dword v154, v[78:79], off sc1 nt
	ds_bpermute_b32 v66, v20, v115
	ds_bpermute_b32 v58, v31, v115
	ds_bpermute_b32 v67, v21, v115
	s_waitcnt lgkmcnt(3)
	v_mul_f32_e32 v102, v84, v56
	ds_bpermute_b32 v56, v34, v115
	s_waitcnt lgkmcnt(3)
	v_mul_f32_e32 v88, v62, v66
	ds_bpermute_b32 v62, v22, v115
	ds_bpermute_b32 v66, v25, v115
	s_waitcnt lgkmcnt(4)
	v_mul_f32_e32 v101, v85, v58
	ds_bpermute_b32 v58, v35, v115
	ds_bpermute_b32 v80, v18, v115
	s_waitcnt lgkmcnt(3)
	v_mul_f32_e32 v94, v60, v62
	ds_bpermute_b32 v60, v28, v115
	s_waitcnt lgkmcnt(3)
	v_mul_f32_e32 v91, v59, v66
	ds_bpermute_b32 v59, v27, v115
	v_mul_f32_e32 v87, v63, v67
	ds_bpermute_b32 v63, v23, v115
	s_waitcnt lgkmcnt(2)
	v_mul_f32_e32 v96, v82, v60
	ds_bpermute_b32 v60, v33, v115
	s_waitcnt lgkmcnt(2)
	v_mul_f32_e32 v97, v65, v59
	ds_bpermute_b32 v59, v32, v115
	v_mul_f32_e32 v106, v103, v56
	v_mul_f32_e32 v105, v104, v58
	s_waitcnt lgkmcnt(1)
	v_mul_f32_e32 v99, v99, v60
	ds_bpermute_b32 v60, v37, v115
	s_waitcnt lgkmcnt(1)
	v_mul_f32_e32 v100, v86, v59
	ds_bpermute_b32 v59, v36, v115
	ds_bpermute_b32 v56, v38, v115
	ds_bpermute_b32 v58, v39, v115
	s_waitcnt lgkmcnt(3)
	v_mul_f32_e32 v103, v108, v60
	ds_bpermute_b32 v60, v41, v115
	v_mul_f32_e32 v90, v55, v80
	v_mul_f32_e32 v93, v61, v63
	ds_bpermute_b32 v61, v29, v115
	s_waitcnt lgkmcnt(4)
	v_mul_f32_e32 v104, v107, v59
	ds_bpermute_b32 v59, v40, v115
	v_max3_f32 v55, |v90|, 0, |v89|
	s_waitcnt lgkmcnt(4)
	v_mul_f32_e32 v110, v109, v56
	s_waitcnt lgkmcnt(3)
	v_mul_f32_e32 v109, v111, v58
	ds_bpermute_b32 v56, v42, v115
	ds_bpermute_b32 v58, v43, v115
	v_max3_f32 v55, v55, |v88|, |v87|
	s_waitcnt lgkmcnt(4)
	v_mul_f32_e32 v107, v113, v60
	ds_bpermute_b32 v60, v45, v115
	v_max3_f32 v55, v55, |v94|, |v93|
	v_max3_f32 v55, v55, |v92|, |v91|
	v_max3_f32 v55, v55, |v98|, |v97|
	s_waitcnt lgkmcnt(4)
	v_mul_f32_e32 v95, v83, v61
	s_waitcnt lgkmcnt(3)
	v_mul_f32_e32 v108, v112, v59
	ds_bpermute_b32 v59, v44, v115
	v_max3_f32 v55, v55, |v96|, |v95|
	s_waitcnt lgkmcnt(3)
	v_mul_f32_e32 v114, v114, v56
	s_waitcnt vmcnt(38) lgkmcnt(2)
	v_mul_f32_e32 v113, v116, v58
	ds_bpermute_b32 v56, v46, v115
	ds_bpermute_b32 v58, v47, v115
	v_max3_f32 v55, v55, |v102|, |v101|
	s_waitcnt vmcnt(36) lgkmcnt(3)
	v_mul_f32_e32 v111, v118, v60
	ds_bpermute_b32 v60, v49, v115
	v_max3_f32 v55, v55, |v100|, |v99|
	v_max3_f32 v55, v55, |v106|, |v105|
	v_max3_f32 v55, v55, |v104|, |v103|
	s_waitcnt lgkmcnt(3)
	v_mul_f32_e32 v112, v117, v59
	ds_bpermute_b32 v59, v48, v115
	v_max3_f32 v55, v55, |v110|, |v109|
	s_waitcnt vmcnt(35) lgkmcnt(3)
	v_mul_f32_e32 v118, v119, v56
	s_waitcnt vmcnt(34) lgkmcnt(2)
	v_mul_f32_e32 v117, v120, v58
	ds_bpermute_b32 v56, v18, v57
	ds_bpermute_b32 v58, v19, v57
	v_max3_f32 v55, v55, |v108|, |v107|
	s_waitcnt vmcnt(32) lgkmcnt(3)
	v_mul_f32_e32 v115, v122, v60
	ds_bpermute_b32 v60, v20, v57
	ds_bpermute_b32 v61, v21, v57
	v_max3_f32 v55, v55, |v114|, |v113|
	v_max3_f32 v55, v55, |v112|, |v111|
	v_max3_f32 v55, v55, |v118|, |v117|
	s_waitcnt lgkmcnt(4)
	v_mul_f32_e32 v116, v121, v59
	v_max3_f32 v55, v55, |v116|, |v115|
	s_waitcnt vmcnt(31) lgkmcnt(3)
	v_mul_f32_e32 v59, v123, v56
	s_waitcnt vmcnt(30) lgkmcnt(2)
	v_mul_f32_e32 v58, v124, v58
	v_max3_f32 v62, v55, |v59|, |v58|
	s_waitcnt vmcnt(29) lgkmcnt(1)
	v_mul_f32_e32 v56, v125, v60
	s_waitcnt vmcnt(28) lgkmcnt(0)
	v_mul_f32_e32 v55, v126, v61
	ds_bpermute_b32 v60, v22, v57
	ds_bpermute_b32 v61, v23, v57
	ds_bpermute_b32 v65, v24, v57
	ds_bpermute_b32 v66, v25, v57
	v_max3_f32 v64, v62, |v56|, |v55|
	s_waitcnt vmcnt(27) lgkmcnt(3)
	v_mul_f32_e32 v63, v127, v60
	s_waitcnt vmcnt(26) lgkmcnt(2)
	v_mul_f32_e32 v62, v128, v61
	s_waitcnt vmcnt(25) lgkmcnt(1)
	v_mul_f32_e32 v61, v129, v65
	s_waitcnt vmcnt(24) lgkmcnt(0)
	v_mul_f32_e32 v60, v130, v66
	ds_bpermute_b32 v65, v26, v57
	ds_bpermute_b32 v66, v27, v57
	ds_bpermute_b32 v68, v28, v57
	ds_bpermute_b32 v69, v29, v57
	v_max3_f32 v64, v64, |v63|, |v62|
	v_max3_f32 v64, v64, |v61|, |v60|
	s_waitcnt vmcnt(23) lgkmcnt(3)
	v_mul_f32_e32 v67, v131, v65
	s_waitcnt vmcnt(22) lgkmcnt(2)
	v_mul_f32_e32 v66, v132, v66
	v_max3_f32 v70, v64, |v67|, |v66|
	s_waitcnt vmcnt(21) lgkmcnt(1)
	v_mul_f32_e32 v65, v133, v68
	s_waitcnt vmcnt(20) lgkmcnt(0)
	v_mul_f32_e32 v64, v134, v69
	ds_bpermute_b32 v68, v30, v57
	ds_bpermute_b32 v69, v31, v57
	ds_bpermute_b32 v73, v32, v57
	ds_bpermute_b32 v74, v33, v57
	v_max3_f32 v72, v70, |v65|, |v64|
	s_waitcnt vmcnt(19) lgkmcnt(3)
	v_mul_f32_e32 v71, v135, v68
	s_waitcnt vmcnt(18) lgkmcnt(2)
	v_mul_f32_e32 v70, v136, v69
	s_waitcnt vmcnt(17) lgkmcnt(1)
	v_mul_f32_e32 v69, v137, v73
	s_waitcnt vmcnt(16) lgkmcnt(0)
	v_mul_f32_e32 v68, v138, v74
	ds_bpermute_b32 v73, v34, v57
	ds_bpermute_b32 v74, v35, v57
	ds_bpermute_b32 v76, v36, v57
	ds_bpermute_b32 v77, v37, v57
	v_max3_f32 v72, v72, |v71|, |v70|
	v_max3_f32 v72, v72, |v69|, |v68|
	s_waitcnt vmcnt(15) lgkmcnt(3)
	v_mul_f32_e32 v75, v139, v73
	s_waitcnt vmcnt(14) lgkmcnt(2)
	v_mul_f32_e32 v74, v140, v74
	v_max3_f32 v78, v72, |v75|, |v74|
	s_waitcnt vmcnt(13) lgkmcnt(1)
	v_mul_f32_e32 v73, v141, v76
	s_waitcnt vmcnt(12) lgkmcnt(0)
	v_mul_f32_e32 v72, v142, v77
	ds_bpermute_b32 v76, v38, v57
	ds_bpermute_b32 v77, v39, v57
	ds_bpermute_b32 v81, v40, v57
	ds_bpermute_b32 v82, v41, v57
	v_max3_f32 v80, v78, |v73|, |v72|
	s_waitcnt vmcnt(11) lgkmcnt(3)
	v_mul_f32_e32 v79, v143, v76
	s_waitcnt vmcnt(10) lgkmcnt(2)
	v_mul_f32_e32 v78, v144, v77
	s_waitcnt vmcnt(9) lgkmcnt(1)
	v_mul_f32_e32 v77, v145, v81
	s_waitcnt vmcnt(8) lgkmcnt(0)
	v_mul_f32_e32 v76, v146, v82
	ds_bpermute_b32 v81, v42, v57
	ds_bpermute_b32 v82, v43, v57
	ds_bpermute_b32 v84, v44, v57
	ds_bpermute_b32 v85, v45, v57
	v_max3_f32 v80, v80, |v79|, |v78|
	v_max3_f32 v80, v80, |v77|, |v76|
	s_waitcnt vmcnt(7) lgkmcnt(3)
	v_mul_f32_e32 v83, v147, v81
	s_waitcnt vmcnt(6) lgkmcnt(2)
	v_mul_f32_e32 v82, v148, v82
	v_max3_f32 v86, v80, |v83|, |v82|
	s_waitcnt vmcnt(5) lgkmcnt(1)
	v_mul_f32_e32 v81, v149, v84
	s_waitcnt vmcnt(4) lgkmcnt(0)
	v_mul_f32_e32 v80, v150, v85
	ds_bpermute_b32 v84, v46, v57
	ds_bpermute_b32 v85, v47, v57
	ds_bpermute_b32 v120, v48, v57
	ds_bpermute_b32 v57, v49, v57
	v_max3_f32 v119, v86, |v81|, |v80|
	s_waitcnt vmcnt(3) lgkmcnt(3)
	v_mul_f32_e32 v86, v151, v84
	s_waitcnt vmcnt(2) lgkmcnt(2)
	v_mul_f32_e32 v85, v152, v85
	v_max3_f32 v119, v119, |v86|, |v85|
	s_waitcnt vmcnt(1) lgkmcnt(1)
	v_mul_f32_e32 v84, v153, v120
	s_waitcnt vmcnt(0) lgkmcnt(0)
	v_mul_f32_e32 v57, v154, v57
	v_max3_f32 v119, v119, |v84|, |v57|
	v_mov_b32_e32 v120, v119
	s_nop 1
	v_permlane32_swap_b32_e32 v119, v120
	s_and_saveexec_b64 s[8:9], s[4:5]
	v_max_f32_e32 v119, v119, v119
	v_max_f32_e32 v120, v120, v120
	v_max_f32_e32 v119, v119, v120
	ds_write_b32 v53, v119
	s_or_b64 exec, exec, s[8:9]
	s_addk_i32 s15, 0x80
	s_waitcnt lgkmcnt(0)
	s_barrier
	ds_read2_b32 v[120:121], v50 offset1:32
	ds_read2_b32 v[122:123], v50 offset0:64 offset1:96
	ds_read2_b32 v[124:125], v50 offset0:128 offset1:160
	ds_read2_b32 v[126:127], v50 offset0:192 offset1:224
	s_cmpk_gt_i32 s15, 0x57
	s_cselect_b32 s8, 0xfffff500, 0
	s_waitcnt lgkmcnt(3)
	v_max3_f32 v119, v120, 0, v121
	s_cselect_b32 s9, 0x80, 0
	s_add_i32 s8, s8, s2
	s_waitcnt lgkmcnt(2)
	v_max3_f32 v119, v119, v122, v123
	s_lshl_b32 s8, s8, 1
	s_and_b32 s10, s2, 0x60
	s_waitcnt lgkmcnt(1)
	v_max3_f32 v119, v119, v124, v125
	s_and_b32 s8, s8, 0xffffff00
	s_or_b32 s9, s9, s10
	s_waitcnt lgkmcnt(0)
	v_max3_f32 v119, v119, v126, v127
	s_or_b32 s8, s9, s8
	s_and_saveexec_b64 s[10:11], s[0:1]
	s_cbranch_execz .LBB0_775
	s_ashr_i32 s9, s8, 31
	v_lshl_add_u64 v[120:121], s[8:9], 2, v[4:5]
	v_mul_f32_e32 v122, 0x3c010204, v119
	global_store_dword v[120:121], v122, off sc1
	s_branch .LBB0_775
.LBB0_780:
	s_sub_i32 s0, s14, 50
	s_cmp_lt_u32 s0, 32
	s_cbranch_scc0 .LBB0_786
	s_load_dwordx2 s[6:7], s[22:23], 0x78
	s_lshl_b32 s0, s14, 5
	s_addk_i32 s0, 0xf9c0
	s_mov_b32 s1, 0
	s_lshl_b32 s2, s13, 7
	s_lshl_b64 s[4:5], s[0:1], 2
	s_waitcnt lgkmcnt(0)
	s_add_u32 s6, s6, s4
	v_lshlrev_b32_e32 v4, 2, v17
	s_addc_u32 s7, s7, s5
	v_lshl_or_b32 v2, v14, 12, v4
	v_mov_b32_e32 v3, 0
	s_ashr_i32 s3, s2, 31
	v_lshl_add_u64 v[2:3], s[6:7], 0, v[2:3]
	s_lshl_b64 s[6:7], s[2:3], 12
	v_lshl_add_u64 v[20:21], v[2:3], 0, s[6:7]
	s_or_b32 s6, s2, 2
	s_ashr_i32 s7, s6, 31
	s_lshl_b64 s[6:7], s[6:7], 12
	v_lshl_add_u64 v[22:23], v[2:3], 0, s[6:7]
	s_or_b32 s6, s2, 4
	s_ashr_i32 s7, s6, 31
	s_lshl_b64 s[6:7], s[6:7], 12
	v_lshl_add_u64 v[24:25], v[2:3], 0, s[6:7]
	s_or_b32 s6, s2, 6
	s_ashr_i32 s7, s6, 31
	s_lshl_b64 s[6:7], s[6:7], 12
	v_lshl_add_u64 v[26:27], v[2:3], 0, s[6:7]
	s_or_b32 s6, s2, 8
	s_ashr_i32 s7, s6, 31
	s_lshl_b64 s[6:7], s[6:7], 12
	v_lshl_add_u64 v[28:29], v[2:3], 0, s[6:7]
	s_or_b32 s6, s2, 10
	s_ashr_i32 s7, s6, 31
	s_lshl_b64 s[6:7], s[6:7], 12
	v_lshl_add_u64 v[30:31], v[2:3], 0, s[6:7]
	s_or_b32 s6, s2, 12
	s_ashr_i32 s7, s6, 31
	s_lshl_b64 s[6:7], s[6:7], 12
	v_lshl_add_u64 v[32:33], v[2:3], 0, s[6:7]
	s_or_b32 s6, s2, 14
	s_ashr_i32 s7, s6, 31
	s_lshl_b64 s[6:7], s[6:7], 12
	v_lshl_add_u64 v[34:35], v[2:3], 0, s[6:7]
	s_or_b32 s6, s2, 16
	s_ashr_i32 s7, s6, 31
	s_lshl_b64 s[6:7], s[6:7], 12
	global_load_dword v18, v[20:21], off sc1 nt
	global_load_dword v11, v[22:23], off sc1 nt
	global_load_dword v10, v[24:25], off sc1 nt
	global_load_dword v9, v[26:27], off sc1 nt
	global_load_dword v8, v[28:29], off sc1 nt
	global_load_dword v7, v[30:31], off sc1 nt
	global_load_dword v6, v[32:33], off sc1 nt
	global_load_dword v5, v[34:35], off sc1 nt
	v_lshl_add_u64 v[20:21], v[2:3], 0, s[6:7]
	s_or_b32 s6, s2, 18
	s_ashr_i32 s7, s6, 31
	s_lshl_b64 s[6:7], s[6:7], 12
	v_lshl_add_u64 v[22:23], v[2:3], 0, s[6:7]
	s_or_b32 s6, s2, 20
	s_ashr_i32 s7, s6, 31
	s_lshl_b64 s[6:7], s[6:7], 12
	v_lshl_add_u64 v[24:25], v[2:3], 0, s[6:7]
	s_or_b32 s6, s2, 22
	s_ashr_i32 s7, s6, 31
	s_lshl_b64 s[6:7], s[6:7], 12
	v_lshl_add_u64 v[36:37], v[2:3], 0, s[6:7]
	s_or_b32 s6, s2, 24
	s_ashr_i32 s7, s6, 31
	s_lshl_b64 s[6:7], s[6:7], 12
	v_lshl_add_u64 v[38:39], v[2:3], 0, s[6:7]
	s_or_b32 s6, s2, 26
	s_ashr_i32 s7, s6, 31
	s_lshl_b64 s[6:7], s[6:7], 12
	v_lshl_add_u64 v[40:41], v[2:3], 0, s[6:7]
	s_or_b32 s6, s2, 28
	s_ashr_i32 s7, s6, 31
	s_lshl_b64 s[6:7], s[6:7], 12
	v_lshl_add_u64 v[42:43], v[2:3], 0, s[6:7]
	s_or_b32 s6, s2, 30
	s_ashr_i32 s7, s6, 31
	s_lshl_b64 s[6:7], s[6:7], 12
	v_lshl_add_u64 v[44:45], v[2:3], 0, s[6:7]
	s_or_b32 s6, s2, 32
	s_ashr_i32 s7, s6, 31
	s_lshl_b64 s[6:7], s[6:7], 12
	global_load_dword v34, v[20:21], off sc1 nt
	global_load_dword v33, v[22:23], off sc1 nt
	global_load_dword v32, v[24:25], off sc1 nt
	global_load_dword v31, v[36:37], off sc1 nt
	global_load_dword v30, v[38:39], off sc1 nt
	global_load_dword v29, v[40:41], off sc1 nt
	global_load_dword v28, v[42:43], off sc1 nt
	global_load_dword v27, v[44:45], off sc1 nt
	v_lshl_add_u64 v[20:21], v[2:3], 0, s[6:7]
	s_or_b32 s6, s2, 34
	s_ashr_i32 s7, s6, 31
	s_lshl_b64 s[6:7], s[6:7], 12
	v_lshl_add_u64 v[22:23], v[2:3], 0, s[6:7]
	s_or_b32 s6, s2, 36
	s_ashr_i32 s7, s6, 31
	s_lshl_b64 s[6:7], s[6:7], 12
	v_lshl_add_u64 v[24:25], v[2:3], 0, s[6:7]
	s_or_b32 s6, s2, 38
	s_ashr_i32 s7, s6, 31
	s_lshl_b64 s[6:7], s[6:7], 12
	v_lshl_add_u64 v[36:37], v[2:3], 0, s[6:7]
	s_or_b32 s6, s2, 40
	s_ashr_i32 s7, s6, 31
	s_lshl_b64 s[6:7], s[6:7], 12
	v_lshl_add_u64 v[38:39], v[2:3], 0, s[6:7]
	s_or_b32 s6, s2, 42
	s_ashr_i32 s7, s6, 31
	s_lshl_b64 s[6:7], s[6:7], 12
	v_lshl_add_u64 v[40:41], v[2:3], 0, s[6:7]
	s_or_b32 s6, s2, 44
	s_ashr_i32 s7, s6, 31
	s_lshl_b64 s[6:7], s[6:7], 12
	s_waitcnt vmcnt(23)
	v_lshl_add_u64 v[52:53], v[2:3], 0, s[6:7]
	s_or_b32 s6, s2, 46
	s_ashr_i32 s7, s6, 31
	s_lshl_b64 s[6:7], s[6:7], 12
	s_waitcnt vmcnt(20)
	v_lshl_add_u64 v[54:55], v[2:3], 0, s[6:7]
	s_or_b32 s6, s2, 48
	s_ashr_i32 s7, s6, 31
	s_lshl_b64 s[6:7], s[6:7], 12
	global_load_dword v50, v[20:21], off sc1 nt
	global_load_dword v49, v[22:23], off sc1 nt
	global_load_dword v48, v[24:25], off sc1 nt
	global_load_dword v47, v[36:37], off sc1 nt
	global_load_dword v46, v[38:39], off sc1 nt
	global_load_dword v45, v[40:41], off sc1 nt
	global_load_dword v44, v[52:53], off sc1 nt
	global_load_dword v43, v[54:55], off sc1 nt
	v_lshl_add_u64 v[20:21], v[2:3], 0, s[6:7]
	s_or_b32 s6, s2, 50
	s_ashr_i32 s7, s6, 31
	s_lshl_b64 s[6:7], s[6:7], 12
	v_lshl_add_u64 v[22:23], v[2:3], 0, s[6:7]
	s_or_b32 s6, s2, 52
	s_ashr_i32 s7, s6, 31
	s_lshl_b64 s[6:7], s[6:7], 12
	v_lshl_add_u64 v[24:25], v[2:3], 0, s[6:7]
	s_or_b32 s6, s2, 54
	s_ashr_i32 s7, s6, 31
	s_lshl_b64 s[6:7], s[6:7], 12
	v_lshl_add_u64 v[36:37], v[2:3], 0, s[6:7]
	s_or_b32 s6, s2, 56
	s_ashr_i32 s7, s6, 31
	s_lshl_b64 s[6:7], s[6:7], 12
	v_lshl_add_u64 v[38:39], v[2:3], 0, s[6:7]
	s_or_b32 s6, s2, 58
	s_ashr_i32 s7, s6, 31
	s_lshl_b64 s[6:7], s[6:7], 12
	v_lshl_add_u64 v[40:41], v[2:3], 0, s[6:7]
	s_or_b32 s6, s2, 60
	s_ashr_i32 s7, s6, 31
	s_lshl_b64 s[6:7], s[6:7], 12
	v_lshl_add_u64 v[52:53], v[2:3], 0, s[6:7]
	s_or_b32 s6, s2, 62
	s_ashr_i32 s7, s6, 31
	s_lshl_b64 s[6:7], s[6:7], 12
	v_lshl_add_u64 v[54:55], v[2:3], 0, s[6:7]
	s_or_b32 s6, s2, 64
	s_ashr_i32 s7, s6, 31
	s_lshl_b64 s[6:7], s[6:7], 12
	global_load_dword v66, v[20:21], off sc1 nt
	global_load_dword v65, v[22:23], off sc1 nt
	global_load_dword v64, v[24:25], off sc1 nt
	global_load_dword v63, v[36:37], off sc1 nt
	global_load_dword v62, v[38:39], off sc1 nt
	global_load_dword v61, v[40:41], off sc1 nt
	global_load_dword v60, v[52:53], off sc1 nt
	global_load_dword v59, v[54:55], off sc1 nt
	v_lshl_add_u64 v[36:37], v[2:3], 0, s[6:7]
	s_or_b32 s6, s2, 0x42
	s_ashr_i32 s7, s6, 31
	s_lshl_b64 s[6:7], s[6:7], 12
	v_lshl_add_u64 v[38:39], v[2:3], 0, s[6:7]
	s_or_b32 s6, s2, 0x44
	s_ashr_i32 s7, s6, 31
	s_lshl_b64 s[6:7], s[6:7], 12
	v_lshl_add_u64 v[40:41], v[2:3], 0, s[6:7]
	s_or_b32 s6, s2, 0x46
	s_ashr_i32 s7, s6, 31
	s_lshl_b64 s[6:7], s[6:7], 12
	v_lshl_add_u64 v[52:53], v[2:3], 0, s[6:7]
	s_or_b32 s6, s2, 0x48
	s_ashr_i32 s7, s6, 31
	s_lshl_b64 s[6:7], s[6:7], 12
	v_lshl_add_u64 v[54:55], v[2:3], 0, s[6:7]
	s_or_b32 s6, s2, 0x4a
	s_ashr_i32 s7, s6, 31
	s_lshl_b64 s[6:7], s[6:7], 12
	v_lshl_add_u64 v[56:57], v[2:3], 0, s[6:7]
	s_or_b32 s6, s2, 0x4c
	s_ashr_i32 s7, s6, 31
	s_lshl_b64 s[6:7], s[6:7], 12
	v_lshl_add_u64 v[68:69], v[2:3], 0, s[6:7]
	s_or_b32 s6, s2, 0x4e
	s_ashr_i32 s7, s6, 31
	s_lshl_b64 s[6:7], s[6:7], 12
	v_lshl_add_u64 v[70:71], v[2:3], 0, s[6:7]
	s_or_b32 s6, s2, 0x50
	s_ashr_i32 s7, s6, 31
	s_lshl_b64 s[6:7], s[6:7], 12
	global_load_dword v26, v[36:37], off sc1 nt
	global_load_dword v25, v[38:39], off sc1 nt
	global_load_dword v24, v[40:41], off sc1 nt
	global_load_dword v23, v[52:53], off sc1 nt
	global_load_dword v22, v[54:55], off sc1 nt
	global_load_dword v21, v[56:57], off sc1 nt
	global_load_dword v20, v[68:69], off sc1 nt
	global_load_dword v19, v[70:71], off sc1 nt
	v_lshl_add_u64 v[52:53], v[2:3], 0, s[6:7]
	s_or_b32 s6, s2, 0x52
	s_ashr_i32 s7, s6, 31
	s_lshl_b64 s[6:7], s[6:7], 12
	v_lshl_add_u64 v[54:55], v[2:3], 0, s[6:7]
	s_or_b32 s6, s2, 0x54
	s_ashr_i32 s7, s6, 31
	s_lshl_b64 s[6:7], s[6:7], 12
	v_lshl_add_u64 v[56:57], v[2:3], 0, s[6:7]
	s_or_b32 s6, s2, 0x56
	s_ashr_i32 s7, s6, 31
	s_lshl_b64 s[6:7], s[6:7], 12
	v_lshl_add_u64 v[68:69], v[2:3], 0, s[6:7]
	s_or_b32 s6, s2, 0x58
	s_ashr_i32 s7, s6, 31
	s_lshl_b64 s[6:7], s[6:7], 12
	v_lshl_add_u64 v[70:71], v[2:3], 0, s[6:7]
	s_or_b32 s6, s2, 0x5a
	s_ashr_i32 s7, s6, 31
	s_lshl_b64 s[6:7], s[6:7], 12
	v_lshl_add_u64 v[72:73], v[2:3], 0, s[6:7]
	s_or_b32 s6, s2, 0x5c
	s_ashr_i32 s7, s6, 31
	s_lshl_b64 s[6:7], s[6:7], 12
	v_lshl_add_u64 v[74:75], v[2:3], 0, s[6:7]
	s_or_b32 s6, s2, 0x5e
	s_ashr_i32 s7, s6, 31
	s_lshl_b64 s[6:7], s[6:7], 12
	v_lshl_add_u64 v[76:77], v[2:3], 0, s[6:7]
	s_or_b32 s6, s2, 0x60
	s_ashr_i32 s7, s6, 31
	s_lshl_b64 s[6:7], s[6:7], 12
	global_load_dword v42, v[52:53], off sc1 nt
	global_load_dword v41, v[54:55], off sc1 nt
	global_load_dword v40, v[56:57], off sc1 nt
	global_load_dword v39, v[68:69], off sc1 nt
	global_load_dword v38, v[70:71], off sc1 nt
	global_load_dword v37, v[72:73], off sc1 nt
	global_load_dword v36, v[74:75], off sc1 nt
	global_load_dword v35, v[76:77], off sc1 nt
	v_lshl_add_u64 v[68:69], v[2:3], 0, s[6:7]
	s_or_b32 s6, s2, 0x62
	s_ashr_i32 s7, s6, 31
	s_lshl_b64 s[6:7], s[6:7], 12
	v_lshl_add_u64 v[70:71], v[2:3], 0, s[6:7]
	s_or_b32 s6, s2, 0x64
	s_ashr_i32 s7, s6, 31
	s_lshl_b64 s[6:7], s[6:7], 12
	v_lshl_add_u64 v[72:73], v[2:3], 0, s[6:7]
	s_or_b32 s6, s2, 0x66
	s_ashr_i32 s7, s6, 31
	s_lshl_b64 s[6:7], s[6:7], 12
	v_lshl_add_u64 v[74:75], v[2:3], 0, s[6:7]
	s_or_b32 s6, s2, 0x68
	s_ashr_i32 s7, s6, 31
	s_lshl_b64 s[6:7], s[6:7], 12
	v_lshl_add_u64 v[76:77], v[2:3], 0, s[6:7]
	s_or_b32 s6, s2, 0x6a
	s_ashr_i32 s7, s6, 31
	s_lshl_b64 s[6:7], s[6:7], 12
	v_lshl_add_u64 v[78:79], v[2:3], 0, s[6:7]
	s_or_b32 s6, s2, 0x6c
	s_ashr_i32 s7, s6, 31
	s_lshl_b64 s[6:7], s[6:7], 12
	v_lshl_add_u64 v[80:81], v[2:3], 0, s[6:7]
	s_or_b32 s6, s2, 0x6e
	s_ashr_i32 s7, s6, 31
	s_lshl_b64 s[6:7], s[6:7], 12
	v_lshl_add_u64 v[82:83], v[2:3], 0, s[6:7]
	s_or_b32 s6, s2, 0x70
	s_ashr_i32 s7, s6, 31
	s_lshl_b64 s[6:7], s[6:7], 12
	global_load_dword v58, v[68:69], off sc1 nt
	global_load_dword v57, v[70:71], off sc1 nt
	global_load_dword v56, v[72:73], off sc1 nt
	global_load_dword v55, v[74:75], off sc1 nt
	global_load_dword v54, v[76:77], off sc1 nt
	global_load_dword v53, v[78:79], off sc1 nt
	global_load_dword v52, v[80:81], off sc1 nt
	global_load_dword v51, v[82:83], off sc1 nt
	v_lshl_add_u64 v[76:77], v[2:3], 0, s[6:7]
	s_or_b32 s6, s2, 0x72
	s_ashr_i32 s7, s6, 31
	s_lshl_b64 s[6:7], s[6:7], 12
	v_lshl_add_u64 v[78:79], v[2:3], 0, s[6:7]
	s_or_b32 s6, s2, 0x74
	s_ashr_i32 s7, s6, 31
	s_lshl_b64 s[6:7], s[6:7], 12
	v_lshl_add_u64 v[80:81], v[2:3], 0, s[6:7]
	s_or_b32 s6, s2, 0x76
	s_ashr_i32 s7, s6, 31
	s_lshl_b64 s[6:7], s[6:7], 12
	v_lshl_add_u64 v[82:83], v[2:3], 0, s[6:7]
	s_or_b32 s6, s2, 0x78
	s_ashr_i32 s7, s6, 31
	s_lshl_b64 s[6:7], s[6:7], 12
	v_lshl_add_u64 v[84:85], v[2:3], 0, s[6:7]
	s_or_b32 s6, s2, 0x7a
	s_ashr_i32 s7, s6, 31
	s_lshl_b64 s[6:7], s[6:7], 12
	v_lshl_add_u64 v[86:87], v[2:3], 0, s[6:7]
	s_or_b32 s6, s2, 0x7c
	s_ashr_i32 s7, s6, 31
	s_lshl_b64 s[6:7], s[6:7], 12
	v_lshl_add_u64 v[88:89], v[2:3], 0, s[6:7]
	s_or_b32 s6, s2, 0x7e
	s_ashr_i32 s7, s6, 31
	s_lshl_b64 s[6:7], s[6:7], 12
	v_lshl_add_u64 v[2:3], v[2:3], 0, s[6:7]
	global_load_dword v74, v[76:77], off sc1 nt
	global_load_dword v73, v[78:79], off sc1 nt
	global_load_dword v72, v[80:81], off sc1 nt
	global_load_dword v71, v[82:83], off sc1 nt
	global_load_dword v70, v[84:85], off sc1 nt
	global_load_dword v69, v[86:87], off sc1 nt
	global_load_dword v68, v[88:89], off sc1 nt
	global_load_dword v67, v[2:3], off sc1 nt
	s_waitcnt vmcnt(62)
	v_max3_f32 v2, |v18|, 0, |v11|
	s_waitcnt vmcnt(60)
	v_max3_f32 v2, v2, |v10|, |v9|
	s_waitcnt vmcnt(58)
	v_max3_f32 v2, v2, |v8|, |v7|
	s_waitcnt vmcnt(56)
	v_max3_f32 v2, v2, |v6|, |v5|
	s_waitcnt vmcnt(54)
	v_max3_f32 v2, v2, |v34|, |v33|
	s_waitcnt vmcnt(52)
	v_max3_f32 v2, v2, |v32|, |v31|
	s_waitcnt vmcnt(50)
	v_max3_f32 v2, v2, |v30|, |v29|
	s_waitcnt vmcnt(48)
	v_max3_f32 v2, v2, |v28|, |v27|
	s_waitcnt vmcnt(46)
	v_max3_f32 v2, v2, |v50|, |v49|
	s_waitcnt vmcnt(44)
	v_max3_f32 v2, v2, |v48|, |v47|
	s_waitcnt vmcnt(42)
	v_max3_f32 v2, v2, |v46|, |v45|
	s_waitcnt vmcnt(40)
	v_max3_f32 v2, v2, |v44|, |v43|
	s_waitcnt vmcnt(38)
	v_max3_f32 v2, v2, |v66|, |v65|
	s_waitcnt vmcnt(36)
	v_max3_f32 v2, v2, |v64|, |v63|
	s_waitcnt vmcnt(34)
	v_max3_f32 v2, v2, |v62|, |v61|
	s_waitcnt vmcnt(32)
	v_max3_f32 v2, v2, |v60|, |v59|
	s_waitcnt vmcnt(30)
	v_max3_f32 v2, v2, |v26|, |v25|
	s_waitcnt vmcnt(28)
	v_max3_f32 v2, v2, |v24|, |v23|
	s_waitcnt vmcnt(26)
	v_max3_f32 v2, v2, |v22|, |v21|
	s_waitcnt vmcnt(24)
	v_max3_f32 v2, v2, |v20|, |v19|
	s_waitcnt vmcnt(22)
	v_max3_f32 v2, v2, |v42|, |v41|
	s_waitcnt vmcnt(20)
	v_max3_f32 v2, v2, |v40|, |v39|
	s_waitcnt vmcnt(18)
	v_max3_f32 v2, v2, |v38|, |v37|
	s_waitcnt vmcnt(16)
	v_max3_f32 v2, v2, |v36|, |v35|
	v_cmp_gt_u32_e32 vcc, 32, v16
	s_waitcnt vmcnt(14)
	v_max3_f32 v2, v2, |v58|, |v57|
	s_waitcnt vmcnt(12)
	v_max3_f32 v2, v2, |v56|, |v55|
	s_waitcnt vmcnt(10)
	v_max3_f32 v2, v2, |v54|, |v53|
	s_waitcnt vmcnt(8)
	v_max3_f32 v2, v2, |v52|, |v51|
	s_waitcnt vmcnt(6)
	v_max3_f32 v2, v2, |v74|, |v73|
	s_waitcnt vmcnt(4)
	v_max3_f32 v2, v2, |v72|, |v71|
	s_waitcnt vmcnt(2)
	v_max3_f32 v2, v2, |v70|, |v69|
	s_waitcnt vmcnt(0)
	v_max3_f32 v2, v2, |v68|, |v67|
	v_mov_b32_e32 v3, v2
	s_nop 1
	v_permlane32_swap_b32_e32 v2, v3
	s_and_saveexec_b64 s[6:7], vcc
	s_cbranch_execz .LBB0_783
	v_max_f32_e32 v2, v2, v2
	v_max_f32_e32 v3, v3, v3
	s_add_i32 s1, s2, 0
	v_max_f32_e32 v2, v2, v3
	v_lshl_add_u32 v3, v16, 2, s1
	v_add_u32_e32 v3, 0x20000, v3
	ds_write_b32 v3, v2
